# GEMM main loops: pre-MMA s_barrier moved below the first 8 MFMAs of each MMA block (MFMAs do not touch LDS; barrier guards slot reuse only), on top of MLA loop rewrite + diff producer fusion
# baseline (speedup 1.0000x reference)
; #define PG8_STAGE(bufoff, gbase, voff) do { _Pragma("unroll") for (int _i = 0; _i < 2; ++_i) \
;         __builtin_amdgcn_global_load_lds((const unsigned*)((const char*)(gbase) + (voff)[_i]), (PG8_LAS unsigned*)(lds + (bufoff) + ldsw + _i * 8192), 16, 0, 0); } while (0)
; #define PG8_LDA(dst, b, h) do { _Pragma("unroll") for (int m = 0; m < 4; ++m) _Pragma("unroll") for (int k = 0; k < 2; ++k) dst[m][k] = *(const PG8_LAS bf16x8*)(lds + PG8_SA(b, h) + aoff + m * 2048 + k * 1024); } while (0)
; #define PG8_LDB(dst, b, h) do { _Pragma("unroll") for (int n = 0; n < 2; ++n) _Pragma("unroll") for (int k = 0; k < 2; ++k) dst[n][k] = *(const PG8_LAS bf16x8*)(lds + PG8_SB(b, h) + boff + n * 2048 + k * 1024); } while (0)
; #define PG8_MMA(ai, bj, At, Bt) do { __builtin_amdgcn_s_setprio(1); _Pragma("unroll") for (int m = 0; m < 4; ++m) _Pragma("unroll") for (int n = 0; n < 2; ++n) _Pragma("unroll") for (int k = 0; k < 2; ++k) \
;         acc[ai][bj][m][n] = __builtin_amdgcn_mfma_f32_16x16x32_bf16(Bt[n][k], At[m][k], acc[ai][bj][m][n], 0, 0, 0); __builtin_amdgcn_s_setprio(0); } while (0)
; #define PG8_WAIT_V(n) asm volatile("s_waitcnt vmcnt(" #n ")" ::: "memory")
; #define PG8_WAIT_L(n) asm volatile("s_waitcnt lgkmcnt(" #n ")" ::: "memory")
; #define PG8_BAR __builtin_amdgcn_s_barrier()
; #define PG8_SCHED __builtin_amdgcn_sched_barrier(0)
; template <class Epi, class Sched, bool ALIGN_EPI = false, bool SP2 = false>
; __device__ __forceinline__ void gemm_phase(PG8_LAS unsigned char* lds, const Gemm g, const Sched& S, const Epi& E) {
;     ...
;             PG8_LDB(B0, 0, 0); PG8_LDB(B1, 0, 1); PG8_SCHED; PG8_LDA(At, 0, 0); PG8_STAGE(PG8_SA(1, 1), a1 + hstep, voffA);
;             PG8_WAIT_V(8); PG8_WAIT_L(0); PG8_BAR; PG8_MMA(0, 0, At, B0); PG8_MMA(0, 1, At, B1); PG8_BAR; PG8_SCHED;
;             PG8_LDA(At, 0, 1); PG8_STAGE(PG8_SB(0, 0), b2, voffB); PG8_STAGE(PG8_SB(0, 1), b2 + hstep, voffB); PG8_STAGE(PG8_SA(0, 0), a2, voffA);
;             PG8_WAIT_V(8); PG8_WAIT_L(0); PG8_BAR; PG8_MMA(1, 0, At, B0); PG8_MMA(1, 1, At, B1); PG8_BAR; PG8_SCHED;
.LBB0_210:
	ds_read_b128 v[146:149], v152
	ds_read_b128 v[156:159], v152 offset:1024
	ds_read_b128 v[160:163], v152 offset:2048
	ds_read_b128 v[164:167], v152 offset:3072
	ds_read_b128 v[168:171], v153
	ds_read_b128 v[172:175], v153 offset:1024
	ds_read_b128 v[176:179], v153 offset:2048
	ds_read_b128 v[180:183], v153 offset:3072
	s_add_u32 s62, s60, 0xfff80080
	s_addc_u32 s63, s61, -1
	s_cmp_eq_u32 s75, 28
	s_cselect_b32 s65, s21, s63
	s_cselect_b32 s64, s71, s62
	s_cselect_b32 s63, s19, s74
	s_cselect_b32 s62, s72, s73
	v_lshl_add_u64 v[208:209], s[60:61], 0, v[138:139]
	s_add_i32 m0, s43, 0xc000
	ds_read_b128 v[184:187], v154
	ds_read_b128 v[188:191], v154 offset:1024
	ds_read_b128 v[192:195], v154 offset:2048
	ds_read_b128 v[196:199], v154 offset:3072
	ds_read_b128 v[200:203], v154 offset:4096
	ds_read_b128 v[204:207], v154 offset:5120
	ds_read_b128 v[212:215], v154 offset:6144
	ds_read_b128 v[216:219], v154 offset:7168
	global_load_lds_dwordx4 v[208:209], off
	v_lshl_add_u64 v[208:209], s[60:61], 0, v[140:141]
	s_add_i32 m0, s43, 0xe000
	s_nop 0
	global_load_lds_dwordx4 v[208:209], off
	s_waitcnt vmcnt(8)
	s_waitcnt lgkmcnt(0)
	s_waitcnt lgkmcnt(0)
	v_mfma_f32_16x16x32_bf16 v[124:127], v[146:149], v[184:187], v[124:127]
	v_mfma_f32_16x16x32_bf16 v[120:123], v[160:163], v[184:187], v[120:123]
	v_mfma_f32_16x16x32_bf16 v[116:119], v[146:149], v[192:195], v[116:119]
	v_mfma_f32_16x16x32_bf16 v[108:111], v[160:163], v[192:195], v[108:111]
	v_mfma_f32_16x16x32_bf16 v[100:103], v[146:149], v[200:203], v[100:103]
	v_mfma_f32_16x16x32_bf16 v[92:95], v[160:163], v[200:203], v[92:95]
	v_mfma_f32_16x16x32_bf16 v[84:87], v[146:149], v[212:215], v[84:87]
	v_mfma_f32_16x16x32_bf16 v[76:79], v[160:163], v[212:215], v[76:79]
	s_barrier
	s_setprio 1
	v_mfma_f32_16x16x32_bf16 v[124:127], v[156:159], v[188:191], v[124:127]
	v_mfma_f32_16x16x32_bf16 v[120:123], v[164:167], v[188:191], v[120:123]
	v_mfma_f32_16x16x32_bf16 v[116:119], v[156:159], v[196:199], v[116:119]
	v_mfma_f32_16x16x32_bf16 v[108:111], v[164:167], v[196:199], v[108:111]
	v_mfma_f32_16x16x32_bf16 v[100:103], v[156:159], v[204:207], v[100:103]
	v_mfma_f32_16x16x32_bf16 v[92:95], v[164:167], v[204:207], v[92:95]
	v_mfma_f32_16x16x32_bf16 v[84:87], v[156:159], v[216:219], v[84:87]
	v_mfma_f32_16x16x32_bf16 v[76:79], v[164:167], v[216:219], v[76:79]
	s_setprio 0
	s_setprio 1
	v_mfma_f32_16x16x32_bf16 v[112:115], v[168:171], v[184:187], v[112:115]
	v_mfma_f32_16x16x32_bf16 v[104:107], v[176:179], v[184:187], v[104:107]
	v_mfma_f32_16x16x32_bf16 v[96:99], v[168:171], v[192:195], v[96:99]
	v_mfma_f32_16x16x32_bf16 v[88:91], v[176:179], v[192:195], v[88:91]
	v_mfma_f32_16x16x32_bf16 v[80:83], v[168:171], v[200:203], v[80:83]
	v_mfma_f32_16x16x32_bf16 v[72:75], v[176:179], v[200:203], v[72:75]
	v_mfma_f32_16x16x32_bf16 v[68:71], v[168:171], v[212:215], v[68:71]
	v_mfma_f32_16x16x32_bf16 v[64:67], v[176:179], v[212:215], v[64:67]
	v_mfma_f32_16x16x32_bf16 v[112:115], v[172:175], v[188:191], v[112:115]
	v_mfma_f32_16x16x32_bf16 v[104:107], v[180:183], v[188:191], v[104:107]
	v_mfma_f32_16x16x32_bf16 v[96:99], v[172:175], v[196:199], v[96:99]
	v_mfma_f32_16x16x32_bf16 v[88:91], v[180:183], v[196:199], v[88:91]
	v_mfma_f32_16x16x32_bf16 v[80:83], v[172:175], v[204:207], v[80:83]
	v_mfma_f32_16x16x32_bf16 v[72:75], v[180:183], v[204:207], v[72:75]
	v_mfma_f32_16x16x32_bf16 v[68:71], v[172:175], v[216:219], v[68:71]
	v_mfma_f32_16x16x32_bf16 v[64:67], v[180:183], v[216:219], v[64:67]
	s_setprio 0
	s_barrier
	s_add_i32 s76, s66, s0
	v_lshl_add_u64 v[208:209], s[62:63], 0, v[132:133]
	s_mov_b32 m0, s76
	ds_read_b128 v[184:187], v154 offset:16384
	ds_read_b128 v[188:191], v154 offset:17408
	ds_read_b128 v[192:195], v154 offset:18432
	ds_read_b128 v[196:199], v154 offset:19456
	ds_read_b128 v[200:203], v154 offset:20480
	ds_read_b128 v[204:207], v154 offset:21504
	ds_read_b128 v[212:215], v154 offset:22528
	ds_read_b128 v[216:219], v154 offset:23552
	global_load_lds_dwordx4 v[208:209], off
	s_add_i32 m0, s76, 0x2000
	s_add_u32 s76, s62, 0x80000
	v_lshl_add_u64 v[220:221], s[62:63], 0, v[128:129]
	s_addc_u32 s77, s63, 0
	s_add_i32 s78, s67, s0
	global_load_lds_dwordx4 v[220:221], off
	v_lshl_add_u64 v[222:223], s[76:77], 0, v[132:133]
	s_mov_b32 m0, s78
	v_lshl_add_u64 v[224:225], s[64:65], 0, v[130:131]
	global_load_lds_dwordx4 v[222:223], off
	v_lshl_add_u64 v[222:223], s[76:77], 0, v[128:129]
	s_add_i32 m0, s78, 0x2000
	s_nop 0
	global_load_lds_dwordx4 v[222:223], off
	v_lshl_add_u64 v[222:223], s[64:65], 0, v[134:135]
	s_mov_b32 m0, s43
	s_nop 0
	global_load_lds_dwordx4 v[222:223], off
	s_mov_b32 m0, s46
	s_nop 0
	global_load_lds_dwordx4 v[224:225], off
	s_waitcnt vmcnt(8)
	s_waitcnt lgkmcnt(0)
	s_waitcnt lgkmcnt(0)
	v_mfma_f32_16x16x32_bf16 v[60:63], v[146:149], v[184:187], v[60:63]
	v_mfma_f32_16x16x32_bf16 v[56:59], v[160:163], v[184:187], v[56:59]
	v_mfma_f32_16x16x32_bf16 v[52:55], v[146:149], v[192:195], v[52:55]
	v_mfma_f32_16x16x32_bf16 v[44:47], v[160:163], v[192:195], v[44:47]
	v_mfma_f32_16x16x32_bf16 v[36:39], v[146:149], v[200:203], v[36:39]
	v_mfma_f32_16x16x32_bf16 v[28:31], v[160:163], v[200:203], v[28:31]
	v_mfma_f32_16x16x32_bf16 v[20:23], v[146:149], v[212:215], v[20:23]
	v_mfma_f32_16x16x32_bf16 v[12:15], v[160:163], v[212:215], v[12:15]
	s_barrier
; #define PG8_STAGE(bufoff, gbase, voff) do { _Pragma("unroll") for (int _i = 0; _i < 2; ++_i) \
;         __builtin_amdgcn_global_load_lds((const unsigned*)((const char*)(gbase) + (voff)[_i]), (PG8_LAS unsigned*)(lds + (bufoff) + ldsw + _i * 8192), 16, 0, 0); } while (0)
; #define PG8_LDA(dst, b, h) do { _Pragma("unroll") for (int m = 0; m < 4; ++m) _Pragma("unroll") for (int k = 0; k < 2; ++k) dst[m][k] = *(const PG8_LAS bf16x8*)(lds + PG8_SA(b, h) + aoff + m * 2048 + k * 1024); } while (0)
; #define PG8_LDB(dst, b, h) do { _Pragma("unroll") for (int n = 0; n < 2; ++n) _Pragma("unroll") for (int k = 0; k < 2; ++k) dst[n][k] = *(const PG8_LAS bf16x8*)(lds + PG8_SB(b, h) + boff + n * 2048 + k * 1024); } while (0)
; #define PG8_MMA(ai, bj, At, Bt) do { __builtin_amdgcn_s_setprio(1); _Pragma("unroll") for (int m = 0; m < 4; ++m) _Pragma("unroll") for (int n = 0; n < 2; ++n) _Pragma("unroll") for (int k = 0; k < 2; ++k) \
;         acc[ai][bj][m][n] = __builtin_amdgcn_mfma_f32_16x16x32_bf16(Bt[n][k], At[m][k], acc[ai][bj][m][n], 0, 0, 0); __builtin_amdgcn_s_setprio(0); } while (0)
; #define PG8_WAIT_V(n) asm volatile("s_waitcnt vmcnt(" #n ")" ::: "memory")
; #define PG8_WAIT_L(n) asm volatile("s_waitcnt lgkmcnt(" #n ")" ::: "memory")
; #define PG8_BAR __builtin_amdgcn_s_barrier()
; #define PG8_SCHED __builtin_amdgcn_sched_barrier(0)
; template <class Epi, class Sched, bool ALIGN_EPI = false, bool SP2 = false>
; __device__ __forceinline__ void gemm_phase(PG8_LAS unsigned char* lds, const Gemm g, const Sched& S, const Epi& E) {
;     ...
;             PG8_WAIT_V(8); PG8_WAIT_L(0); PG8_BAR; PG8_MMA(1, 0, At, B0); PG8_MMA(1, 1, At, B1); PG8_BAR; PG8_SCHED;
;             PG8_LDB(B0, 1, 0); PG8_LDB(B1, 1, 1); PG8_SCHED; PG8_LDA(At, 1, 0); PG8_STAGE(PG8_SA(0, 1), a2 + hstep, voffA);
;             PG8_WAIT_V(8); PG8_WAIT_L(0); PG8_BAR; PG8_MMA(0, 0, At, B0); PG8_MMA(0, 1, At, B1); PG8_BAR; PG8_SCHED;
	s_setprio 1
	v_mfma_f32_16x16x32_bf16 v[60:63], v[156:159], v[188:191], v[60:63]
	v_mfma_f32_16x16x32_bf16 v[56:59], v[164:167], v[188:191], v[56:59]
	v_mfma_f32_16x16x32_bf16 v[52:55], v[156:159], v[196:199], v[52:55]
	v_mfma_f32_16x16x32_bf16 v[44:47], v[164:167], v[196:199], v[44:47]
	v_mfma_f32_16x16x32_bf16 v[36:39], v[156:159], v[204:207], v[36:39]
	v_mfma_f32_16x16x32_bf16 v[28:31], v[164:167], v[204:207], v[28:31]
	v_mfma_f32_16x16x32_bf16 v[20:23], v[156:159], v[216:219], v[20:23]
	v_mfma_f32_16x16x32_bf16 v[12:15], v[164:167], v[216:219], v[12:15]
	s_setprio 0
	s_setprio 1
	v_mfma_f32_16x16x32_bf16 v[48:51], v[168:171], v[184:187], v[48:51]
	v_mfma_f32_16x16x32_bf16 v[40:43], v[176:179], v[184:187], v[40:43]
	v_mfma_f32_16x16x32_bf16 v[32:35], v[168:171], v[192:195], v[32:35]
	v_mfma_f32_16x16x32_bf16 v[24:27], v[176:179], v[192:195], v[24:27]
	v_mfma_f32_16x16x32_bf16 v[16:19], v[168:171], v[200:203], v[16:19]
	v_mfma_f32_16x16x32_bf16 v[8:11], v[176:179], v[200:203], v[8:11]
	v_mfma_f32_16x16x32_bf16 v[4:7], v[168:171], v[212:215], v[4:7]
	v_mfma_f32_16x16x32_bf16 v[0:3], v[176:179], v[212:215], v[0:3]
	v_mfma_f32_16x16x32_bf16 v[48:51], v[172:175], v[188:191], v[48:51]
	v_mfma_f32_16x16x32_bf16 v[40:43], v[180:183], v[188:191], v[40:43]
	v_mfma_f32_16x16x32_bf16 v[32:35], v[172:175], v[196:199], v[32:35]
	v_mfma_f32_16x16x32_bf16 v[24:27], v[180:183], v[196:199], v[24:27]
	v_mfma_f32_16x16x32_bf16 v[16:19], v[172:175], v[204:207], v[16:19]
	v_mfma_f32_16x16x32_bf16 v[8:11], v[180:183], v[204:207], v[8:11]
	v_mfma_f32_16x16x32_bf16 v[4:7], v[172:175], v[216:219], v[4:7]
	v_mfma_f32_16x16x32_bf16 v[0:3], v[180:183], v[216:219], v[0:3]
	s_setprio 0
	s_barrier
	s_add_i32 s76, 0, 0x18000
	v_add_u32_e32 v155, s76, v151
	s_add_i32 s77, 0, 0x1c000
	ds_read_b128 v[146:149], v155
	ds_read_b128 v[156:159], v155 offset:1024
	ds_read_b128 v[160:163], v155 offset:2048
	ds_read_b128 v[164:167], v155 offset:3072
	v_add_u32_e32 v155, s77, v151
	ds_read_b128 v[168:171], v155
	ds_read_b128 v[172:175], v155 offset:1024
	ds_read_b128 v[176:179], v155 offset:2048
	ds_read_b128 v[180:183], v155 offset:3072
	s_add_u32 s64, s64, 0x80000
	s_addc_u32 s65, s65, 0
	s_mov_b32 m0, s47
	v_lshl_add_u64 v[226:227], s[64:65], 0, v[134:135]
	ds_read_b128 v[184:187], v154 offset:32768
	ds_read_b128 v[188:191], v154 offset:33792
	ds_read_b128 v[192:195], v154 offset:34816
	ds_read_b128 v[196:199], v154 offset:35840
	ds_read_b128 v[200:203], v154 offset:36864
	ds_read_b128 v[204:207], v154 offset:37888
	ds_read_b128 v[212:215], v154 offset:38912
	ds_read_b128 v[216:219], v154 offset:39936
	global_load_lds_dwordx4 v[226:227], off
	v_lshl_add_u64 v[226:227], s[64:65], 0, v[130:131]
	s_mov_b32 m0, s48
	s_nop 0
	global_load_lds_dwordx4 v[226:227], off
	s_waitcnt vmcnt(8)
	s_waitcnt lgkmcnt(0)
	s_waitcnt lgkmcnt(0)
	v_mfma_f32_16x16x32_bf16 v[124:127], v[146:149], v[184:187], v[124:127]
	v_mfma_f32_16x16x32_bf16 v[120:123], v[160:163], v[184:187], v[120:123]
	v_mfma_f32_16x16x32_bf16 v[116:119], v[146:149], v[192:195], v[116:119]
	v_mfma_f32_16x16x32_bf16 v[108:111], v[160:163], v[192:195], v[108:111]
	v_mfma_f32_16x16x32_bf16 v[100:103], v[146:149], v[200:203], v[100:103]
	v_mfma_f32_16x16x32_bf16 v[92:95], v[160:163], v[200:203], v[92:95]
	v_mfma_f32_16x16x32_bf16 v[84:87], v[146:149], v[212:215], v[84:87]
	v_mfma_f32_16x16x32_bf16 v[76:79], v[160:163], v[212:215], v[76:79]
	s_barrier
	s_setprio 1
	v_mfma_f32_16x16x32_bf16 v[124:127], v[156:159], v[188:191], v[124:127]
	v_mfma_f32_16x16x32_bf16 v[120:123], v[164:167], v[188:191], v[120:123]
	v_mfma_f32_16x16x32_bf16 v[116:119], v[156:159], v[196:199], v[116:119]
	v_mfma_f32_16x16x32_bf16 v[108:111], v[164:167], v[196:199], v[108:111]
	v_mfma_f32_16x16x32_bf16 v[100:103], v[156:159], v[204:207], v[100:103]
	v_mfma_f32_16x16x32_bf16 v[92:95], v[164:167], v[204:207], v[92:95]
	v_mfma_f32_16x16x32_bf16 v[84:87], v[156:159], v[216:219], v[84:87]
	v_mfma_f32_16x16x32_bf16 v[76:79], v[164:167], v[216:219], v[76:79]
	s_setprio 0
	s_setprio 1
	v_mfma_f32_16x16x32_bf16 v[112:115], v[168:171], v[184:187], v[112:115]
	v_mfma_f32_16x16x32_bf16 v[104:107], v[176:179], v[184:187], v[104:107]
	v_mfma_f32_16x16x32_bf16 v[96:99], v[168:171], v[192:195], v[96:99]
	v_mfma_f32_16x16x32_bf16 v[88:91], v[176:179], v[192:195], v[88:91]
	v_mfma_f32_16x16x32_bf16 v[80:83], v[168:171], v[200:203], v[80:83]
	v_mfma_f32_16x16x32_bf16 v[72:75], v[176:179], v[200:203], v[72:75]
	v_mfma_f32_16x16x32_bf16 v[68:71], v[168:171], v[212:215], v[68:71]
	v_mfma_f32_16x16x32_bf16 v[64:67], v[176:179], v[212:215], v[64:67]
	v_mfma_f32_16x16x32_bf16 v[112:115], v[172:175], v[188:191], v[112:115]
	v_mfma_f32_16x16x32_bf16 v[104:107], v[180:183], v[188:191], v[104:107]
	v_mfma_f32_16x16x32_bf16 v[96:99], v[172:175], v[196:199], v[96:99]
	v_mfma_f32_16x16x32_bf16 v[88:91], v[180:183], v[196:199], v[88:91]
	v_mfma_f32_16x16x32_bf16 v[80:83], v[172:175], v[204:207], v[80:83]
	v_mfma_f32_16x16x32_bf16 v[72:75], v[180:183], v[204:207], v[72:75]
	v_mfma_f32_16x16x32_bf16 v[68:71], v[172:175], v[216:219], v[68:71]
	v_mfma_f32_16x16x32_bf16 v[64:67], v[180:183], v[216:219], v[64:67]
	s_setprio 0
	s_barrier
; #define PG8_STAGE(bufoff, gbase, voff) do { _Pragma("unroll") for (int _i = 0; _i < 2; ++_i) \
;         __builtin_amdgcn_global_load_lds((const unsigned*)((const char*)(gbase) + (voff)[_i]), (PG8_LAS unsigned*)(lds + (bufoff) + ldsw + _i * 8192), 16, 0, 0); } while (0)
; #define PG8_LDA(dst, b, h) do { _Pragma("unroll") for (int m = 0; m < 4; ++m) _Pragma("unroll") for (int k = 0; k < 2; ++k) dst[m][k] = *(const PG8_LAS bf16x8*)(lds + PG8_SA(b, h) + aoff + m * 2048 + k * 1024); } while (0)
; #define PG8_MMA(ai, bj, At, Bt) do { __builtin_amdgcn_s_setprio(1); _Pragma("unroll") for (int m = 0; m < 4; ++m) _Pragma("unroll") for (int n = 0; n < 2; ++n) _Pragma("unroll") for (int k = 0; k < 2; ++k) \
;         acc[ai][bj][m][n] = __builtin_amdgcn_mfma_f32_16x16x32_bf16(Bt[n][k], At[m][k], acc[ai][bj][m][n], 0, 0, 0); __builtin_amdgcn_s_setprio(0); } while (0)
; #define PG8_WAIT_V(n) asm volatile("s_waitcnt vmcnt(" #n ")" ::: "memory")
; #define PG8_WAIT_L(n) asm volatile("s_waitcnt lgkmcnt(" #n ")" ::: "memory")
; #define PG8_BAR __builtin_amdgcn_s_barrier()
; #define PG8_SCHED __builtin_amdgcn_sched_barrier(0)
; template <class Epi, class Sched, bool ALIGN_EPI = false, bool SP2 = false>
; __device__ __forceinline__ void gemm_phase(PG8_LAS unsigned char* lds, const Gemm g, const Sched& S, const Epi& E) {
;     ...
;             PG8_LDA(At, 1, 1); PG8_STAGE(PG8_SB(1, 0), b3, voffB); PG8_STAGE(PG8_SB(1, 1), b3 + hstep, voffB); PG8_STAGE(PG8_SA(1, 0), a3, voffA);
;             PG8_WAIT_V(8); PG8_WAIT_L(0); PG8_BAR; PG8_MMA(1, 0, At, B0); PG8_MMA(1, 1, At, B1); PG8_BAR; PG8_SCHED;
;     ...
;         }
;         if constexpr (ALIGN_EPI) { if (wr == 0) PG8_BAR; }
	s_add_i32 s64, s76, s0
	v_lshl_add_u64 v[208:209], v[208:209], 0, s[14:15]
	s_mov_b32 m0, s64
	ds_read_b128 v[184:187], v154 offset:49152
	ds_read_b128 v[188:191], v154 offset:50176
	ds_read_b128 v[192:195], v154 offset:51200
	ds_read_b128 v[196:199], v154 offset:52224
	ds_read_b128 v[200:203], v154 offset:53248
	ds_read_b128 v[204:207], v154 offset:54272
	ds_read_b128 v[212:215], v154 offset:55296
	ds_read_b128 v[216:219], v154 offset:56320
	global_load_lds_dwordx4 v[208:209], off
	s_add_i32 m0, s64, 0x2000
	s_add_u32 s62, s62, 0x80080
	v_lshl_add_u64 v[208:209], v[220:221], 0, s[14:15]
	s_addc_u32 s63, s63, 0
	s_add_i32 s64, s77, s0
	global_load_lds_dwordx4 v[208:209], off
	v_lshl_add_u64 v[208:209], s[62:63], 0, v[132:133]
	s_mov_b32 m0, s64
	s_nop 0
	global_load_lds_dwordx4 v[208:209], off
	v_lshl_add_u64 v[208:209], s[62:63], 0, v[128:129]
	s_add_i32 m0, s64, 0x2000
	s_nop 0
	global_load_lds_dwordx4 v[208:209], off
	v_lshl_add_u64 v[208:209], v[222:223], 0, s[14:15]
	s_mov_b32 m0, s51
	s_nop 0
	global_load_lds_dwordx4 v[208:209], off
	v_lshl_add_u64 v[208:209], v[224:225], 0, s[14:15]
	s_mov_b32 m0, s56
	s_nop 0
	global_load_lds_dwordx4 v[208:209], off
	s_waitcnt vmcnt(8)
	s_waitcnt lgkmcnt(0)
	s_waitcnt lgkmcnt(0)
	v_mfma_f32_16x16x32_bf16 v[60:63], v[146:149], v[184:187], v[60:63]
	v_mfma_f32_16x16x32_bf16 v[56:59], v[160:163], v[184:187], v[56:59]
	v_mfma_f32_16x16x32_bf16 v[52:55], v[146:149], v[192:195], v[52:55]
	v_mfma_f32_16x16x32_bf16 v[44:47], v[160:163], v[192:195], v[44:47]
	v_mfma_f32_16x16x32_bf16 v[36:39], v[146:149], v[200:203], v[36:39]
	v_mfma_f32_16x16x32_bf16 v[28:31], v[160:163], v[200:203], v[28:31]
	v_mfma_f32_16x16x32_bf16 v[20:23], v[146:149], v[212:215], v[20:23]
	v_mfma_f32_16x16x32_bf16 v[12:15], v[160:163], v[212:215], v[12:15]
	s_barrier
	s_setprio 1
	v_mfma_f32_16x16x32_bf16 v[60:63], v[156:159], v[188:191], v[60:63]
	v_mfma_f32_16x16x32_bf16 v[56:59], v[164:167], v[188:191], v[56:59]
	v_mfma_f32_16x16x32_bf16 v[52:55], v[156:159], v[196:199], v[52:55]
	v_mfma_f32_16x16x32_bf16 v[44:47], v[164:167], v[196:199], v[44:47]
	v_mfma_f32_16x16x32_bf16 v[36:39], v[156:159], v[204:207], v[36:39]
	v_mfma_f32_16x16x32_bf16 v[28:31], v[164:167], v[204:207], v[28:31]
	v_mfma_f32_16x16x32_bf16 v[20:23], v[156:159], v[216:219], v[20:23]
	v_mfma_f32_16x16x32_bf16 v[12:15], v[164:167], v[216:219], v[12:15]
	s_setprio 0
	s_setprio 1
	v_mfma_f32_16x16x32_bf16 v[48:51], v[168:171], v[184:187], v[48:51]
	v_mfma_f32_16x16x32_bf16 v[40:43], v[176:179], v[184:187], v[40:43]
	v_mfma_f32_16x16x32_bf16 v[32:35], v[168:171], v[192:195], v[32:35]
	v_mfma_f32_16x16x32_bf16 v[24:27], v[176:179], v[192:195], v[24:27]
	v_mfma_f32_16x16x32_bf16 v[16:19], v[168:171], v[200:203], v[16:19]
	v_mfma_f32_16x16x32_bf16 v[8:11], v[176:179], v[200:203], v[8:11]
	v_mfma_f32_16x16x32_bf16 v[4:7], v[168:171], v[212:215], v[4:7]
	v_mfma_f32_16x16x32_bf16 v[0:3], v[176:179], v[212:215], v[0:3]
	v_mfma_f32_16x16x32_bf16 v[48:51], v[172:175], v[188:191], v[48:51]
	v_mfma_f32_16x16x32_bf16 v[40:43], v[180:183], v[188:191], v[40:43]
	v_mfma_f32_16x16x32_bf16 v[32:35], v[172:175], v[196:199], v[32:35]
	v_mfma_f32_16x16x32_bf16 v[24:27], v[180:183], v[196:199], v[24:27]
	v_mfma_f32_16x16x32_bf16 v[16:19], v[172:175], v[204:207], v[16:19]
	v_mfma_f32_16x16x32_bf16 v[8:11], v[180:183], v[204:207], v[8:11]
	v_mfma_f32_16x16x32_bf16 v[4:7], v[172:175], v[216:219], v[4:7]
	v_mfma_f32_16x16x32_bf16 v[0:3], v[180:183], v[216:219], v[0:3]
	s_setprio 0
	s_barrier
	s_add_i32 s75, s75, 2
	s_add_u32 s60, s60, 0x100
	s_addc_u32 s61, s61, 0
	s_add_u32 s73, s73, 0x100
	s_addc_u32 s74, s74, 0
	s_cmp_gt_u32 s75, 29
	s_cbranch_scc0 .LBB0_210
	s_and_b64 vcc, exec, s[16:17]
	s_cbranch_vccz .LBB0_213
	s_barrier

; #define PG8_STAGE(bufoff, gbase, voff) do { _Pragma("unroll") for (int _i = 0; _i < 2; ++_i) \
;         __builtin_amdgcn_global_load_lds((const unsigned*)((const char*)(gbase) + (voff)[_i]), (PG8_LAS unsigned*)(lds + (bufoff) + ldsw + _i * 8192), 16, 0, 0); } while (0)
; #define PG8_LDA(dst, b, h) do { _Pragma("unroll") for (int m = 0; m < 4; ++m) _Pragma("unroll") for (int k = 0; k < 2; ++k) dst[m][k] = *(const PG8_LAS bf16x8*)(lds + PG8_SA(b, h) + aoff + m * 2048 + k * 1024); } while (0)
; #define PG8_LDB(dst, b, h) do { _Pragma("unroll") for (int n = 0; n < 2; ++n) _Pragma("unroll") for (int k = 0; k < 2; ++k) dst[n][k] = *(const PG8_LAS bf16x8*)(lds + PG8_SB(b, h) + boff + n * 2048 + k * 1024); } while (0)
; #define PG8_MMA(ai, bj, At, Bt) do { __builtin_amdgcn_s_setprio(1); _Pragma("unroll") for (int m = 0; m < 4; ++m) _Pragma("unroll") for (int n = 0; n < 2; ++n) _Pragma("unroll") for (int k = 0; k < 2; ++k) \
;         acc[ai][bj][m][n] = __builtin_amdgcn_mfma_f32_16x16x32_bf16(Bt[n][k], At[m][k], acc[ai][bj][m][n], 0, 0, 0); __builtin_amdgcn_s_setprio(0); } while (0)
; #define PG8_WAIT_V(n) asm volatile("s_waitcnt vmcnt(" #n ")" ::: "memory")
; #define PG8_WAIT_L(n) asm volatile("s_waitcnt lgkmcnt(" #n ")" ::: "memory")
; #define PG8_BAR __builtin_amdgcn_s_barrier()
; #define PG8_SCHED __builtin_amdgcn_sched_barrier(0)
; template <class Epi, class Sched, bool ALIGN_EPI = false, bool SP2 = false>
; __device__ __forceinline__ void gemm_phase(PG8_LAS unsigned char* lds, const Gemm g, const Sched& S, const Epi& E) {
;     ...
;             PG8_LDB(B0, 0, 0); PG8_LDB(B1, 0, 1); PG8_SCHED; PG8_LDA(At, 0, 0); PG8_STAGE(PG8_SA(1, 1), a1 + hstep, voffA);
;             PG8_WAIT_V(8); PG8_WAIT_L(0); PG8_BAR; PG8_MMA(0, 0, At, B0); PG8_MMA(0, 1, At, B1); PG8_BAR; PG8_SCHED;
;             PG8_LDA(At, 0, 1); PG8_STAGE(PG8_SB(0, 0), b2, voffB); PG8_STAGE(PG8_SB(0, 1), b2 + hstep, voffB); PG8_STAGE(PG8_SA(0, 0), a2, voffA);
;             PG8_WAIT_V(8); PG8_WAIT_L(0); PG8_BAR; PG8_MMA(1, 0, At, B0); PG8_MMA(1, 1, At, B1); PG8_BAR; PG8_SCHED;
.LBB0_528:
	ds_read_b128 v[152:155], v149
	ds_read_b128 v[156:159], v149 offset:1024
	ds_read_b128 v[160:163], v149 offset:2048
	ds_read_b128 v[164:167], v149 offset:3072
	ds_read_b128 v[168:171], v150
	ds_read_b128 v[172:175], v150 offset:1024
	ds_read_b128 v[176:179], v150 offset:2048
	ds_read_b128 v[180:183], v150 offset:3072
	s_add_u32 s68, s66, 0xfff80080
	s_addc_u32 s69, s67, -1
	s_cmp_eq_u32 s81, 28
	s_cselect_b32 s71, s39, s69
	s_cselect_b32 s70, s77, s68
	s_cselect_b32 s69, s35, s80
	s_cselect_b32 s68, s78, s79
	v_lshl_add_u64 v[144:145], s[66:67], 0, v[136:137]
	s_add_i32 m0, s41, 0xc000
	ds_read_b128 v[184:187], v151
	ds_read_b128 v[188:191], v151 offset:1024
	ds_read_b128 v[192:195], v151 offset:2048
	ds_read_b128 v[196:199], v151 offset:3072
	ds_read_b128 v[200:203], v151 offset:4096
	ds_read_b128 v[204:207], v151 offset:5120
	ds_read_b128 v[214:217], v151 offset:6144
	ds_read_b128 v[218:221], v151 offset:7168
	global_load_lds_dwordx4 v[144:145], off
	v_lshl_add_u64 v[144:145], s[66:67], 0, v[138:139]
	s_add_i32 m0, s41, 0xe000
	s_nop 0
	global_load_lds_dwordx4 v[144:145], off
	s_waitcnt vmcnt(8)
	s_waitcnt lgkmcnt(0)
	s_waitcnt lgkmcnt(0)
	v_mfma_f32_16x16x32_bf16 v[124:127], v[152:155], v[184:187], v[124:127]
	v_mfma_f32_16x16x32_bf16 v[120:123], v[160:163], v[184:187], v[120:123]
	v_mfma_f32_16x16x32_bf16 v[116:119], v[152:155], v[192:195], v[116:119]
	v_mfma_f32_16x16x32_bf16 v[108:111], v[160:163], v[192:195], v[108:111]
	v_mfma_f32_16x16x32_bf16 v[100:103], v[152:155], v[200:203], v[100:103]
	v_mfma_f32_16x16x32_bf16 v[92:95], v[160:163], v[200:203], v[92:95]
	v_mfma_f32_16x16x32_bf16 v[84:87], v[152:155], v[214:217], v[84:87]
	v_mfma_f32_16x16x32_bf16 v[76:79], v[160:163], v[214:217], v[76:79]
	s_barrier
	s_setprio 1
	v_mfma_f32_16x16x32_bf16 v[124:127], v[156:159], v[188:191], v[124:127]
	v_mfma_f32_16x16x32_bf16 v[120:123], v[164:167], v[188:191], v[120:123]
	v_mfma_f32_16x16x32_bf16 v[116:119], v[156:159], v[196:199], v[116:119]
	v_mfma_f32_16x16x32_bf16 v[108:111], v[164:167], v[196:199], v[108:111]
	v_mfma_f32_16x16x32_bf16 v[100:103], v[156:159], v[204:207], v[100:103]
	v_mfma_f32_16x16x32_bf16 v[92:95], v[164:167], v[204:207], v[92:95]
	v_mfma_f32_16x16x32_bf16 v[84:87], v[156:159], v[218:221], v[84:87]
	v_mfma_f32_16x16x32_bf16 v[76:79], v[164:167], v[218:221], v[76:79]
	s_setprio 0
	s_setprio 1
	v_mfma_f32_16x16x32_bf16 v[112:115], v[168:171], v[184:187], v[112:115]
	v_mfma_f32_16x16x32_bf16 v[104:107], v[176:179], v[184:187], v[104:107]
	v_mfma_f32_16x16x32_bf16 v[96:99], v[168:171], v[192:195], v[96:99]
	v_mfma_f32_16x16x32_bf16 v[88:91], v[176:179], v[192:195], v[88:91]
	v_mfma_f32_16x16x32_bf16 v[80:83], v[168:171], v[200:203], v[80:83]
	v_mfma_f32_16x16x32_bf16 v[72:75], v[176:179], v[200:203], v[72:75]
	v_mfma_f32_16x16x32_bf16 v[68:71], v[168:171], v[214:217], v[68:71]
	v_mfma_f32_16x16x32_bf16 v[64:67], v[176:179], v[214:217], v[64:67]
	v_mfma_f32_16x16x32_bf16 v[112:115], v[172:175], v[188:191], v[112:115]
	v_mfma_f32_16x16x32_bf16 v[104:107], v[180:183], v[188:191], v[104:107]
	v_mfma_f32_16x16x32_bf16 v[96:99], v[172:175], v[196:199], v[96:99]
	v_mfma_f32_16x16x32_bf16 v[88:91], v[180:183], v[196:199], v[88:91]
	v_mfma_f32_16x16x32_bf16 v[80:83], v[172:175], v[204:207], v[80:83]
	v_mfma_f32_16x16x32_bf16 v[72:75], v[180:183], v[204:207], v[72:75]
	v_mfma_f32_16x16x32_bf16 v[68:71], v[172:175], v[218:221], v[68:71]
	v_mfma_f32_16x16x32_bf16 v[64:67], v[180:183], v[218:221], v[64:67]
	s_setprio 0
	s_barrier
	s_add_i32 s82, s57, s0
	v_lshl_add_u64 v[144:145], s[68:69], 0, v[132:133]
	s_mov_b32 m0, s82
	ds_read_b128 v[184:187], v151 offset:16384
	ds_read_b128 v[188:191], v151 offset:17408
	ds_read_b128 v[192:195], v151 offset:18432
	ds_read_b128 v[196:199], v151 offset:19456
	ds_read_b128 v[200:203], v151 offset:20480
	ds_read_b128 v[204:207], v151 offset:21504
	ds_read_b128 v[214:217], v151 offset:22528
	ds_read_b128 v[218:221], v151 offset:23552
	global_load_lds_dwordx4 v[144:145], off
	s_add_i32 m0, s82, 0x2000
	s_add_u32 s82, s68, 0x80000
	v_lshl_add_u64 v[222:223], s[68:69], 0, v[128:129]
	s_addc_u32 s83, s69, 0
	s_add_i32 s84, s65, s0
	global_load_lds_dwordx4 v[222:223], off
	v_lshl_add_u64 v[224:225], s[82:83], 0, v[132:133]
	s_mov_b32 m0, s84
	v_lshl_add_u64 v[226:227], s[70:71], 0, v[130:131]
	global_load_lds_dwordx4 v[224:225], off
	v_lshl_add_u64 v[224:225], s[82:83], 0, v[128:129]
	s_add_i32 m0, s84, 0x2000
	s_nop 0
	global_load_lds_dwordx4 v[224:225], off
	v_lshl_add_u64 v[224:225], s[70:71], 0, v[134:135]
	s_mov_b32 m0, s41
	s_nop 0
	global_load_lds_dwordx4 v[224:225], off
	s_mov_b32 m0, s43
	s_nop 0
	global_load_lds_dwordx4 v[226:227], off
	s_waitcnt vmcnt(8)
	s_waitcnt lgkmcnt(0)
	s_waitcnt lgkmcnt(0)
	v_mfma_f32_16x16x32_bf16 v[60:63], v[152:155], v[184:187], v[60:63]
	v_mfma_f32_16x16x32_bf16 v[56:59], v[160:163], v[184:187], v[56:59]
	v_mfma_f32_16x16x32_bf16 v[52:55], v[152:155], v[192:195], v[52:55]
	v_mfma_f32_16x16x32_bf16 v[44:47], v[160:163], v[192:195], v[44:47]
	v_mfma_f32_16x16x32_bf16 v[36:39], v[152:155], v[200:203], v[36:39]
	v_mfma_f32_16x16x32_bf16 v[28:31], v[160:163], v[200:203], v[28:31]
	v_mfma_f32_16x16x32_bf16 v[20:23], v[152:155], v[214:217], v[20:23]
	v_mfma_f32_16x16x32_bf16 v[12:15], v[160:163], v[214:217], v[12:15]
	s_barrier
; #define PG8_STAGE(bufoff, gbase, voff) do { _Pragma("unroll") for (int _i = 0; _i < 2; ++_i) \
;         __builtin_amdgcn_global_load_lds((const unsigned*)((const char*)(gbase) + (voff)[_i]), (PG8_LAS unsigned*)(lds + (bufoff) + ldsw + _i * 8192), 16, 0, 0); } while (0)
; #define PG8_LDA(dst, b, h) do { _Pragma("unroll") for (int m = 0; m < 4; ++m) _Pragma("unroll") for (int k = 0; k < 2; ++k) dst[m][k] = *(const PG8_LAS bf16x8*)(lds + PG8_SA(b, h) + aoff + m * 2048 + k * 1024); } while (0)
; #define PG8_LDB(dst, b, h) do { _Pragma("unroll") for (int n = 0; n < 2; ++n) _Pragma("unroll") for (int k = 0; k < 2; ++k) dst[n][k] = *(const PG8_LAS bf16x8*)(lds + PG8_SB(b, h) + boff + n * 2048 + k * 1024); } while (0)
; #define PG8_MMA(ai, bj, At, Bt) do { __builtin_amdgcn_s_setprio(1); _Pragma("unroll") for (int m = 0; m < 4; ++m) _Pragma("unroll") for (int n = 0; n < 2; ++n) _Pragma("unroll") for (int k = 0; k < 2; ++k) \
;         acc[ai][bj][m][n] = __builtin_amdgcn_mfma_f32_16x16x32_bf16(Bt[n][k], At[m][k], acc[ai][bj][m][n], 0, 0, 0); __builtin_amdgcn_s_setprio(0); } while (0)
; #define PG8_WAIT_V(n) asm volatile("s_waitcnt vmcnt(" #n ")" ::: "memory")
; #define PG8_WAIT_L(n) asm volatile("s_waitcnt lgkmcnt(" #n ")" ::: "memory")
; #define PG8_BAR __builtin_amdgcn_s_barrier()
; #define PG8_SCHED __builtin_amdgcn_sched_barrier(0)
; template <class Epi, class Sched, bool ALIGN_EPI = false, bool SP2 = false>
; __device__ __forceinline__ void gemm_phase(PG8_LAS unsigned char* lds, const Gemm g, const Sched& S, const Epi& E) {
;     ...
;             PG8_WAIT_V(8); PG8_WAIT_L(0); PG8_BAR; PG8_MMA(1, 0, At, B0); PG8_MMA(1, 1, At, B1); PG8_BAR; PG8_SCHED;
;             PG8_LDB(B0, 1, 0); PG8_LDB(B1, 1, 1); PG8_SCHED; PG8_LDA(At, 1, 0); PG8_STAGE(PG8_SA(0, 1), a2 + hstep, voffA);
;             PG8_WAIT_V(8); PG8_WAIT_L(0); PG8_BAR; PG8_MMA(0, 0, At, B0); PG8_MMA(0, 1, At, B1); PG8_BAR; PG8_SCHED;
	s_setprio 1
	v_mfma_f32_16x16x32_bf16 v[60:63], v[156:159], v[188:191], v[60:63]
	v_mfma_f32_16x16x32_bf16 v[56:59], v[164:167], v[188:191], v[56:59]
	v_mfma_f32_16x16x32_bf16 v[52:55], v[156:159], v[196:199], v[52:55]
	v_mfma_f32_16x16x32_bf16 v[44:47], v[164:167], v[196:199], v[44:47]
	v_mfma_f32_16x16x32_bf16 v[36:39], v[156:159], v[204:207], v[36:39]
	v_mfma_f32_16x16x32_bf16 v[28:31], v[164:167], v[204:207], v[28:31]
	v_mfma_f32_16x16x32_bf16 v[20:23], v[156:159], v[218:221], v[20:23]
	v_mfma_f32_16x16x32_bf16 v[12:15], v[164:167], v[218:221], v[12:15]
	s_setprio 0
	s_setprio 1
	v_mfma_f32_16x16x32_bf16 v[48:51], v[168:171], v[184:187], v[48:51]
	v_mfma_f32_16x16x32_bf16 v[40:43], v[176:179], v[184:187], v[40:43]
	v_mfma_f32_16x16x32_bf16 v[32:35], v[168:171], v[192:195], v[32:35]
	v_mfma_f32_16x16x32_bf16 v[24:27], v[176:179], v[192:195], v[24:27]
	v_mfma_f32_16x16x32_bf16 v[16:19], v[168:171], v[200:203], v[16:19]
	v_mfma_f32_16x16x32_bf16 v[8:11], v[176:179], v[200:203], v[8:11]
	v_mfma_f32_16x16x32_bf16 v[4:7], v[168:171], v[214:217], v[4:7]
	v_mfma_f32_16x16x32_bf16 v[0:3], v[176:179], v[214:217], v[0:3]
	v_mfma_f32_16x16x32_bf16 v[48:51], v[172:175], v[188:191], v[48:51]
	v_mfma_f32_16x16x32_bf16 v[40:43], v[180:183], v[188:191], v[40:43]
	v_mfma_f32_16x16x32_bf16 v[32:35], v[172:175], v[196:199], v[32:35]
	v_mfma_f32_16x16x32_bf16 v[24:27], v[180:183], v[196:199], v[24:27]
	v_mfma_f32_16x16x32_bf16 v[16:19], v[172:175], v[204:207], v[16:19]
	v_mfma_f32_16x16x32_bf16 v[8:11], v[180:183], v[204:207], v[8:11]
	v_mfma_f32_16x16x32_bf16 v[4:7], v[172:175], v[218:221], v[4:7]
	v_mfma_f32_16x16x32_bf16 v[0:3], v[180:183], v[218:221], v[0:3]
	s_setprio 0
	s_barrier
	s_add_i32 s82, 0, 0x18000
	s_add_i32 s83, 0, 0x1c000
	v_add_u32_e32 v164, s82, v147
	v_add_u32_e32 v180, s83, v147
	ds_read_b128 v[152:155], v164
	ds_read_b128 v[156:159], v164 offset:1024
	ds_read_b128 v[160:163], v164 offset:2048
	ds_read_b128 v[164:167], v164 offset:3072
	ds_read_b128 v[168:171], v180
	ds_read_b128 v[172:175], v180 offset:1024
	ds_read_b128 v[176:179], v180 offset:2048
	ds_read_b128 v[180:183], v180 offset:3072
	s_add_u32 s70, s70, 0x80000
	s_addc_u32 s71, s71, 0
	s_mov_b32 m0, s46
	v_lshl_add_u64 v[228:229], s[70:71], 0, v[134:135]
	ds_read_b128 v[184:187], v151 offset:32768
	ds_read_b128 v[188:191], v151 offset:33792
	ds_read_b128 v[192:195], v151 offset:34816
	ds_read_b128 v[196:199], v151 offset:35840
	ds_read_b128 v[200:203], v151 offset:36864
	ds_read_b128 v[204:207], v151 offset:37888
	ds_read_b128 v[214:217], v151 offset:38912
	ds_read_b128 v[218:221], v151 offset:39936
	global_load_lds_dwordx4 v[228:229], off
	v_lshl_add_u64 v[228:229], s[70:71], 0, v[130:131]
	s_mov_b32 m0, s47
	s_nop 0
	global_load_lds_dwordx4 v[228:229], off
	s_waitcnt vmcnt(8)
	s_waitcnt lgkmcnt(0)
	s_waitcnt lgkmcnt(0)
	v_mfma_f32_16x16x32_bf16 v[124:127], v[152:155], v[184:187], v[124:127]
	v_mfma_f32_16x16x32_bf16 v[120:123], v[160:163], v[184:187], v[120:123]
	v_mfma_f32_16x16x32_bf16 v[116:119], v[152:155], v[192:195], v[116:119]
	v_mfma_f32_16x16x32_bf16 v[108:111], v[160:163], v[192:195], v[108:111]
	v_mfma_f32_16x16x32_bf16 v[100:103], v[152:155], v[200:203], v[100:103]
	v_mfma_f32_16x16x32_bf16 v[92:95], v[160:163], v[200:203], v[92:95]
	v_mfma_f32_16x16x32_bf16 v[84:87], v[152:155], v[214:217], v[84:87]
	v_mfma_f32_16x16x32_bf16 v[76:79], v[160:163], v[214:217], v[76:79]
	s_barrier
	s_setprio 1
	v_mfma_f32_16x16x32_bf16 v[124:127], v[156:159], v[188:191], v[124:127]
	v_mfma_f32_16x16x32_bf16 v[120:123], v[164:167], v[188:191], v[120:123]
	v_mfma_f32_16x16x32_bf16 v[116:119], v[156:159], v[196:199], v[116:119]
	v_mfma_f32_16x16x32_bf16 v[108:111], v[164:167], v[196:199], v[108:111]
	v_mfma_f32_16x16x32_bf16 v[100:103], v[156:159], v[204:207], v[100:103]
	v_mfma_f32_16x16x32_bf16 v[92:95], v[164:167], v[204:207], v[92:95]
	v_mfma_f32_16x16x32_bf16 v[84:87], v[156:159], v[218:221], v[84:87]
	v_mfma_f32_16x16x32_bf16 v[76:79], v[164:167], v[218:221], v[76:79]
	s_setprio 0
	s_setprio 1
	v_mfma_f32_16x16x32_bf16 v[112:115], v[168:171], v[184:187], v[112:115]
	v_mfma_f32_16x16x32_bf16 v[104:107], v[176:179], v[184:187], v[104:107]
	v_mfma_f32_16x16x32_bf16 v[96:99], v[168:171], v[192:195], v[96:99]
	v_mfma_f32_16x16x32_bf16 v[88:91], v[176:179], v[192:195], v[88:91]
	v_mfma_f32_16x16x32_bf16 v[80:83], v[168:171], v[200:203], v[80:83]
	v_mfma_f32_16x16x32_bf16 v[72:75], v[176:179], v[200:203], v[72:75]
	v_mfma_f32_16x16x32_bf16 v[68:71], v[168:171], v[214:217], v[68:71]
	v_mfma_f32_16x16x32_bf16 v[64:67], v[176:179], v[214:217], v[64:67]
	v_mfma_f32_16x16x32_bf16 v[112:115], v[172:175], v[188:191], v[112:115]
	v_mfma_f32_16x16x32_bf16 v[104:107], v[180:183], v[188:191], v[104:107]
	v_mfma_f32_16x16x32_bf16 v[96:99], v[172:175], v[196:199], v[96:99]
	v_mfma_f32_16x16x32_bf16 v[88:91], v[180:183], v[196:199], v[88:91]
	v_mfma_f32_16x16x32_bf16 v[80:83], v[172:175], v[204:207], v[80:83]
	v_mfma_f32_16x16x32_bf16 v[72:75], v[180:183], v[204:207], v[72:75]
	v_mfma_f32_16x16x32_bf16 v[68:71], v[172:175], v[218:221], v[68:71]
	v_mfma_f32_16x16x32_bf16 v[64:67], v[180:183], v[218:221], v[64:67]
	s_setprio 0
	s_barrier
; #define PG8_STAGE(bufoff, gbase, voff) do { _Pragma("unroll") for (int _i = 0; _i < 2; ++_i) \
;         __builtin_amdgcn_global_load_lds((const unsigned*)((const char*)(gbase) + (voff)[_i]), (PG8_LAS unsigned*)(lds + (bufoff) + ldsw + _i * 8192), 16, 0, 0); } while (0)
; #define PG8_LDA(dst, b, h) do { _Pragma("unroll") for (int m = 0; m < 4; ++m) _Pragma("unroll") for (int k = 0; k < 2; ++k) dst[m][k] = *(const PG8_LAS bf16x8*)(lds + PG8_SA(b, h) + aoff + m * 2048 + k * 1024); } while (0)
; #define PG8_MMA(ai, bj, At, Bt) do { __builtin_amdgcn_s_setprio(1); _Pragma("unroll") for (int m = 0; m < 4; ++m) _Pragma("unroll") for (int n = 0; n < 2; ++n) _Pragma("unroll") for (int k = 0; k < 2; ++k) \
;         acc[ai][bj][m][n] = __builtin_amdgcn_mfma_f32_16x16x32_bf16(Bt[n][k], At[m][k], acc[ai][bj][m][n], 0, 0, 0); __builtin_amdgcn_s_setprio(0); } while (0)
; #define PG8_WAIT_V(n) asm volatile("s_waitcnt vmcnt(" #n ")" ::: "memory")
; #define PG8_WAIT_L(n) asm volatile("s_waitcnt lgkmcnt(" #n ")" ::: "memory")
; #define PG8_BAR __builtin_amdgcn_s_barrier()
; #define PG8_SCHED __builtin_amdgcn_sched_barrier(0)
; template <class Epi, class Sched, bool ALIGN_EPI = false, bool SP2 = false>
; __device__ __forceinline__ void gemm_phase(PG8_LAS unsigned char* lds, const Gemm g, const Sched& S, const Epi& E) {
;     ...
;             PG8_LDA(At, 1, 1); PG8_STAGE(PG8_SB(1, 0), b3, voffB); PG8_STAGE(PG8_SB(1, 1), b3 + hstep, voffB); PG8_STAGE(PG8_SA(1, 0), a3, voffA);
;             PG8_WAIT_V(8); PG8_WAIT_L(0); PG8_BAR; PG8_MMA(1, 0, At, B0); PG8_MMA(1, 1, At, B1); PG8_BAR; PG8_SCHED;
;     ...
;         }
;         if constexpr (ALIGN_EPI) { if (wr == 0) PG8_BAR; }
	s_add_i32 s70, s82, s0
	v_lshl_add_u64 v[144:145], v[144:145], 0, s[12:13]
	s_mov_b32 m0, s70
	ds_read_b128 v[184:187], v151 offset:49152
	ds_read_b128 v[188:191], v151 offset:50176
	ds_read_b128 v[192:195], v151 offset:51200
	ds_read_b128 v[196:199], v151 offset:52224
	ds_read_b128 v[200:203], v151 offset:53248
	ds_read_b128 v[204:207], v151 offset:54272
	ds_read_b128 v[214:217], v151 offset:55296
	ds_read_b128 v[218:221], v151 offset:56320
	global_load_lds_dwordx4 v[144:145], off
	s_add_i32 m0, s70, 0x2000
	s_add_u32 s68, s68, 0x80080
	v_lshl_add_u64 v[144:145], v[222:223], 0, s[12:13]
	s_addc_u32 s69, s69, 0
	s_add_i32 s70, s83, s0
	global_load_lds_dwordx4 v[144:145], off
	v_lshl_add_u64 v[144:145], s[68:69], 0, v[132:133]
	s_mov_b32 m0, s70
	s_nop 0
	global_load_lds_dwordx4 v[144:145], off
	v_lshl_add_u64 v[144:145], s[68:69], 0, v[128:129]
	s_add_i32 m0, s70, 0x2000
	s_nop 0
	global_load_lds_dwordx4 v[144:145], off
	v_lshl_add_u64 v[144:145], v[224:225], 0, s[12:13]
	s_mov_b32 m0, s49
	s_nop 0
	global_load_lds_dwordx4 v[144:145], off
	v_lshl_add_u64 v[144:145], v[226:227], 0, s[12:13]
	s_mov_b32 m0, s50
	s_nop 0
	global_load_lds_dwordx4 v[144:145], off
	s_waitcnt vmcnt(8)
	s_waitcnt lgkmcnt(0)
	s_waitcnt lgkmcnt(0)
	v_mfma_f32_16x16x32_bf16 v[60:63], v[152:155], v[184:187], v[60:63]
	v_mfma_f32_16x16x32_bf16 v[56:59], v[160:163], v[184:187], v[56:59]
	v_mfma_f32_16x16x32_bf16 v[52:55], v[152:155], v[192:195], v[52:55]
	v_mfma_f32_16x16x32_bf16 v[44:47], v[160:163], v[192:195], v[44:47]
	v_mfma_f32_16x16x32_bf16 v[36:39], v[152:155], v[200:203], v[36:39]
	v_mfma_f32_16x16x32_bf16 v[28:31], v[160:163], v[200:203], v[28:31]
	v_mfma_f32_16x16x32_bf16 v[20:23], v[152:155], v[214:217], v[20:23]
	v_mfma_f32_16x16x32_bf16 v[12:15], v[160:163], v[214:217], v[12:15]
	s_barrier
	s_setprio 1
	v_mfma_f32_16x16x32_bf16 v[60:63], v[156:159], v[188:191], v[60:63]
	v_mfma_f32_16x16x32_bf16 v[56:59], v[164:167], v[188:191], v[56:59]
	v_mfma_f32_16x16x32_bf16 v[52:55], v[156:159], v[196:199], v[52:55]
	v_mfma_f32_16x16x32_bf16 v[44:47], v[164:167], v[196:199], v[44:47]
	v_mfma_f32_16x16x32_bf16 v[36:39], v[156:159], v[204:207], v[36:39]
	v_mfma_f32_16x16x32_bf16 v[28:31], v[164:167], v[204:207], v[28:31]
	v_mfma_f32_16x16x32_bf16 v[20:23], v[156:159], v[218:221], v[20:23]
	v_mfma_f32_16x16x32_bf16 v[12:15], v[164:167], v[218:221], v[12:15]
	s_setprio 0
	s_setprio 1
	v_mfma_f32_16x16x32_bf16 v[48:51], v[168:171], v[184:187], v[48:51]
	v_mfma_f32_16x16x32_bf16 v[40:43], v[176:179], v[184:187], v[40:43]
	v_mfma_f32_16x16x32_bf16 v[32:35], v[168:171], v[192:195], v[32:35]
	v_mfma_f32_16x16x32_bf16 v[24:27], v[176:179], v[192:195], v[24:27]
	v_mfma_f32_16x16x32_bf16 v[16:19], v[168:171], v[200:203], v[16:19]
	v_mfma_f32_16x16x32_bf16 v[8:11], v[176:179], v[200:203], v[8:11]
	v_mfma_f32_16x16x32_bf16 v[4:7], v[168:171], v[214:217], v[4:7]
	v_mfma_f32_16x16x32_bf16 v[0:3], v[176:179], v[214:217], v[0:3]
	v_mfma_f32_16x16x32_bf16 v[48:51], v[172:175], v[188:191], v[48:51]
	v_mfma_f32_16x16x32_bf16 v[40:43], v[180:183], v[188:191], v[40:43]
	v_mfma_f32_16x16x32_bf16 v[32:35], v[172:175], v[196:199], v[32:35]
	v_mfma_f32_16x16x32_bf16 v[24:27], v[180:183], v[196:199], v[24:27]
	v_mfma_f32_16x16x32_bf16 v[16:19], v[172:175], v[204:207], v[16:19]
	v_mfma_f32_16x16x32_bf16 v[8:11], v[180:183], v[204:207], v[8:11]
	v_mfma_f32_16x16x32_bf16 v[4:7], v[172:175], v[218:221], v[4:7]
	v_mfma_f32_16x16x32_bf16 v[0:3], v[180:183], v[218:221], v[0:3]
	s_setprio 0
	s_barrier
	s_add_i32 s81, s81, 2
	s_add_u32 s66, s66, 0x100
	s_addc_u32 s67, s67, 0
	s_add_u32 s79, s79, 0x100
	s_addc_u32 s80, s80, 0
	s_cmp_gt_u32 s81, 29
	s_cbranch_scc0 .LBB0_528
	s_and_b64 vcc, exec, s[14:15]
	s_cbranch_vccz .LBB0_531
	s_barrier

; #define PG8_STAGE(bufoff, gbase, voff) do { _Pragma("unroll") for (int _i = 0; _i < 2; ++_i) \
;         __builtin_amdgcn_global_load_lds((const unsigned*)((const char*)(gbase) + (voff)[_i]), (PG8_LAS unsigned*)(lds + (bufoff) + ldsw + _i * 8192), 16, 0, 0); } while (0)
; #define PG8_LDA(dst, b, h) do { _Pragma("unroll") for (int m = 0; m < 4; ++m) _Pragma("unroll") for (int k = 0; k < 2; ++k) dst[m][k] = *(const PG8_LAS bf16x8*)(lds + PG8_SA(b, h) + aoff + m * 2048 + k * 1024); } while (0)
; #define PG8_LDB(dst, b, h) do { _Pragma("unroll") for (int n = 0; n < 2; ++n) _Pragma("unroll") for (int k = 0; k < 2; ++k) dst[n][k] = *(const PG8_LAS bf16x8*)(lds + PG8_SB(b, h) + boff + n * 2048 + k * 1024); } while (0)
; #define PG8_MMA(ai, bj, At, Bt) do { __builtin_amdgcn_s_setprio(1); _Pragma("unroll") for (int m = 0; m < 4; ++m) _Pragma("unroll") for (int n = 0; n < 2; ++n) _Pragma("unroll") for (int k = 0; k < 2; ++k) \
;         acc[ai][bj][m][n] = __builtin_amdgcn_mfma_f32_16x16x32_bf16(Bt[n][k], At[m][k], acc[ai][bj][m][n], 0, 0, 0); __builtin_amdgcn_s_setprio(0); } while (0)
; #define PG8_WAIT_V(n) asm volatile("s_waitcnt vmcnt(" #n ")" ::: "memory")
; #define PG8_WAIT_L(n) asm volatile("s_waitcnt lgkmcnt(" #n ")" ::: "memory")
; #define PG8_BAR __builtin_amdgcn_s_barrier()
; #define PG8_SCHED __builtin_amdgcn_sched_barrier(0)
; template <class Epi, class Sched, bool ALIGN_EPI = false, bool SP2 = false>
; __device__ __forceinline__ void gemm_phase(PG8_LAS unsigned char* lds, const Gemm g, const Sched& S, const Epi& E) {
;     ...
;             PG8_LDB(B0, 0, 0); PG8_LDB(B1, 0, 1); PG8_SCHED; PG8_LDA(At, 0, 0); PG8_STAGE(PG8_SA(1, 1), a1 + hstep, voffA);
;             PG8_WAIT_V(8); PG8_WAIT_L(0); PG8_BAR; PG8_MMA(0, 0, At, B0); PG8_MMA(0, 1, At, B1); PG8_BAR; PG8_SCHED;
;             PG8_LDA(At, 0, 1); PG8_STAGE(PG8_SB(0, 0), b2, voffB); PG8_STAGE(PG8_SB(0, 1), b2 + hstep, voffB); PG8_STAGE(PG8_SA(0, 0), a2, voffA);
;             PG8_WAIT_V(8); PG8_WAIT_L(0); PG8_BAR; PG8_MMA(1, 0, At, B0); PG8_MMA(1, 1, At, B1); PG8_BAR; PG8_SCHED;
.LBB0_656:
	ds_read_b128 v[144:147], v151
	ds_read_b128 v[154:157], v151 offset:1024
	ds_read_b128 v[158:161], v151 offset:2048
	ds_read_b128 v[164:167], v151 offset:3072
	ds_read_b128 v[168:171], v152
	ds_read_b128 v[172:175], v152 offset:1024
	ds_read_b128 v[176:179], v152 offset:2048
	ds_read_b128 v[180:183], v152 offset:3072
	s_add_u32 s38, s34, 0xfff80080
	s_addc_u32 s39, s35, -1
	s_cmp_eq_u32 s71, 28
	s_cselect_b32 s63, s17, s39
	s_cselect_b32 s62, s57, s38
	s_cselect_b32 s39, s15, s70
	s_cselect_b32 s38, s68, s69
	v_lshl_add_u64 v[222:223], s[34:35], 0, v[136:137]
	s_add_i32 m0, s31, 0xc000
	ds_read_b128 v[184:187], v153
	ds_read_b128 v[188:191], v153 offset:1024
	ds_read_b128 v[192:195], v153 offset:2048
	ds_read_b128 v[196:199], v153 offset:3072
	ds_read_b128 v[200:203], v153 offset:4096
	ds_read_b128 v[204:207], v153 offset:5120
	ds_read_b128 v[214:217], v153 offset:6144
	ds_read_b128 v[218:221], v153 offset:7168
	global_load_lds_dwordx4 v[222:223], off
	v_lshl_add_u64 v[222:223], s[34:35], 0, v[138:139]
	s_add_i32 m0, s31, 0xe000
	s_nop 0
	global_load_lds_dwordx4 v[222:223], off
	s_waitcnt vmcnt(8)
	s_waitcnt lgkmcnt(0)
	s_waitcnt lgkmcnt(0)
	v_mfma_f32_16x16x32_bf16 v[124:127], v[144:147], v[184:187], v[124:127]
	v_mfma_f32_16x16x32_bf16 v[116:119], v[158:161], v[184:187], v[116:119]
	v_mfma_f32_16x16x32_bf16 v[108:111], v[144:147], v[192:195], v[108:111]
	v_mfma_f32_16x16x32_bf16 v[100:103], v[158:161], v[192:195], v[100:103]
	v_mfma_f32_16x16x32_bf16 v[92:95], v[144:147], v[200:203], v[92:95]
	v_mfma_f32_16x16x32_bf16 v[84:87], v[158:161], v[200:203], v[84:87]
	v_mfma_f32_16x16x32_bf16 v[76:79], v[144:147], v[214:217], v[76:79]
	v_mfma_f32_16x16x32_bf16 v[68:71], v[158:161], v[214:217], v[68:71]
	s_barrier
	s_setprio 1
	v_mfma_f32_16x16x32_bf16 v[124:127], v[154:157], v[188:191], v[124:127]
	v_mfma_f32_16x16x32_bf16 v[116:119], v[164:167], v[188:191], v[116:119]
	v_mfma_f32_16x16x32_bf16 v[108:111], v[154:157], v[196:199], v[108:111]
	v_mfma_f32_16x16x32_bf16 v[100:103], v[164:167], v[196:199], v[100:103]
	v_mfma_f32_16x16x32_bf16 v[92:95], v[154:157], v[204:207], v[92:95]
	v_mfma_f32_16x16x32_bf16 v[84:87], v[164:167], v[204:207], v[84:87]
	v_mfma_f32_16x16x32_bf16 v[76:79], v[154:157], v[218:221], v[76:79]
	v_mfma_f32_16x16x32_bf16 v[68:71], v[164:167], v[218:221], v[68:71]
	s_setprio 0
	s_setprio 1
	v_mfma_f32_16x16x32_bf16 v[120:123], v[168:171], v[184:187], v[120:123]
	v_mfma_f32_16x16x32_bf16 v[112:115], v[176:179], v[184:187], v[112:115]
	v_mfma_f32_16x16x32_bf16 v[104:107], v[168:171], v[192:195], v[104:107]
	v_mfma_f32_16x16x32_bf16 v[96:99], v[176:179], v[192:195], v[96:99]
	v_mfma_f32_16x16x32_bf16 v[88:91], v[168:171], v[200:203], v[88:91]
	v_mfma_f32_16x16x32_bf16 v[80:83], v[176:179], v[200:203], v[80:83]
	v_mfma_f32_16x16x32_bf16 v[72:75], v[168:171], v[214:217], v[72:75]
	v_mfma_f32_16x16x32_bf16 v[64:67], v[176:179], v[214:217], v[64:67]
	v_mfma_f32_16x16x32_bf16 v[120:123], v[172:175], v[188:191], v[120:123]
	v_mfma_f32_16x16x32_bf16 v[112:115], v[180:183], v[188:191], v[112:115]
	v_mfma_f32_16x16x32_bf16 v[104:107], v[172:175], v[196:199], v[104:107]
	v_mfma_f32_16x16x32_bf16 v[96:99], v[180:183], v[196:199], v[96:99]
	v_mfma_f32_16x16x32_bf16 v[88:91], v[172:175], v[204:207], v[88:91]
	v_mfma_f32_16x16x32_bf16 v[80:83], v[180:183], v[204:207], v[80:83]
	v_mfma_f32_16x16x32_bf16 v[72:75], v[172:175], v[218:221], v[72:75]
	v_mfma_f32_16x16x32_bf16 v[64:67], v[180:183], v[218:221], v[64:67]
	s_setprio 0
	s_barrier
	s_add_i32 s72, s65, s0
	v_lshl_add_u64 v[222:223], s[38:39], 0, v[132:133]
	s_mov_b32 m0, s72
	ds_read_b128 v[184:187], v153 offset:16384
	ds_read_b128 v[188:191], v153 offset:17408
	ds_read_b128 v[192:195], v153 offset:18432
	ds_read_b128 v[196:199], v153 offset:19456
	ds_read_b128 v[200:203], v153 offset:20480
	ds_read_b128 v[204:207], v153 offset:21504
	ds_read_b128 v[214:217], v153 offset:22528
	ds_read_b128 v[218:221], v153 offset:23552
	global_load_lds_dwordx4 v[222:223], off
	s_add_i32 m0, s72, 0x2000
	s_add_u32 s72, s38, 0x80000
	v_lshl_add_u64 v[224:225], s[38:39], 0, v[128:129]
	s_addc_u32 s73, s39, 0
	s_add_i32 s74, s66, s0
	global_load_lds_dwordx4 v[224:225], off
	v_lshl_add_u64 v[226:227], s[72:73], 0, v[132:133]
	s_mov_b32 m0, s74
	v_lshl_add_u64 v[228:229], s[62:63], 0, v[130:131]
	global_load_lds_dwordx4 v[226:227], off
	v_lshl_add_u64 v[226:227], s[72:73], 0, v[128:129]
	s_add_i32 m0, s74, 0x2000
	s_nop 0
	global_load_lds_dwordx4 v[226:227], off
	v_lshl_add_u64 v[226:227], s[62:63], 0, v[134:135]
	s_mov_b32 m0, s31
	s_nop 0
	global_load_lds_dwordx4 v[226:227], off
	s_mov_b32 m0, s43
	s_nop 0
	global_load_lds_dwordx4 v[228:229], off
	s_waitcnt vmcnt(8)
	s_waitcnt lgkmcnt(0)
	s_waitcnt lgkmcnt(0)
	v_mfma_f32_16x16x32_bf16 v[60:63], v[144:147], v[184:187], v[60:63]
	v_mfma_f32_16x16x32_bf16 v[52:55], v[158:161], v[184:187], v[52:55]
	v_mfma_f32_16x16x32_bf16 v[44:47], v[144:147], v[192:195], v[44:47]
	v_mfma_f32_16x16x32_bf16 v[36:39], v[158:161], v[192:195], v[36:39]
	v_mfma_f32_16x16x32_bf16 v[28:31], v[144:147], v[200:203], v[28:31]
	v_mfma_f32_16x16x32_bf16 v[20:23], v[158:161], v[200:203], v[20:23]
	v_mfma_f32_16x16x32_bf16 v[12:15], v[144:147], v[214:217], v[12:15]
	v_mfma_f32_16x16x32_bf16 v[4:7], v[158:161], v[214:217], v[4:7]
	s_barrier
; #define PG8_STAGE(bufoff, gbase, voff) do { _Pragma("unroll") for (int _i = 0; _i < 2; ++_i) \
;         __builtin_amdgcn_global_load_lds((const unsigned*)((const char*)(gbase) + (voff)[_i]), (PG8_LAS unsigned*)(lds + (bufoff) + ldsw + _i * 8192), 16, 0, 0); } while (0)
; #define PG8_LDA(dst, b, h) do { _Pragma("unroll") for (int m = 0; m < 4; ++m) _Pragma("unroll") for (int k = 0; k < 2; ++k) dst[m][k] = *(const PG8_LAS bf16x8*)(lds + PG8_SA(b, h) + aoff + m * 2048 + k * 1024); } while (0)
; #define PG8_LDB(dst, b, h) do { _Pragma("unroll") for (int n = 0; n < 2; ++n) _Pragma("unroll") for (int k = 0; k < 2; ++k) dst[n][k] = *(const PG8_LAS bf16x8*)(lds + PG8_SB(b, h) + boff + n * 2048 + k * 1024); } while (0)
; #define PG8_MMA(ai, bj, At, Bt) do { __builtin_amdgcn_s_setprio(1); _Pragma("unroll") for (int m = 0; m < 4; ++m) _Pragma("unroll") for (int n = 0; n < 2; ++n) _Pragma("unroll") for (int k = 0; k < 2; ++k) \
;         acc[ai][bj][m][n] = __builtin_amdgcn_mfma_f32_16x16x32_bf16(Bt[n][k], At[m][k], acc[ai][bj][m][n], 0, 0, 0); __builtin_amdgcn_s_setprio(0); } while (0)
; #define PG8_WAIT_V(n) asm volatile("s_waitcnt vmcnt(" #n ")" ::: "memory")
; #define PG8_WAIT_L(n) asm volatile("s_waitcnt lgkmcnt(" #n ")" ::: "memory")
; #define PG8_BAR __builtin_amdgcn_s_barrier()
; #define PG8_SCHED __builtin_amdgcn_sched_barrier(0)
; template <class Epi, class Sched, bool ALIGN_EPI = false, bool SP2 = false>
; __device__ __forceinline__ void gemm_phase(PG8_LAS unsigned char* lds, const Gemm g, const Sched& S, const Epi& E) {
;     ...
;             PG8_WAIT_V(8); PG8_WAIT_L(0); PG8_BAR; PG8_MMA(1, 0, At, B0); PG8_MMA(1, 1, At, B1); PG8_BAR; PG8_SCHED;
;             PG8_LDB(B0, 1, 0); PG8_LDB(B1, 1, 1); PG8_SCHED; PG8_LDA(At, 1, 0); PG8_STAGE(PG8_SA(0, 1), a2 + hstep, voffA);
;             PG8_WAIT_V(8); PG8_WAIT_L(0); PG8_BAR; PG8_MMA(0, 0, At, B0); PG8_MMA(0, 1, At, B1); PG8_BAR; PG8_SCHED;
	s_setprio 1
	v_mfma_f32_16x16x32_bf16 v[60:63], v[154:157], v[188:191], v[60:63]
	v_mfma_f32_16x16x32_bf16 v[52:55], v[164:167], v[188:191], v[52:55]
	v_mfma_f32_16x16x32_bf16 v[44:47], v[154:157], v[196:199], v[44:47]
	v_mfma_f32_16x16x32_bf16 v[36:39], v[164:167], v[196:199], v[36:39]
	v_mfma_f32_16x16x32_bf16 v[28:31], v[154:157], v[204:207], v[28:31]
	v_mfma_f32_16x16x32_bf16 v[20:23], v[164:167], v[204:207], v[20:23]
	v_mfma_f32_16x16x32_bf16 v[12:15], v[154:157], v[218:221], v[12:15]
	v_mfma_f32_16x16x32_bf16 v[4:7], v[164:167], v[218:221], v[4:7]
	s_setprio 0
	s_setprio 1
	v_mfma_f32_16x16x32_bf16 v[56:59], v[168:171], v[184:187], v[56:59]
	v_mfma_f32_16x16x32_bf16 v[48:51], v[176:179], v[184:187], v[48:51]
	v_mfma_f32_16x16x32_bf16 v[40:43], v[168:171], v[192:195], v[40:43]
	v_mfma_f32_16x16x32_bf16 v[32:35], v[176:179], v[192:195], v[32:35]
	v_mfma_f32_16x16x32_bf16 v[24:27], v[168:171], v[200:203], v[24:27]
	v_mfma_f32_16x16x32_bf16 v[16:19], v[176:179], v[200:203], v[16:19]
	v_mfma_f32_16x16x32_bf16 v[8:11], v[168:171], v[214:217], v[8:11]
	v_mfma_f32_16x16x32_bf16 v[0:3], v[176:179], v[214:217], v[0:3]
	v_mfma_f32_16x16x32_bf16 v[56:59], v[172:175], v[188:191], v[56:59]
	v_mfma_f32_16x16x32_bf16 v[48:51], v[180:183], v[188:191], v[48:51]
	v_mfma_f32_16x16x32_bf16 v[40:43], v[172:175], v[196:199], v[40:43]
	v_mfma_f32_16x16x32_bf16 v[32:35], v[180:183], v[196:199], v[32:35]
	v_mfma_f32_16x16x32_bf16 v[24:27], v[172:175], v[204:207], v[24:27]
	v_mfma_f32_16x16x32_bf16 v[16:19], v[180:183], v[204:207], v[16:19]
	v_mfma_f32_16x16x32_bf16 v[8:11], v[172:175], v[218:221], v[8:11]
	v_mfma_f32_16x16x32_bf16 v[0:3], v[180:183], v[218:221], v[0:3]
	s_setprio 0
	s_barrier
	s_add_i32 s72, 0, 0x18000
	v_add_u32_e32 v163, s72, v149
	s_add_i32 s73, 0, 0x1c000
	ds_read_b128 v[144:147], v163
	ds_read_b128 v[154:157], v163 offset:1024
	ds_read_b128 v[158:161], v163 offset:2048
	ds_read_b128 v[164:167], v163 offset:3072
	v_add_u32_e32 v163, s73, v149
	ds_read_b128 v[168:171], v163
	ds_read_b128 v[172:175], v163 offset:1024
	ds_read_b128 v[176:179], v163 offset:2048
	ds_read_b128 v[180:183], v163 offset:3072
	s_add_u32 s62, s62, 0x80000
	s_addc_u32 s63, s63, 0
	s_mov_b32 m0, s46
	v_lshl_add_u64 v[230:231], s[62:63], 0, v[134:135]
	ds_read_b128 v[184:187], v153 offset:32768
	ds_read_b128 v[188:191], v153 offset:33792
	ds_read_b128 v[192:195], v153 offset:34816
	ds_read_b128 v[196:199], v153 offset:35840
	ds_read_b128 v[200:203], v153 offset:36864
	ds_read_b128 v[204:207], v153 offset:37888
	ds_read_b128 v[214:217], v153 offset:38912
	ds_read_b128 v[218:221], v153 offset:39936
	global_load_lds_dwordx4 v[230:231], off
	v_lshl_add_u64 v[230:231], s[62:63], 0, v[130:131]
	s_mov_b32 m0, s47
	s_nop 0
	global_load_lds_dwordx4 v[230:231], off
	s_waitcnt vmcnt(8)
	s_waitcnt lgkmcnt(0)
	s_waitcnt lgkmcnt(0)
	v_mfma_f32_16x16x32_bf16 v[124:127], v[144:147], v[184:187], v[124:127]
	v_mfma_f32_16x16x32_bf16 v[116:119], v[158:161], v[184:187], v[116:119]
	v_mfma_f32_16x16x32_bf16 v[108:111], v[144:147], v[192:195], v[108:111]
	v_mfma_f32_16x16x32_bf16 v[100:103], v[158:161], v[192:195], v[100:103]
	v_mfma_f32_16x16x32_bf16 v[92:95], v[144:147], v[200:203], v[92:95]
	v_mfma_f32_16x16x32_bf16 v[84:87], v[158:161], v[200:203], v[84:87]
	v_mfma_f32_16x16x32_bf16 v[76:79], v[144:147], v[214:217], v[76:79]
	v_mfma_f32_16x16x32_bf16 v[68:71], v[158:161], v[214:217], v[68:71]
	s_barrier
	s_setprio 1
	v_mfma_f32_16x16x32_bf16 v[124:127], v[154:157], v[188:191], v[124:127]
	v_mfma_f32_16x16x32_bf16 v[116:119], v[164:167], v[188:191], v[116:119]
	v_mfma_f32_16x16x32_bf16 v[108:111], v[154:157], v[196:199], v[108:111]
	v_mfma_f32_16x16x32_bf16 v[100:103], v[164:167], v[196:199], v[100:103]
	v_mfma_f32_16x16x32_bf16 v[92:95], v[154:157], v[204:207], v[92:95]
	v_mfma_f32_16x16x32_bf16 v[84:87], v[164:167], v[204:207], v[84:87]
	v_mfma_f32_16x16x32_bf16 v[76:79], v[154:157], v[218:221], v[76:79]
	v_mfma_f32_16x16x32_bf16 v[68:71], v[164:167], v[218:221], v[68:71]
	s_setprio 0
	s_setprio 1
	v_mfma_f32_16x16x32_bf16 v[120:123], v[168:171], v[184:187], v[120:123]
	v_mfma_f32_16x16x32_bf16 v[112:115], v[176:179], v[184:187], v[112:115]
	v_mfma_f32_16x16x32_bf16 v[104:107], v[168:171], v[192:195], v[104:107]
	v_mfma_f32_16x16x32_bf16 v[96:99], v[176:179], v[192:195], v[96:99]
	v_mfma_f32_16x16x32_bf16 v[88:91], v[168:171], v[200:203], v[88:91]
	v_mfma_f32_16x16x32_bf16 v[80:83], v[176:179], v[200:203], v[80:83]
	v_mfma_f32_16x16x32_bf16 v[72:75], v[168:171], v[214:217], v[72:75]
	v_mfma_f32_16x16x32_bf16 v[64:67], v[176:179], v[214:217], v[64:67]
	v_mfma_f32_16x16x32_bf16 v[120:123], v[172:175], v[188:191], v[120:123]
	v_mfma_f32_16x16x32_bf16 v[112:115], v[180:183], v[188:191], v[112:115]
	v_mfma_f32_16x16x32_bf16 v[104:107], v[172:175], v[196:199], v[104:107]
	v_mfma_f32_16x16x32_bf16 v[96:99], v[180:183], v[196:199], v[96:99]
	v_mfma_f32_16x16x32_bf16 v[88:91], v[172:175], v[204:207], v[88:91]
	v_mfma_f32_16x16x32_bf16 v[80:83], v[180:183], v[204:207], v[80:83]
	v_mfma_f32_16x16x32_bf16 v[72:75], v[172:175], v[218:221], v[72:75]
	v_mfma_f32_16x16x32_bf16 v[64:67], v[180:183], v[218:221], v[64:67]
	s_setprio 0
	s_barrier
; #define PG8_STAGE(bufoff, gbase, voff) do { _Pragma("unroll") for (int _i = 0; _i < 2; ++_i) \
;         __builtin_amdgcn_global_load_lds((const unsigned*)((const char*)(gbase) + (voff)[_i]), (PG8_LAS unsigned*)(lds + (bufoff) + ldsw + _i * 8192), 16, 0, 0); } while (0)
; #define PG8_LDA(dst, b, h) do { _Pragma("unroll") for (int m = 0; m < 4; ++m) _Pragma("unroll") for (int k = 0; k < 2; ++k) dst[m][k] = *(const PG8_LAS bf16x8*)(lds + PG8_SA(b, h) + aoff + m * 2048 + k * 1024); } while (0)
; #define PG8_MMA(ai, bj, At, Bt) do { __builtin_amdgcn_s_setprio(1); _Pragma("unroll") for (int m = 0; m < 4; ++m) _Pragma("unroll") for (int n = 0; n < 2; ++n) _Pragma("unroll") for (int k = 0; k < 2; ++k) \
;         acc[ai][bj][m][n] = __builtin_amdgcn_mfma_f32_16x16x32_bf16(Bt[n][k], At[m][k], acc[ai][bj][m][n], 0, 0, 0); __builtin_amdgcn_s_setprio(0); } while (0)
; #define PG8_WAIT_V(n) asm volatile("s_waitcnt vmcnt(" #n ")" ::: "memory")
; #define PG8_WAIT_L(n) asm volatile("s_waitcnt lgkmcnt(" #n ")" ::: "memory")
; #define PG8_BAR __builtin_amdgcn_s_barrier()
; #define PG8_SCHED __builtin_amdgcn_sched_barrier(0)
; template <class Epi, class Sched, bool ALIGN_EPI = false, bool SP2 = false>
; __device__ __forceinline__ void gemm_phase(PG8_LAS unsigned char* lds, const Gemm g, const Sched& S, const Epi& E) {
;     ...
;             PG8_LDA(At, 1, 1); PG8_STAGE(PG8_SB(1, 0), b3, voffB); PG8_STAGE(PG8_SB(1, 1), b3 + hstep, voffB); PG8_STAGE(PG8_SA(1, 0), a3, voffA);
;             PG8_WAIT_V(8); PG8_WAIT_L(0); PG8_BAR; PG8_MMA(1, 0, At, B0); PG8_MMA(1, 1, At, B1); PG8_BAR; PG8_SCHED;
;     ...
;         }
;         if constexpr (ALIGN_EPI) { if (wr == 0) PG8_BAR; }
	s_add_i32 s62, s72, s0
	v_lshl_add_u64 v[222:223], v[222:223], 0, s[10:11]
	s_mov_b32 m0, s62
	ds_read_b128 v[184:187], v153 offset:49152
	ds_read_b128 v[188:191], v153 offset:50176
	ds_read_b128 v[192:195], v153 offset:51200
	ds_read_b128 v[196:199], v153 offset:52224
	ds_read_b128 v[200:203], v153 offset:53248
	ds_read_b128 v[204:207], v153 offset:54272
	ds_read_b128 v[214:217], v153 offset:55296
	ds_read_b128 v[218:221], v153 offset:56320
	global_load_lds_dwordx4 v[222:223], off
	s_add_i32 m0, s62, 0x2000
	s_add_u32 s38, s38, 0x80080
	v_lshl_add_u64 v[222:223], v[224:225], 0, s[10:11]
	s_addc_u32 s39, s39, 0
	s_add_i32 s62, s73, s0
	global_load_lds_dwordx4 v[222:223], off
	v_lshl_add_u64 v[222:223], s[38:39], 0, v[132:133]
	s_mov_b32 m0, s62
	s_nop 0
	global_load_lds_dwordx4 v[222:223], off
	v_lshl_add_u64 v[222:223], s[38:39], 0, v[128:129]
	s_add_i32 m0, s62, 0x2000
	s_nop 0
	global_load_lds_dwordx4 v[222:223], off
	v_lshl_add_u64 v[222:223], v[226:227], 0, s[10:11]
	s_mov_b32 m0, s49
	s_nop 0
	global_load_lds_dwordx4 v[222:223], off
	v_lshl_add_u64 v[222:223], v[228:229], 0, s[10:11]
	s_mov_b32 m0, s50
	s_nop 0
	global_load_lds_dwordx4 v[222:223], off
	s_waitcnt vmcnt(8)
	s_waitcnt lgkmcnt(0)
	s_waitcnt lgkmcnt(0)
	v_mfma_f32_16x16x32_bf16 v[60:63], v[144:147], v[184:187], v[60:63]
	v_mfma_f32_16x16x32_bf16 v[52:55], v[158:161], v[184:187], v[52:55]
	v_mfma_f32_16x16x32_bf16 v[44:47], v[144:147], v[192:195], v[44:47]
	v_mfma_f32_16x16x32_bf16 v[36:39], v[158:161], v[192:195], v[36:39]
	v_mfma_f32_16x16x32_bf16 v[28:31], v[144:147], v[200:203], v[28:31]
	v_mfma_f32_16x16x32_bf16 v[20:23], v[158:161], v[200:203], v[20:23]
	v_mfma_f32_16x16x32_bf16 v[12:15], v[144:147], v[214:217], v[12:15]
	v_mfma_f32_16x16x32_bf16 v[4:7], v[158:161], v[214:217], v[4:7]
	s_barrier
	s_setprio 1
	v_mfma_f32_16x16x32_bf16 v[60:63], v[154:157], v[188:191], v[60:63]
	v_mfma_f32_16x16x32_bf16 v[52:55], v[164:167], v[188:191], v[52:55]
	v_mfma_f32_16x16x32_bf16 v[44:47], v[154:157], v[196:199], v[44:47]
	v_mfma_f32_16x16x32_bf16 v[36:39], v[164:167], v[196:199], v[36:39]
	v_mfma_f32_16x16x32_bf16 v[28:31], v[154:157], v[204:207], v[28:31]
	v_mfma_f32_16x16x32_bf16 v[20:23], v[164:167], v[204:207], v[20:23]
	v_mfma_f32_16x16x32_bf16 v[12:15], v[154:157], v[218:221], v[12:15]
	v_mfma_f32_16x16x32_bf16 v[4:7], v[164:167], v[218:221], v[4:7]
	s_setprio 0
	s_setprio 1
	v_mfma_f32_16x16x32_bf16 v[56:59], v[168:171], v[184:187], v[56:59]
	v_mfma_f32_16x16x32_bf16 v[48:51], v[176:179], v[184:187], v[48:51]
	v_mfma_f32_16x16x32_bf16 v[40:43], v[168:171], v[192:195], v[40:43]
	v_mfma_f32_16x16x32_bf16 v[32:35], v[176:179], v[192:195], v[32:35]
	v_mfma_f32_16x16x32_bf16 v[24:27], v[168:171], v[200:203], v[24:27]
	v_mfma_f32_16x16x32_bf16 v[16:19], v[176:179], v[200:203], v[16:19]
	v_mfma_f32_16x16x32_bf16 v[8:11], v[168:171], v[214:217], v[8:11]
	v_mfma_f32_16x16x32_bf16 v[0:3], v[176:179], v[214:217], v[0:3]
	v_mfma_f32_16x16x32_bf16 v[56:59], v[172:175], v[188:191], v[56:59]
	v_mfma_f32_16x16x32_bf16 v[48:51], v[180:183], v[188:191], v[48:51]
	v_mfma_f32_16x16x32_bf16 v[40:43], v[172:175], v[196:199], v[40:43]
	v_mfma_f32_16x16x32_bf16 v[32:35], v[180:183], v[196:199], v[32:35]
	v_mfma_f32_16x16x32_bf16 v[24:27], v[172:175], v[204:207], v[24:27]
	v_mfma_f32_16x16x32_bf16 v[16:19], v[180:183], v[204:207], v[16:19]
	v_mfma_f32_16x16x32_bf16 v[8:11], v[172:175], v[218:221], v[8:11]
	v_mfma_f32_16x16x32_bf16 v[0:3], v[180:183], v[218:221], v[0:3]
	s_setprio 0
	s_barrier
	s_add_i32 s71, s71, 2
	s_add_u32 s34, s34, 0x100
	s_addc_u32 s35, s35, 0
	s_add_u32 s69, s69, 0x100
	s_addc_u32 s70, s70, 0
	s_cmp_gt_u32 s71, 29
	s_cbranch_scc0 .LBB0_656
	s_and_b64 vcc, exec, s[12:13]
	s_cbranch_vccz .LBB0_659
	s_barrier

; #define PG8_STAGE(bufoff, gbase, voff) do { _Pragma("unroll") for (int _i = 0; _i < 2; ++_i) \
;         __builtin_amdgcn_global_load_lds((const unsigned*)((const char*)(gbase) + (voff)[_i]), (PG8_LAS unsigned*)(lds + (bufoff) + ldsw + _i * 8192), 16, 0, 0); } while (0)
; #define PG8_LDA(dst, b, h) do { _Pragma("unroll") for (int m = 0; m < 4; ++m) _Pragma("unroll") for (int k = 0; k < 2; ++k) dst[m][k] = *(const PG8_LAS bf16x8*)(lds + PG8_SA(b, h) + aoff + m * 2048 + k * 1024); } while (0)
; #define PG8_LDB(dst, b, h) do { _Pragma("unroll") for (int n = 0; n < 2; ++n) _Pragma("unroll") for (int k = 0; k < 2; ++k) dst[n][k] = *(const PG8_LAS bf16x8*)(lds + PG8_SB(b, h) + boff + n * 2048 + k * 1024); } while (0)
; #define PG8_MMA(ai, bj, At, Bt) do { __builtin_amdgcn_s_setprio(1); _Pragma("unroll") for (int m = 0; m < 4; ++m) _Pragma("unroll") for (int n = 0; n < 2; ++n) _Pragma("unroll") for (int k = 0; k < 2; ++k) \
;         acc[ai][bj][m][n] = __builtin_amdgcn_mfma_f32_16x16x32_bf16(Bt[n][k], At[m][k], acc[ai][bj][m][n], 0, 0, 0); __builtin_amdgcn_s_setprio(0); } while (0)
; #define PG8_WAIT_V(n) asm volatile("s_waitcnt vmcnt(" #n ")" ::: "memory")
; #define PG8_WAIT_L(n) asm volatile("s_waitcnt lgkmcnt(" #n ")" ::: "memory")
; #define PG8_BAR __builtin_amdgcn_s_barrier()
; #define PG8_SCHED __builtin_amdgcn_sched_barrier(0)
; template <class Epi, class Sched, bool ALIGN_EPI = false, bool SP2 = false>
; __device__ __forceinline__ void gemm_phase(PG8_LAS unsigned char* lds, const Gemm g, const Sched& S, const Epi& E) {
;     ...
;             PG8_LDB(B0, 0, 0); PG8_LDB(B1, 0, 1); PG8_SCHED; PG8_LDA(At, 0, 0); PG8_STAGE(PG8_SA(1, 1), a1 + hstep, voffA);
;             PG8_WAIT_V(8); PG8_WAIT_L(0); PG8_BAR; PG8_MMA(0, 0, At, B0); PG8_MMA(0, 1, At, B1); PG8_BAR; PG8_SCHED;
;             PG8_LDA(At, 0, 1); PG8_STAGE(PG8_SB(0, 0), b2, voffB); PG8_STAGE(PG8_SB(0, 1), b2 + hstep, voffB); PG8_STAGE(PG8_SA(0, 0), a2, voffA);
;             PG8_WAIT_V(8); PG8_WAIT_L(0); PG8_BAR; PG8_MMA(1, 0, At, B0); PG8_MMA(1, 1, At, B1); PG8_BAR; PG8_SCHED;
.LBB0_731:
	ds_read_b128 v[152:155], v149
	ds_read_b128 v[156:159], v149 offset:1024
	ds_read_b128 v[164:167], v149 offset:2048
	ds_read_b128 v[168:171], v149 offset:3072
	ds_read_b128 v[172:175], v150
	ds_read_b128 v[176:179], v150 offset:1024
	ds_read_b128 v[180:183], v150 offset:2048
	ds_read_b128 v[184:187], v150 offset:3072
	s_add_u32 s62, s38, 0xffea0080
	s_addc_u32 s63, s39, -1
	s_cmpk_eq_i32 s77, 0x54
	s_cselect_b32 s65, s7, s63
	s_cselect_b32 s64, s6, s62
	s_cselect_b32 s63, s35, s76
	s_cselect_b32 s62, s34, s75
	v_lshl_add_u64 v[144:145], s[38:39], 0, v[136:137]
	s_add_i32 m0, s41, 0xc000
	ds_read_b128 v[188:191], v151
	ds_read_b128 v[192:195], v151 offset:1024
	ds_read_b128 v[196:199], v151 offset:2048
	ds_read_b128 v[200:203], v151 offset:3072
	ds_read_b128 v[204:207], v151 offset:4096
	ds_read_b128 v[214:217], v151 offset:5120
	ds_read_b128 v[218:221], v151 offset:6144
	ds_read_b128 v[222:225], v151 offset:7168
	global_load_lds_dwordx4 v[144:145], off
	v_lshl_add_u64 v[144:145], s[38:39], 0, v[138:139]
	s_add_i32 m0, s41, 0xe000
	s_nop 0
	global_load_lds_dwordx4 v[144:145], off
	s_waitcnt vmcnt(8)
	s_waitcnt lgkmcnt(0)
	s_waitcnt lgkmcnt(0)
	v_mfma_f32_16x16x32_bf16 v[124:127], v[152:155], v[188:191], v[124:127]
	v_mfma_f32_16x16x32_bf16 v[120:123], v[164:167], v[188:191], v[120:123]
	v_mfma_f32_16x16x32_bf16 v[116:119], v[152:155], v[196:199], v[116:119]
	v_mfma_f32_16x16x32_bf16 v[108:111], v[164:167], v[196:199], v[108:111]
	v_mfma_f32_16x16x32_bf16 v[100:103], v[152:155], v[204:207], v[100:103]
	v_mfma_f32_16x16x32_bf16 v[92:95], v[164:167], v[204:207], v[92:95]
	v_mfma_f32_16x16x32_bf16 v[84:87], v[152:155], v[218:221], v[84:87]
	v_mfma_f32_16x16x32_bf16 v[76:79], v[164:167], v[218:221], v[76:79]
	s_barrier
	s_setprio 1
	v_mfma_f32_16x16x32_bf16 v[124:127], v[156:159], v[192:195], v[124:127]
	v_mfma_f32_16x16x32_bf16 v[120:123], v[168:171], v[192:195], v[120:123]
	v_mfma_f32_16x16x32_bf16 v[116:119], v[156:159], v[200:203], v[116:119]
	v_mfma_f32_16x16x32_bf16 v[108:111], v[168:171], v[200:203], v[108:111]
	v_mfma_f32_16x16x32_bf16 v[100:103], v[156:159], v[214:217], v[100:103]
	v_mfma_f32_16x16x32_bf16 v[92:95], v[168:171], v[214:217], v[92:95]
	v_mfma_f32_16x16x32_bf16 v[84:87], v[156:159], v[222:225], v[84:87]
	v_mfma_f32_16x16x32_bf16 v[76:79], v[168:171], v[222:225], v[76:79]
	s_setprio 0
	s_setprio 1
	v_mfma_f32_16x16x32_bf16 v[112:115], v[172:175], v[188:191], v[112:115]
	v_mfma_f32_16x16x32_bf16 v[104:107], v[180:183], v[188:191], v[104:107]
	v_mfma_f32_16x16x32_bf16 v[96:99], v[172:175], v[196:199], v[96:99]
	v_mfma_f32_16x16x32_bf16 v[88:91], v[180:183], v[196:199], v[88:91]
	v_mfma_f32_16x16x32_bf16 v[80:83], v[172:175], v[204:207], v[80:83]
	v_mfma_f32_16x16x32_bf16 v[72:75], v[180:183], v[204:207], v[72:75]
	v_mfma_f32_16x16x32_bf16 v[68:71], v[172:175], v[218:221], v[68:71]
	v_mfma_f32_16x16x32_bf16 v[64:67], v[180:183], v[218:221], v[64:67]
	v_mfma_f32_16x16x32_bf16 v[112:115], v[176:179], v[192:195], v[112:115]
	v_mfma_f32_16x16x32_bf16 v[104:107], v[184:187], v[192:195], v[104:107]
	v_mfma_f32_16x16x32_bf16 v[96:99], v[176:179], v[200:203], v[96:99]
	v_mfma_f32_16x16x32_bf16 v[88:91], v[184:187], v[200:203], v[88:91]
	v_mfma_f32_16x16x32_bf16 v[80:83], v[176:179], v[214:217], v[80:83]
	v_mfma_f32_16x16x32_bf16 v[72:75], v[184:187], v[214:217], v[72:75]
	v_mfma_f32_16x16x32_bf16 v[68:71], v[176:179], v[222:225], v[68:71]
	v_mfma_f32_16x16x32_bf16 v[64:67], v[184:187], v[222:225], v[64:67]
	s_setprio 0
	s_barrier
	s_add_i32 s78, s57, s0
	v_lshl_add_u64 v[144:145], s[62:63], 0, v[132:133]
	s_mov_b32 m0, s78
	ds_read_b128 v[188:191], v151 offset:16384
	ds_read_b128 v[192:195], v151 offset:17408
	ds_read_b128 v[196:199], v151 offset:18432
	ds_read_b128 v[200:203], v151 offset:19456
	ds_read_b128 v[204:207], v151 offset:20480
	ds_read_b128 v[214:217], v151 offset:21504
	ds_read_b128 v[218:221], v151 offset:22528
	ds_read_b128 v[222:225], v151 offset:23552
	global_load_lds_dwordx4 v[144:145], off
	s_add_i32 m0, s78, 0x2000
	s_add_u32 s78, s62, 0x160000
	v_lshl_add_u64 v[160:161], s[62:63], 0, v[128:129]
	s_addc_u32 s79, s63, 0
	s_add_i32 s80, s66, s0
	global_load_lds_dwordx4 v[160:161], off
	v_lshl_add_u64 v[226:227], s[78:79], 0, v[132:133]
	s_mov_b32 m0, s80
	v_lshl_add_u64 v[228:229], s[64:65], 0, v[130:131]
	global_load_lds_dwordx4 v[226:227], off
	v_lshl_add_u64 v[226:227], s[78:79], 0, v[128:129]
	s_add_i32 m0, s80, 0x2000
	s_nop 0
	global_load_lds_dwordx4 v[226:227], off
	v_lshl_add_u64 v[226:227], s[64:65], 0, v[134:135]
	s_mov_b32 m0, s41
	s_nop 0
	global_load_lds_dwordx4 v[226:227], off
	s_mov_b32 m0, s43
	s_nop 0
	global_load_lds_dwordx4 v[228:229], off
	s_waitcnt vmcnt(8)
	s_waitcnt lgkmcnt(0)
	s_waitcnt lgkmcnt(0)
	v_mfma_f32_16x16x32_bf16 v[60:63], v[152:155], v[188:191], v[60:63]
	v_mfma_f32_16x16x32_bf16 v[56:59], v[164:167], v[188:191], v[56:59]
	v_mfma_f32_16x16x32_bf16 v[52:55], v[152:155], v[196:199], v[52:55]
	v_mfma_f32_16x16x32_bf16 v[44:47], v[164:167], v[196:199], v[44:47]
	v_mfma_f32_16x16x32_bf16 v[36:39], v[152:155], v[204:207], v[36:39]
	v_mfma_f32_16x16x32_bf16 v[28:31], v[164:167], v[204:207], v[28:31]
	v_mfma_f32_16x16x32_bf16 v[20:23], v[152:155], v[218:221], v[20:23]
	v_mfma_f32_16x16x32_bf16 v[12:15], v[164:167], v[218:221], v[12:15]
	s_barrier
; #define PG8_STAGE(bufoff, gbase, voff) do { _Pragma("unroll") for (int _i = 0; _i < 2; ++_i) \
;         __builtin_amdgcn_global_load_lds((const unsigned*)((const char*)(gbase) + (voff)[_i]), (PG8_LAS unsigned*)(lds + (bufoff) + ldsw + _i * 8192), 16, 0, 0); } while (0)
; #define PG8_LDA(dst, b, h) do { _Pragma("unroll") for (int m = 0; m < 4; ++m) _Pragma("unroll") for (int k = 0; k < 2; ++k) dst[m][k] = *(const PG8_LAS bf16x8*)(lds + PG8_SA(b, h) + aoff + m * 2048 + k * 1024); } while (0)
; #define PG8_LDB(dst, b, h) do { _Pragma("unroll") for (int n = 0; n < 2; ++n) _Pragma("unroll") for (int k = 0; k < 2; ++k) dst[n][k] = *(const PG8_LAS bf16x8*)(lds + PG8_SB(b, h) + boff + n * 2048 + k * 1024); } while (0)
; #define PG8_MMA(ai, bj, At, Bt) do { __builtin_amdgcn_s_setprio(1); _Pragma("unroll") for (int m = 0; m < 4; ++m) _Pragma("unroll") for (int n = 0; n < 2; ++n) _Pragma("unroll") for (int k = 0; k < 2; ++k) \
;         acc[ai][bj][m][n] = __builtin_amdgcn_mfma_f32_16x16x32_bf16(Bt[n][k], At[m][k], acc[ai][bj][m][n], 0, 0, 0); __builtin_amdgcn_s_setprio(0); } while (0)
; #define PG8_WAIT_V(n) asm volatile("s_waitcnt vmcnt(" #n ")" ::: "memory")
; #define PG8_WAIT_L(n) asm volatile("s_waitcnt lgkmcnt(" #n ")" ::: "memory")
; #define PG8_BAR __builtin_amdgcn_s_barrier()
; #define PG8_SCHED __builtin_amdgcn_sched_barrier(0)
; template <class Epi, class Sched, bool ALIGN_EPI = false, bool SP2 = false>
; __device__ __forceinline__ void gemm_phase(PG8_LAS unsigned char* lds, const Gemm g, const Sched& S, const Epi& E) {
;     ...
;             PG8_WAIT_V(8); PG8_WAIT_L(0); PG8_BAR; PG8_MMA(1, 0, At, B0); PG8_MMA(1, 1, At, B1); PG8_BAR; PG8_SCHED;
;             PG8_LDB(B0, 1, 0); PG8_LDB(B1, 1, 1); PG8_SCHED; PG8_LDA(At, 1, 0); PG8_STAGE(PG8_SA(0, 1), a2 + hstep, voffA);
;             PG8_WAIT_V(8); PG8_WAIT_L(0); PG8_BAR; PG8_MMA(0, 0, At, B0); PG8_MMA(0, 1, At, B1); PG8_BAR; PG8_SCHED;
	s_setprio 1
	v_mfma_f32_16x16x32_bf16 v[60:63], v[156:159], v[192:195], v[60:63]
	v_mfma_f32_16x16x32_bf16 v[56:59], v[168:171], v[192:195], v[56:59]
	v_mfma_f32_16x16x32_bf16 v[52:55], v[156:159], v[200:203], v[52:55]
	v_mfma_f32_16x16x32_bf16 v[44:47], v[168:171], v[200:203], v[44:47]
	v_mfma_f32_16x16x32_bf16 v[36:39], v[156:159], v[214:217], v[36:39]
	v_mfma_f32_16x16x32_bf16 v[28:31], v[168:171], v[214:217], v[28:31]
	v_mfma_f32_16x16x32_bf16 v[20:23], v[156:159], v[222:225], v[20:23]
	v_mfma_f32_16x16x32_bf16 v[12:15], v[168:171], v[222:225], v[12:15]
	s_setprio 0
	s_setprio 1
	v_mfma_f32_16x16x32_bf16 v[48:51], v[172:175], v[188:191], v[48:51]
	v_mfma_f32_16x16x32_bf16 v[40:43], v[180:183], v[188:191], v[40:43]
	v_mfma_f32_16x16x32_bf16 v[32:35], v[172:175], v[196:199], v[32:35]
	v_mfma_f32_16x16x32_bf16 v[24:27], v[180:183], v[196:199], v[24:27]
	v_mfma_f32_16x16x32_bf16 v[16:19], v[172:175], v[204:207], v[16:19]
	v_mfma_f32_16x16x32_bf16 v[8:11], v[180:183], v[204:207], v[8:11]
	v_mfma_f32_16x16x32_bf16 v[4:7], v[172:175], v[218:221], v[4:7]
	v_mfma_f32_16x16x32_bf16 v[0:3], v[180:183], v[218:221], v[0:3]
	v_mfma_f32_16x16x32_bf16 v[48:51], v[176:179], v[192:195], v[48:51]
	v_mfma_f32_16x16x32_bf16 v[40:43], v[184:187], v[192:195], v[40:43]
	v_mfma_f32_16x16x32_bf16 v[32:35], v[176:179], v[200:203], v[32:35]
	v_mfma_f32_16x16x32_bf16 v[24:27], v[184:187], v[200:203], v[24:27]
	v_mfma_f32_16x16x32_bf16 v[16:19], v[176:179], v[214:217], v[16:19]
	v_mfma_f32_16x16x32_bf16 v[8:11], v[184:187], v[214:217], v[8:11]
	v_mfma_f32_16x16x32_bf16 v[4:7], v[176:179], v[222:225], v[4:7]
	v_mfma_f32_16x16x32_bf16 v[0:3], v[184:187], v[222:225], v[0:3]
	s_setprio 0
	s_barrier
	s_add_i32 s78, 0, 0x18000
	v_add_u32_e32 v163, s78, v147
	s_add_i32 s79, 0, 0x1c000
	ds_read_b128 v[152:155], v163
	ds_read_b128 v[156:159], v163 offset:1024
	ds_read_b128 v[164:167], v163 offset:2048
	ds_read_b128 v[168:171], v163 offset:3072
	v_add_u32_e32 v163, s79, v147
	ds_read_b128 v[172:175], v163
	ds_read_b128 v[176:179], v163 offset:1024
	ds_read_b128 v[180:183], v163 offset:2048
	ds_read_b128 v[184:187], v163 offset:3072
	s_add_u32 s64, s64, 0x160000
	s_addc_u32 s65, s65, 0
	s_mov_b32 m0, s46
	v_lshl_add_u64 v[230:231], s[64:65], 0, v[134:135]
	ds_read_b128 v[188:191], v151 offset:32768
	ds_read_b128 v[192:195], v151 offset:33792
	ds_read_b128 v[196:199], v151 offset:34816
	ds_read_b128 v[200:203], v151 offset:35840
	ds_read_b128 v[204:207], v151 offset:36864
	ds_read_b128 v[214:217], v151 offset:37888
	ds_read_b128 v[218:221], v151 offset:38912
	ds_read_b128 v[222:225], v151 offset:39936
	global_load_lds_dwordx4 v[230:231], off
	v_lshl_add_u64 v[230:231], s[64:65], 0, v[130:131]
	s_mov_b32 m0, s47
	s_nop 0
	global_load_lds_dwordx4 v[230:231], off
	s_waitcnt vmcnt(8)
	s_waitcnt lgkmcnt(0)
	s_waitcnt lgkmcnt(0)
	v_mfma_f32_16x16x32_bf16 v[124:127], v[152:155], v[188:191], v[124:127]
	v_mfma_f32_16x16x32_bf16 v[120:123], v[164:167], v[188:191], v[120:123]
	v_mfma_f32_16x16x32_bf16 v[116:119], v[152:155], v[196:199], v[116:119]
	v_mfma_f32_16x16x32_bf16 v[108:111], v[164:167], v[196:199], v[108:111]
	v_mfma_f32_16x16x32_bf16 v[100:103], v[152:155], v[204:207], v[100:103]
	v_mfma_f32_16x16x32_bf16 v[92:95], v[164:167], v[204:207], v[92:95]
	v_mfma_f32_16x16x32_bf16 v[84:87], v[152:155], v[218:221], v[84:87]
	v_mfma_f32_16x16x32_bf16 v[76:79], v[164:167], v[218:221], v[76:79]
	s_barrier
	s_setprio 1
	v_mfma_f32_16x16x32_bf16 v[124:127], v[156:159], v[192:195], v[124:127]
	v_mfma_f32_16x16x32_bf16 v[120:123], v[168:171], v[192:195], v[120:123]
	v_mfma_f32_16x16x32_bf16 v[116:119], v[156:159], v[200:203], v[116:119]
	v_mfma_f32_16x16x32_bf16 v[108:111], v[168:171], v[200:203], v[108:111]
	v_mfma_f32_16x16x32_bf16 v[100:103], v[156:159], v[214:217], v[100:103]
	v_mfma_f32_16x16x32_bf16 v[92:95], v[168:171], v[214:217], v[92:95]
	v_mfma_f32_16x16x32_bf16 v[84:87], v[156:159], v[222:225], v[84:87]
	v_mfma_f32_16x16x32_bf16 v[76:79], v[168:171], v[222:225], v[76:79]
	s_setprio 0
	s_setprio 1
	v_mfma_f32_16x16x32_bf16 v[112:115], v[172:175], v[188:191], v[112:115]
	v_mfma_f32_16x16x32_bf16 v[104:107], v[180:183], v[188:191], v[104:107]
	v_mfma_f32_16x16x32_bf16 v[96:99], v[172:175], v[196:199], v[96:99]
	v_mfma_f32_16x16x32_bf16 v[88:91], v[180:183], v[196:199], v[88:91]
	v_mfma_f32_16x16x32_bf16 v[80:83], v[172:175], v[204:207], v[80:83]
	v_mfma_f32_16x16x32_bf16 v[72:75], v[180:183], v[204:207], v[72:75]
	v_mfma_f32_16x16x32_bf16 v[68:71], v[172:175], v[218:221], v[68:71]
	v_mfma_f32_16x16x32_bf16 v[64:67], v[180:183], v[218:221], v[64:67]
	v_mfma_f32_16x16x32_bf16 v[112:115], v[176:179], v[192:195], v[112:115]
	v_mfma_f32_16x16x32_bf16 v[104:107], v[184:187], v[192:195], v[104:107]
	v_mfma_f32_16x16x32_bf16 v[96:99], v[176:179], v[200:203], v[96:99]
	v_mfma_f32_16x16x32_bf16 v[88:91], v[184:187], v[200:203], v[88:91]
	v_mfma_f32_16x16x32_bf16 v[80:83], v[176:179], v[214:217], v[80:83]
	v_mfma_f32_16x16x32_bf16 v[72:75], v[184:187], v[214:217], v[72:75]
	v_mfma_f32_16x16x32_bf16 v[68:71], v[176:179], v[222:225], v[68:71]
	v_mfma_f32_16x16x32_bf16 v[64:67], v[184:187], v[222:225], v[64:67]
	s_setprio 0
	s_barrier
; #define PG8_STAGE(bufoff, gbase, voff) do { _Pragma("unroll") for (int _i = 0; _i < 2; ++_i) \
;         __builtin_amdgcn_global_load_lds((const unsigned*)((const char*)(gbase) + (voff)[_i]), (PG8_LAS unsigned*)(lds + (bufoff) + ldsw + _i * 8192), 16, 0, 0); } while (0)
; #define PG8_LDA(dst, b, h) do { _Pragma("unroll") for (int m = 0; m < 4; ++m) _Pragma("unroll") for (int k = 0; k < 2; ++k) dst[m][k] = *(const PG8_LAS bf16x8*)(lds + PG8_SA(b, h) + aoff + m * 2048 + k * 1024); } while (0)
; #define PG8_MMA(ai, bj, At, Bt) do { __builtin_amdgcn_s_setprio(1); _Pragma("unroll") for (int m = 0; m < 4; ++m) _Pragma("unroll") for (int n = 0; n < 2; ++n) _Pragma("unroll") for (int k = 0; k < 2; ++k) \
;         acc[ai][bj][m][n] = __builtin_amdgcn_mfma_f32_16x16x32_bf16(Bt[n][k], At[m][k], acc[ai][bj][m][n], 0, 0, 0); __builtin_amdgcn_s_setprio(0); } while (0)
; #define PG8_WAIT_V(n) asm volatile("s_waitcnt vmcnt(" #n ")" ::: "memory")
; #define PG8_WAIT_L(n) asm volatile("s_waitcnt lgkmcnt(" #n ")" ::: "memory")
; #define PG8_BAR __builtin_amdgcn_s_barrier()
; #define PG8_SCHED __builtin_amdgcn_sched_barrier(0)
; template <class Epi, class Sched, bool ALIGN_EPI = false, bool SP2 = false>
; __device__ __forceinline__ void gemm_phase(PG8_LAS unsigned char* lds, const Gemm g, const Sched& S, const Epi& E) {
;     ...
;             PG8_LDA(At, 1, 1); PG8_STAGE(PG8_SB(1, 0), b3, voffB); PG8_STAGE(PG8_SB(1, 1), b3 + hstep, voffB); PG8_STAGE(PG8_SA(1, 0), a3, voffA);
;             PG8_WAIT_V(8); PG8_WAIT_L(0); PG8_BAR; PG8_MMA(1, 0, At, B0); PG8_MMA(1, 1, At, B1); PG8_BAR; PG8_SCHED;
;     ...
;         }
;         if constexpr (ALIGN_EPI) { if (wr == 0) PG8_BAR; }
	s_add_i32 s64, s78, s0
	v_lshl_add_u64 v[144:145], v[144:145], 0, s[12:13]
	s_mov_b32 m0, s64
	ds_read_b128 v[188:191], v151 offset:49152
	ds_read_b128 v[192:195], v151 offset:50176
	ds_read_b128 v[196:199], v151 offset:51200
	ds_read_b128 v[200:203], v151 offset:52224
	ds_read_b128 v[204:207], v151 offset:53248
	ds_read_b128 v[214:217], v151 offset:54272
	ds_read_b128 v[218:221], v151 offset:55296
	ds_read_b128 v[222:225], v151 offset:56320
	global_load_lds_dwordx4 v[144:145], off
	s_add_i32 m0, s64, 0x2000
	s_add_u32 s62, s62, 0x160080
	v_lshl_add_u64 v[144:145], v[160:161], 0, s[12:13]
	s_addc_u32 s63, s63, 0
	s_add_i32 s64, s79, s0
	global_load_lds_dwordx4 v[144:145], off
	v_lshl_add_u64 v[144:145], s[62:63], 0, v[132:133]
	s_mov_b32 m0, s64
	s_nop 0
	global_load_lds_dwordx4 v[144:145], off
	v_lshl_add_u64 v[144:145], s[62:63], 0, v[128:129]
	s_add_i32 m0, s64, 0x2000
	s_nop 0
	global_load_lds_dwordx4 v[144:145], off
	v_lshl_add_u64 v[144:145], v[226:227], 0, s[12:13]
	s_mov_b32 m0, s49
	s_nop 0
	global_load_lds_dwordx4 v[144:145], off
	v_lshl_add_u64 v[144:145], v[228:229], 0, s[12:13]
	s_mov_b32 m0, s50
	s_nop 0
	global_load_lds_dwordx4 v[144:145], off
	s_waitcnt vmcnt(8)
	s_waitcnt lgkmcnt(0)
	s_waitcnt lgkmcnt(0)
	v_mfma_f32_16x16x32_bf16 v[60:63], v[152:155], v[188:191], v[60:63]
	v_mfma_f32_16x16x32_bf16 v[56:59], v[164:167], v[188:191], v[56:59]
	v_mfma_f32_16x16x32_bf16 v[52:55], v[152:155], v[196:199], v[52:55]
	v_mfma_f32_16x16x32_bf16 v[44:47], v[164:167], v[196:199], v[44:47]
	v_mfma_f32_16x16x32_bf16 v[36:39], v[152:155], v[204:207], v[36:39]
	v_mfma_f32_16x16x32_bf16 v[28:31], v[164:167], v[204:207], v[28:31]
	v_mfma_f32_16x16x32_bf16 v[20:23], v[152:155], v[218:221], v[20:23]
	v_mfma_f32_16x16x32_bf16 v[12:15], v[164:167], v[218:221], v[12:15]
	s_barrier
	s_setprio 1
	v_mfma_f32_16x16x32_bf16 v[60:63], v[156:159], v[192:195], v[60:63]
	v_mfma_f32_16x16x32_bf16 v[56:59], v[168:171], v[192:195], v[56:59]
	v_mfma_f32_16x16x32_bf16 v[52:55], v[156:159], v[200:203], v[52:55]
	v_mfma_f32_16x16x32_bf16 v[44:47], v[168:171], v[200:203], v[44:47]
	v_mfma_f32_16x16x32_bf16 v[36:39], v[156:159], v[214:217], v[36:39]
	v_mfma_f32_16x16x32_bf16 v[28:31], v[168:171], v[214:217], v[28:31]
	v_mfma_f32_16x16x32_bf16 v[20:23], v[156:159], v[222:225], v[20:23]
	v_mfma_f32_16x16x32_bf16 v[12:15], v[168:171], v[222:225], v[12:15]
	s_setprio 0
	s_setprio 1
	v_mfma_f32_16x16x32_bf16 v[48:51], v[172:175], v[188:191], v[48:51]
	v_mfma_f32_16x16x32_bf16 v[40:43], v[180:183], v[188:191], v[40:43]
	v_mfma_f32_16x16x32_bf16 v[32:35], v[172:175], v[196:199], v[32:35]
	v_mfma_f32_16x16x32_bf16 v[24:27], v[180:183], v[196:199], v[24:27]
	v_mfma_f32_16x16x32_bf16 v[16:19], v[172:175], v[204:207], v[16:19]
	v_mfma_f32_16x16x32_bf16 v[8:11], v[180:183], v[204:207], v[8:11]
	v_mfma_f32_16x16x32_bf16 v[4:7], v[172:175], v[218:221], v[4:7]
	v_mfma_f32_16x16x32_bf16 v[0:3], v[180:183], v[218:221], v[0:3]
	v_mfma_f32_16x16x32_bf16 v[48:51], v[176:179], v[192:195], v[48:51]
	v_mfma_f32_16x16x32_bf16 v[40:43], v[184:187], v[192:195], v[40:43]
	v_mfma_f32_16x16x32_bf16 v[32:35], v[176:179], v[200:203], v[32:35]
	v_mfma_f32_16x16x32_bf16 v[24:27], v[184:187], v[200:203], v[24:27]
	v_mfma_f32_16x16x32_bf16 v[16:19], v[176:179], v[214:217], v[16:19]
	v_mfma_f32_16x16x32_bf16 v[8:11], v[184:187], v[214:217], v[8:11]
	v_mfma_f32_16x16x32_bf16 v[4:7], v[176:179], v[222:225], v[4:7]
	v_mfma_f32_16x16x32_bf16 v[0:3], v[184:187], v[222:225], v[0:3]
	s_setprio 0
	s_barrier
	s_add_i32 s77, s77, 2
	s_add_u32 s38, s38, 0x100
	s_addc_u32 s39, s39, 0
	s_add_u32 s75, s75, 0x100
	s_addc_u32 s76, s76, 0
	s_cmpk_gt_u32 s77, 0x55
	s_cbranch_scc0 .LBB0_731
	s_and_b64 vcc, exec, s[14:15]
	s_cbranch_vccz .LBB0_734
	s_barrier

; #define PG8_STAGE(bufoff, gbase, voff) do { _Pragma("unroll") for (int _i = 0; _i < 2; ++_i) \
;         __builtin_amdgcn_global_load_lds((const unsigned*)((const char*)(gbase) + (voff)[_i]), (PG8_LAS unsigned*)(lds + (bufoff) + ldsw + _i * 8192), 16, 0, 0); } while (0)
; #define PG8_LDA(dst, b, h) do { _Pragma("unroll") for (int m = 0; m < 4; ++m) _Pragma("unroll") for (int k = 0; k < 2; ++k) dst[m][k] = *(const PG8_LAS bf16x8*)(lds + PG8_SA(b, h) + aoff + m * 2048 + k * 1024); } while (0)
; #define PG8_LDB(dst, b, h) do { _Pragma("unroll") for (int n = 0; n < 2; ++n) _Pragma("unroll") for (int k = 0; k < 2; ++k) dst[n][k] = *(const PG8_LAS bf16x8*)(lds + PG8_SB(b, h) + boff + n * 2048 + k * 1024); } while (0)
; #define PG8_MMA(ai, bj, At, Bt) do { __builtin_amdgcn_s_setprio(1); _Pragma("unroll") for (int m = 0; m < 4; ++m) _Pragma("unroll") for (int n = 0; n < 2; ++n) _Pragma("unroll") for (int k = 0; k < 2; ++k) \
;         acc[ai][bj][m][n] = __builtin_amdgcn_mfma_f32_16x16x32_bf16(Bt[n][k], At[m][k], acc[ai][bj][m][n], 0, 0, 0); __builtin_amdgcn_s_setprio(0); } while (0)
; #define PG8_WAIT_V(n) asm volatile("s_waitcnt vmcnt(" #n ")" ::: "memory")
; #define PG8_WAIT_L(n) asm volatile("s_waitcnt lgkmcnt(" #n ")" ::: "memory")
; #define PG8_BAR __builtin_amdgcn_s_barrier()
; #define PG8_SCHED __builtin_amdgcn_sched_barrier(0)
; template <class Epi, class Sched, bool ALIGN_EPI = false, bool SP2 = false>
; __device__ __forceinline__ void gemm_phase(PG8_LAS unsigned char* lds, const Gemm g, const Sched& S, const Epi& E) {
;     ...
;             PG8_LDB(B0, 0, 0); PG8_LDB(B1, 0, 1); PG8_SCHED; PG8_LDA(At, 0, 0); PG8_STAGE(PG8_SA(1, 1), a1 + hstep, voffA);
;             PG8_WAIT_V(8); PG8_WAIT_L(0); PG8_BAR; PG8_MMA(0, 0, At, B0); PG8_MMA(0, 1, At, B1); PG8_BAR; PG8_SCHED;
;             PG8_LDA(At, 0, 1); PG8_STAGE(PG8_SB(0, 0), b2, voffB); PG8_STAGE(PG8_SB(0, 1), b2 + hstep, voffB); PG8_STAGE(PG8_SA(0, 0), a2, voffA);
;             PG8_WAIT_V(8); PG8_WAIT_L(0); PG8_BAR; PG8_MMA(1, 0, At, B0); PG8_MMA(1, 1, At, B1); PG8_BAR; PG8_SCHED;
.LBB0_859:
	ds_read_b128 v[146:149], v143
	ds_read_b128 v[150:153], v143 offset:1024
	ds_read_b128 v[154:157], v143 offset:2048
	ds_read_b128 v[158:161], v143 offset:3072
	ds_read_b128 v[164:167], v144
	ds_read_b128 v[168:171], v144 offset:1024
	ds_read_b128 v[172:175], v144 offset:2048
	ds_read_b128 v[176:179], v144 offset:3072
	s_add_u32 s34, s30, 0xfff80080
	s_addc_u32 s35, s31, -1
	s_cmp_eq_u32 s68, 28
	s_cselect_b32 s39, s19, s35
	s_cselect_b32 s38, s64, s34
	s_cselect_b32 s35, s17, s67
	s_cselect_b32 s34, s65, s66
	v_lshl_add_u64 v[218:219], s[30:31], 0, v[132:133]
	s_add_i32 m0, s11, 0xc000
	ds_read_b128 v[180:183], v145
	ds_read_b128 v[184:187], v145 offset:1024
	ds_read_b128 v[188:191], v145 offset:2048
	ds_read_b128 v[192:195], v145 offset:3072
	ds_read_b128 v[196:199], v145 offset:4096
	ds_read_b128 v[200:203], v145 offset:5120
	ds_read_b128 v[204:207], v145 offset:6144
	ds_read_b128 v[214:217], v145 offset:7168
	global_load_lds_dwordx4 v[218:219], off
	v_lshl_add_u64 v[218:219], s[30:31], 0, v[134:135]
	s_add_i32 m0, s11, 0xe000
	s_nop 0
	global_load_lds_dwordx4 v[218:219], off
	s_waitcnt vmcnt(8)
	s_waitcnt lgkmcnt(0)
	s_waitcnt lgkmcnt(0)
	v_mfma_f32_16x16x32_bf16 v[124:127], v[146:149], v[180:183], v[124:127]
	v_mfma_f32_16x16x32_bf16 v[120:123], v[154:157], v[180:183], v[120:123]
	v_mfma_f32_16x16x32_bf16 v[116:119], v[146:149], v[188:191], v[116:119]
	v_mfma_f32_16x16x32_bf16 v[112:115], v[154:157], v[188:191], v[112:115]
	v_mfma_f32_16x16x32_bf16 v[108:111], v[146:149], v[196:199], v[108:111]
	v_mfma_f32_16x16x32_bf16 v[100:103], v[154:157], v[196:199], v[100:103]
	v_mfma_f32_16x16x32_bf16 v[92:95], v[146:149], v[204:207], v[92:95]
	v_mfma_f32_16x16x32_bf16 v[84:87], v[154:157], v[204:207], v[84:87]
	s_barrier
	s_setprio 1
	v_mfma_f32_16x16x32_bf16 v[124:127], v[150:153], v[184:187], v[124:127]
	v_mfma_f32_16x16x32_bf16 v[120:123], v[158:161], v[184:187], v[120:123]
	v_mfma_f32_16x16x32_bf16 v[116:119], v[150:153], v[192:195], v[116:119]
	v_mfma_f32_16x16x32_bf16 v[112:115], v[158:161], v[192:195], v[112:115]
	v_mfma_f32_16x16x32_bf16 v[108:111], v[150:153], v[200:203], v[108:111]
	v_mfma_f32_16x16x32_bf16 v[100:103], v[158:161], v[200:203], v[100:103]
	v_mfma_f32_16x16x32_bf16 v[92:95], v[150:153], v[214:217], v[92:95]
	v_mfma_f32_16x16x32_bf16 v[84:87], v[158:161], v[214:217], v[84:87]
	s_setprio 0
	s_setprio 1
	v_mfma_f32_16x16x32_bf16 v[104:107], v[164:167], v[180:183], v[104:107]
	v_mfma_f32_16x16x32_bf16 v[96:99], v[172:175], v[180:183], v[96:99]
	v_mfma_f32_16x16x32_bf16 v[88:91], v[164:167], v[188:191], v[88:91]
	v_mfma_f32_16x16x32_bf16 v[80:83], v[172:175], v[188:191], v[80:83]
	v_mfma_f32_16x16x32_bf16 v[76:79], v[164:167], v[196:199], v[76:79]
	v_mfma_f32_16x16x32_bf16 v[72:75], v[172:175], v[196:199], v[72:75]
	v_mfma_f32_16x16x32_bf16 v[68:71], v[164:167], v[204:207], v[68:71]
	v_mfma_f32_16x16x32_bf16 v[64:67], v[172:175], v[204:207], v[64:67]
	v_mfma_f32_16x16x32_bf16 v[104:107], v[168:171], v[184:187], v[104:107]
	v_mfma_f32_16x16x32_bf16 v[96:99], v[176:179], v[184:187], v[96:99]
	v_mfma_f32_16x16x32_bf16 v[88:91], v[168:171], v[192:195], v[88:91]
	v_mfma_f32_16x16x32_bf16 v[80:83], v[176:179], v[192:195], v[80:83]
	v_mfma_f32_16x16x32_bf16 v[76:79], v[168:171], v[200:203], v[76:79]
	v_mfma_f32_16x16x32_bf16 v[72:75], v[176:179], v[200:203], v[72:75]
	v_mfma_f32_16x16x32_bf16 v[68:71], v[168:171], v[214:217], v[68:71]
	v_mfma_f32_16x16x32_bf16 v[64:67], v[176:179], v[214:217], v[64:67]
	s_setprio 0
	s_barrier
	s_add_i32 s69, s56, s0
	v_lshl_add_u64 v[218:219], s[34:35], 0, v[130:131]
	s_mov_b32 m0, s69
	ds_read_b128 v[180:183], v145 offset:16384
	ds_read_b128 v[184:187], v145 offset:17408
	ds_read_b128 v[188:191], v145 offset:18432
	ds_read_b128 v[192:195], v145 offset:19456
	ds_read_b128 v[196:199], v145 offset:20480
	ds_read_b128 v[200:203], v145 offset:21504
	ds_read_b128 v[204:207], v145 offset:22528
	ds_read_b128 v[214:217], v145 offset:23552
	global_load_lds_dwordx4 v[218:219], off
	s_add_i32 m0, s69, 0x2000
	s_add_u32 s70, s34, 0x80000
	v_lshl_add_u64 v[220:221], s[34:35], 0, v[128:129]
	s_addc_u32 s71, s35, 0
	s_add_i32 s69, s57, s0
	global_load_lds_dwordx4 v[220:221], off
	v_lshl_add_u64 v[222:223], s[70:71], 0, v[130:131]
	s_mov_b32 m0, s69
	v_lshl_add_u64 v[224:225], s[38:39], 0, v[128:129]
	global_load_lds_dwordx4 v[222:223], off
	v_lshl_add_u64 v[222:223], s[70:71], 0, v[128:129]
	s_add_i32 m0, s69, 0x2000
	s_nop 0
	global_load_lds_dwordx4 v[222:223], off
	v_lshl_add_u64 v[222:223], s[38:39], 0, v[130:131]
	s_mov_b32 m0, s11
	s_nop 0
	global_load_lds_dwordx4 v[222:223], off
	s_mov_b32 m0, s41
	s_nop 0
	global_load_lds_dwordx4 v[224:225], off
	s_waitcnt vmcnt(8)
	s_waitcnt lgkmcnt(0)
	s_waitcnt lgkmcnt(0)
	v_mfma_f32_16x16x32_bf16 v[60:63], v[146:149], v[180:183], v[60:63]
	v_mfma_f32_16x16x32_bf16 v[56:59], v[154:157], v[180:183], v[56:59]
	v_mfma_f32_16x16x32_bf16 v[52:55], v[146:149], v[188:191], v[52:55]
	v_mfma_f32_16x16x32_bf16 v[48:51], v[154:157], v[188:191], v[48:51]
	v_mfma_f32_16x16x32_bf16 v[44:47], v[146:149], v[196:199], v[44:47]
	v_mfma_f32_16x16x32_bf16 v[36:39], v[154:157], v[196:199], v[36:39]
	v_mfma_f32_16x16x32_bf16 v[28:31], v[146:149], v[204:207], v[28:31]
	v_mfma_f32_16x16x32_bf16 v[20:23], v[154:157], v[204:207], v[20:23]
	s_barrier
; #define PG8_STAGE(bufoff, gbase, voff) do { _Pragma("unroll") for (int _i = 0; _i < 2; ++_i) \
;         __builtin_amdgcn_global_load_lds((const unsigned*)((const char*)(gbase) + (voff)[_i]), (PG8_LAS unsigned*)(lds + (bufoff) + ldsw + _i * 8192), 16, 0, 0); } while (0)
; #define PG8_LDA(dst, b, h) do { _Pragma("unroll") for (int m = 0; m < 4; ++m) _Pragma("unroll") for (int k = 0; k < 2; ++k) dst[m][k] = *(const PG8_LAS bf16x8*)(lds + PG8_SA(b, h) + aoff + m * 2048 + k * 1024); } while (0)
; #define PG8_LDB(dst, b, h) do { _Pragma("unroll") for (int n = 0; n < 2; ++n) _Pragma("unroll") for (int k = 0; k < 2; ++k) dst[n][k] = *(const PG8_LAS bf16x8*)(lds + PG8_SB(b, h) + boff + n * 2048 + k * 1024); } while (0)
; #define PG8_MMA(ai, bj, At, Bt) do { __builtin_amdgcn_s_setprio(1); _Pragma("unroll") for (int m = 0; m < 4; ++m) _Pragma("unroll") for (int n = 0; n < 2; ++n) _Pragma("unroll") for (int k = 0; k < 2; ++k) \
;         acc[ai][bj][m][n] = __builtin_amdgcn_mfma_f32_16x16x32_bf16(Bt[n][k], At[m][k], acc[ai][bj][m][n], 0, 0, 0); __builtin_amdgcn_s_setprio(0); } while (0)
; #define PG8_WAIT_V(n) asm volatile("s_waitcnt vmcnt(" #n ")" ::: "memory")
; #define PG8_WAIT_L(n) asm volatile("s_waitcnt lgkmcnt(" #n ")" ::: "memory")
; #define PG8_BAR __builtin_amdgcn_s_barrier()
; #define PG8_SCHED __builtin_amdgcn_sched_barrier(0)
; template <class Epi, class Sched, bool ALIGN_EPI = false, bool SP2 = false>
; __device__ __forceinline__ void gemm_phase(PG8_LAS unsigned char* lds, const Gemm g, const Sched& S, const Epi& E) {
;     ...
;             PG8_WAIT_V(8); PG8_WAIT_L(0); PG8_BAR; PG8_MMA(1, 0, At, B0); PG8_MMA(1, 1, At, B1); PG8_BAR; PG8_SCHED;
;             PG8_LDB(B0, 1, 0); PG8_LDB(B1, 1, 1); PG8_SCHED; PG8_LDA(At, 1, 0); PG8_STAGE(PG8_SA(0, 1), a2 + hstep, voffA);
;             PG8_WAIT_V(8); PG8_WAIT_L(0); PG8_BAR; PG8_MMA(0, 0, At, B0); PG8_MMA(0, 1, At, B1); PG8_BAR; PG8_SCHED;
	s_setprio 1
	v_mfma_f32_16x16x32_bf16 v[60:63], v[150:153], v[184:187], v[60:63]
	v_mfma_f32_16x16x32_bf16 v[56:59], v[158:161], v[184:187], v[56:59]
	v_mfma_f32_16x16x32_bf16 v[52:55], v[150:153], v[192:195], v[52:55]
	v_mfma_f32_16x16x32_bf16 v[48:51], v[158:161], v[192:195], v[48:51]
	v_mfma_f32_16x16x32_bf16 v[44:47], v[150:153], v[200:203], v[44:47]
	v_mfma_f32_16x16x32_bf16 v[36:39], v[158:161], v[200:203], v[36:39]
	v_mfma_f32_16x16x32_bf16 v[28:31], v[150:153], v[214:217], v[28:31]
	v_mfma_f32_16x16x32_bf16 v[20:23], v[158:161], v[214:217], v[20:23]
	s_setprio 0
	s_setprio 1
	v_mfma_f32_16x16x32_bf16 v[40:43], v[164:167], v[180:183], v[40:43]
	v_mfma_f32_16x16x32_bf16 v[32:35], v[172:175], v[180:183], v[32:35]
	v_mfma_f32_16x16x32_bf16 v[24:27], v[164:167], v[188:191], v[24:27]
	v_mfma_f32_16x16x32_bf16 v[16:19], v[172:175], v[188:191], v[16:19]
	v_mfma_f32_16x16x32_bf16 v[12:15], v[164:167], v[196:199], v[12:15]
	v_mfma_f32_16x16x32_bf16 v[8:11], v[172:175], v[196:199], v[8:11]
	v_mfma_f32_16x16x32_bf16 v[4:7], v[164:167], v[204:207], v[4:7]
	v_mfma_f32_16x16x32_bf16 v[0:3], v[172:175], v[204:207], v[0:3]
	v_mfma_f32_16x16x32_bf16 v[40:43], v[168:171], v[184:187], v[40:43]
	v_mfma_f32_16x16x32_bf16 v[32:35], v[176:179], v[184:187], v[32:35]
	v_mfma_f32_16x16x32_bf16 v[24:27], v[168:171], v[192:195], v[24:27]
	v_mfma_f32_16x16x32_bf16 v[16:19], v[176:179], v[192:195], v[16:19]
	v_mfma_f32_16x16x32_bf16 v[12:15], v[168:171], v[200:203], v[12:15]
	v_mfma_f32_16x16x32_bf16 v[8:11], v[176:179], v[200:203], v[8:11]
	v_mfma_f32_16x16x32_bf16 v[4:7], v[168:171], v[214:217], v[4:7]
	v_mfma_f32_16x16x32_bf16 v[0:3], v[176:179], v[214:217], v[0:3]
	s_setprio 0
	s_barrier
	s_add_i32 s69, 0, 0x18000
	s_add_i32 s70, 0, 0x1c000
	v_add_u32_e32 v158, s69, v141
	v_add_u32_e32 v163, s70, v141
	ds_read_b128 v[146:149], v158
	ds_read_b128 v[150:153], v158 offset:1024
	ds_read_b128 v[154:157], v158 offset:2048
	ds_read_b128 v[158:161], v158 offset:3072
	ds_read_b128 v[164:167], v163
	ds_read_b128 v[168:171], v163 offset:1024
	ds_read_b128 v[172:175], v163 offset:2048
	ds_read_b128 v[176:179], v163 offset:3072
	s_add_u32 s38, s38, 0x80000
	s_addc_u32 s39, s39, 0
	s_mov_b32 m0, s43
	v_lshl_add_u64 v[226:227], s[38:39], 0, v[130:131]
	ds_read_b128 v[180:183], v145 offset:32768
	ds_read_b128 v[184:187], v145 offset:33792
	ds_read_b128 v[188:191], v145 offset:34816
	ds_read_b128 v[192:195], v145 offset:35840
	ds_read_b128 v[196:199], v145 offset:36864
	ds_read_b128 v[200:203], v145 offset:37888
	ds_read_b128 v[204:207], v145 offset:38912
	ds_read_b128 v[214:217], v145 offset:39936
	global_load_lds_dwordx4 v[226:227], off
	v_lshl_add_u64 v[226:227], s[38:39], 0, v[128:129]
	s_mov_b32 m0, s46
	s_nop 0
	global_load_lds_dwordx4 v[226:227], off
	s_waitcnt vmcnt(8)
	s_waitcnt lgkmcnt(0)
	s_waitcnt lgkmcnt(0)
	v_mfma_f32_16x16x32_bf16 v[124:127], v[146:149], v[180:183], v[124:127]
	v_mfma_f32_16x16x32_bf16 v[120:123], v[154:157], v[180:183], v[120:123]
	v_mfma_f32_16x16x32_bf16 v[116:119], v[146:149], v[188:191], v[116:119]
	v_mfma_f32_16x16x32_bf16 v[112:115], v[154:157], v[188:191], v[112:115]
	v_mfma_f32_16x16x32_bf16 v[108:111], v[146:149], v[196:199], v[108:111]
	v_mfma_f32_16x16x32_bf16 v[100:103], v[154:157], v[196:199], v[100:103]
	v_mfma_f32_16x16x32_bf16 v[92:95], v[146:149], v[204:207], v[92:95]
	v_mfma_f32_16x16x32_bf16 v[84:87], v[154:157], v[204:207], v[84:87]
	s_barrier
	s_setprio 1
	v_mfma_f32_16x16x32_bf16 v[124:127], v[150:153], v[184:187], v[124:127]
	v_mfma_f32_16x16x32_bf16 v[120:123], v[158:161], v[184:187], v[120:123]
	v_mfma_f32_16x16x32_bf16 v[116:119], v[150:153], v[192:195], v[116:119]
	v_mfma_f32_16x16x32_bf16 v[112:115], v[158:161], v[192:195], v[112:115]
	v_mfma_f32_16x16x32_bf16 v[108:111], v[150:153], v[200:203], v[108:111]
	v_mfma_f32_16x16x32_bf16 v[100:103], v[158:161], v[200:203], v[100:103]
	v_mfma_f32_16x16x32_bf16 v[92:95], v[150:153], v[214:217], v[92:95]
	v_mfma_f32_16x16x32_bf16 v[84:87], v[158:161], v[214:217], v[84:87]
	s_setprio 0
	s_setprio 1
	v_mfma_f32_16x16x32_bf16 v[104:107], v[164:167], v[180:183], v[104:107]
	v_mfma_f32_16x16x32_bf16 v[96:99], v[172:175], v[180:183], v[96:99]
	v_mfma_f32_16x16x32_bf16 v[88:91], v[164:167], v[188:191], v[88:91]
	v_mfma_f32_16x16x32_bf16 v[80:83], v[172:175], v[188:191], v[80:83]
	v_mfma_f32_16x16x32_bf16 v[76:79], v[164:167], v[196:199], v[76:79]
	v_mfma_f32_16x16x32_bf16 v[72:75], v[172:175], v[196:199], v[72:75]
	v_mfma_f32_16x16x32_bf16 v[68:71], v[164:167], v[204:207], v[68:71]
	v_mfma_f32_16x16x32_bf16 v[64:67], v[172:175], v[204:207], v[64:67]
	v_mfma_f32_16x16x32_bf16 v[104:107], v[168:171], v[184:187], v[104:107]
	v_mfma_f32_16x16x32_bf16 v[96:99], v[176:179], v[184:187], v[96:99]
	v_mfma_f32_16x16x32_bf16 v[88:91], v[168:171], v[192:195], v[88:91]
	v_mfma_f32_16x16x32_bf16 v[80:83], v[176:179], v[192:195], v[80:83]
	v_mfma_f32_16x16x32_bf16 v[76:79], v[168:171], v[200:203], v[76:79]
	v_mfma_f32_16x16x32_bf16 v[72:75], v[176:179], v[200:203], v[72:75]
	v_mfma_f32_16x16x32_bf16 v[68:71], v[168:171], v[214:217], v[68:71]
	v_mfma_f32_16x16x32_bf16 v[64:67], v[176:179], v[214:217], v[64:67]
	s_setprio 0
	s_barrier
; #define PG8_STAGE(bufoff, gbase, voff) do { _Pragma("unroll") for (int _i = 0; _i < 2; ++_i) \
;         __builtin_amdgcn_global_load_lds((const unsigned*)((const char*)(gbase) + (voff)[_i]), (PG8_LAS unsigned*)(lds + (bufoff) + ldsw + _i * 8192), 16, 0, 0); } while (0)
; #define PG8_LDA(dst, b, h) do { _Pragma("unroll") for (int m = 0; m < 4; ++m) _Pragma("unroll") for (int k = 0; k < 2; ++k) dst[m][k] = *(const PG8_LAS bf16x8*)(lds + PG8_SA(b, h) + aoff + m * 2048 + k * 1024); } while (0)
; #define PG8_MMA(ai, bj, At, Bt) do { __builtin_amdgcn_s_setprio(1); _Pragma("unroll") for (int m = 0; m < 4; ++m) _Pragma("unroll") for (int n = 0; n < 2; ++n) _Pragma("unroll") for (int k = 0; k < 2; ++k) \
;         acc[ai][bj][m][n] = __builtin_amdgcn_mfma_f32_16x16x32_bf16(Bt[n][k], At[m][k], acc[ai][bj][m][n], 0, 0, 0); __builtin_amdgcn_s_setprio(0); } while (0)
; #define PG8_WAIT_V(n) asm volatile("s_waitcnt vmcnt(" #n ")" ::: "memory")
; #define PG8_WAIT_L(n) asm volatile("s_waitcnt lgkmcnt(" #n ")" ::: "memory")
; #define PG8_BAR __builtin_amdgcn_s_barrier()
; #define PG8_SCHED __builtin_amdgcn_sched_barrier(0)
; template <class Epi, class Sched, bool ALIGN_EPI = false, bool SP2 = false>
; __device__ __forceinline__ void gemm_phase(PG8_LAS unsigned char* lds, const Gemm g, const Sched& S, const Epi& E) {
;     ...
;             PG8_LDA(At, 1, 1); PG8_STAGE(PG8_SB(1, 0), b3, voffB); PG8_STAGE(PG8_SB(1, 1), b3 + hstep, voffB); PG8_STAGE(PG8_SA(1, 0), a3, voffA);
;             PG8_WAIT_V(8); PG8_WAIT_L(0); PG8_BAR; PG8_MMA(1, 0, At, B0); PG8_MMA(1, 1, At, B1); PG8_BAR; PG8_SCHED;
;     ...
;         }
;         if constexpr (ALIGN_EPI) { if (wr == 0) PG8_BAR; }
	s_add_i32 s38, s69, s0
	v_lshl_add_u64 v[218:219], v[218:219], 0, s[12:13]
	s_mov_b32 m0, s38
	ds_read_b128 v[180:183], v145 offset:49152
	ds_read_b128 v[184:187], v145 offset:50176
	ds_read_b128 v[188:191], v145 offset:51200
	ds_read_b128 v[192:195], v145 offset:52224
	ds_read_b128 v[196:199], v145 offset:53248
	ds_read_b128 v[200:203], v145 offset:54272
	ds_read_b128 v[204:207], v145 offset:55296
	ds_read_b128 v[214:217], v145 offset:56320
	global_load_lds_dwordx4 v[218:219], off
	s_add_i32 m0, s38, 0x2000
	s_add_u32 s34, s34, 0x80080
	v_lshl_add_u64 v[218:219], v[220:221], 0, s[12:13]
	s_addc_u32 s35, s35, 0
	s_add_i32 s38, s70, s0
	global_load_lds_dwordx4 v[218:219], off
	v_lshl_add_u64 v[218:219], s[34:35], 0, v[130:131]
	s_mov_b32 m0, s38
	s_nop 0
	global_load_lds_dwordx4 v[218:219], off
	v_lshl_add_u64 v[218:219], s[34:35], 0, v[128:129]
	s_add_i32 m0, s38, 0x2000
	s_nop 0
	global_load_lds_dwordx4 v[218:219], off
	v_lshl_add_u64 v[218:219], v[222:223], 0, s[12:13]
	s_mov_b32 m0, s48
	s_nop 0
	global_load_lds_dwordx4 v[218:219], off
	v_lshl_add_u64 v[218:219], v[224:225], 0, s[12:13]
	s_mov_b32 m0, s49
	s_nop 0
	global_load_lds_dwordx4 v[218:219], off
	s_waitcnt vmcnt(8)
	s_waitcnt lgkmcnt(0)
	s_waitcnt lgkmcnt(0)
	v_mfma_f32_16x16x32_bf16 v[60:63], v[146:149], v[180:183], v[60:63]
	v_mfma_f32_16x16x32_bf16 v[56:59], v[154:157], v[180:183], v[56:59]
	v_mfma_f32_16x16x32_bf16 v[52:55], v[146:149], v[188:191], v[52:55]
	v_mfma_f32_16x16x32_bf16 v[48:51], v[154:157], v[188:191], v[48:51]
	v_mfma_f32_16x16x32_bf16 v[44:47], v[146:149], v[196:199], v[44:47]
	v_mfma_f32_16x16x32_bf16 v[36:39], v[154:157], v[196:199], v[36:39]
	v_mfma_f32_16x16x32_bf16 v[28:31], v[146:149], v[204:207], v[28:31]
	v_mfma_f32_16x16x32_bf16 v[20:23], v[154:157], v[204:207], v[20:23]
	s_barrier
	s_setprio 1
	v_mfma_f32_16x16x32_bf16 v[60:63], v[150:153], v[184:187], v[60:63]
	v_mfma_f32_16x16x32_bf16 v[56:59], v[158:161], v[184:187], v[56:59]
	v_mfma_f32_16x16x32_bf16 v[52:55], v[150:153], v[192:195], v[52:55]
	v_mfma_f32_16x16x32_bf16 v[48:51], v[158:161], v[192:195], v[48:51]
	v_mfma_f32_16x16x32_bf16 v[44:47], v[150:153], v[200:203], v[44:47]
	v_mfma_f32_16x16x32_bf16 v[36:39], v[158:161], v[200:203], v[36:39]
	v_mfma_f32_16x16x32_bf16 v[28:31], v[150:153], v[214:217], v[28:31]
	v_mfma_f32_16x16x32_bf16 v[20:23], v[158:161], v[214:217], v[20:23]
	s_setprio 0
	s_setprio 1
	v_mfma_f32_16x16x32_bf16 v[40:43], v[164:167], v[180:183], v[40:43]
	v_mfma_f32_16x16x32_bf16 v[32:35], v[172:175], v[180:183], v[32:35]
	v_mfma_f32_16x16x32_bf16 v[24:27], v[164:167], v[188:191], v[24:27]
	v_mfma_f32_16x16x32_bf16 v[16:19], v[172:175], v[188:191], v[16:19]
	v_mfma_f32_16x16x32_bf16 v[12:15], v[164:167], v[196:199], v[12:15]
	v_mfma_f32_16x16x32_bf16 v[8:11], v[172:175], v[196:199], v[8:11]
	v_mfma_f32_16x16x32_bf16 v[4:7], v[164:167], v[204:207], v[4:7]
	v_mfma_f32_16x16x32_bf16 v[0:3], v[172:175], v[204:207], v[0:3]
	v_mfma_f32_16x16x32_bf16 v[40:43], v[168:171], v[184:187], v[40:43]
	v_mfma_f32_16x16x32_bf16 v[32:35], v[176:179], v[184:187], v[32:35]
	v_mfma_f32_16x16x32_bf16 v[24:27], v[168:171], v[192:195], v[24:27]
	v_mfma_f32_16x16x32_bf16 v[16:19], v[176:179], v[192:195], v[16:19]
	v_mfma_f32_16x16x32_bf16 v[12:15], v[168:171], v[200:203], v[12:15]
	v_mfma_f32_16x16x32_bf16 v[8:11], v[176:179], v[200:203], v[8:11]
	v_mfma_f32_16x16x32_bf16 v[4:7], v[168:171], v[214:217], v[4:7]
	v_mfma_f32_16x16x32_bf16 v[0:3], v[176:179], v[214:217], v[0:3]
	s_setprio 0
	s_barrier
	s_add_i32 s68, s68, 2
	s_add_u32 s30, s30, 0x100
	s_addc_u32 s31, s31, 0
	s_add_u32 s66, s66, 0x100
	s_addc_u32 s67, s67, 0
	s_cmp_gt_u32 s68, 29
	s_cbranch_scc0 .LBB0_859
	s_and_b64 vcc, exec, s[14:15]
	s_cbranch_vccz .LBB0_862
	s_barrier

; #define PG8_STAGE(bufoff, gbase, voff) do { _Pragma("unroll") for (int _i = 0; _i < 2; ++_i) \
;         __builtin_amdgcn_global_load_lds((const unsigned*)((const char*)(gbase) + (voff)[_i]), (PG8_LAS unsigned*)(lds + (bufoff) + ldsw + _i * 8192), 16, 0, 0); } while (0)
; #define PG8_LDA(dst, b, h) do { _Pragma("unroll") for (int m = 0; m < 4; ++m) _Pragma("unroll") for (int k = 0; k < 2; ++k) dst[m][k] = *(const PG8_LAS bf16x8*)(lds + PG8_SA(b, h) + aoff + m * 2048 + k * 1024); } while (0)
; #define PG8_LDB(dst, b, h) do { _Pragma("unroll") for (int n = 0; n < 2; ++n) _Pragma("unroll") for (int k = 0; k < 2; ++k) dst[n][k] = *(const PG8_LAS bf16x8*)(lds + PG8_SB(b, h) + boff + n * 2048 + k * 1024); } while (0)
; #define PG8_MMA(ai, bj, At, Bt) do { __builtin_amdgcn_s_setprio(1); _Pragma("unroll") for (int m = 0; m < 4; ++m) _Pragma("unroll") for (int n = 0; n < 2; ++n) _Pragma("unroll") for (int k = 0; k < 2; ++k) \
;         acc[ai][bj][m][n] = __builtin_amdgcn_mfma_f32_16x16x32_bf16(Bt[n][k], At[m][k], acc[ai][bj][m][n], 0, 0, 0); __builtin_amdgcn_s_setprio(0); } while (0)
; #define PG8_WAIT_V(n) asm volatile("s_waitcnt vmcnt(" #n ")" ::: "memory")
; #define PG8_WAIT_L(n) asm volatile("s_waitcnt lgkmcnt(" #n ")" ::: "memory")
; #define PG8_BAR __builtin_amdgcn_s_barrier()
; #define PG8_SCHED __builtin_amdgcn_sched_barrier(0)
; template <class Epi, class Sched, bool ALIGN_EPI = false, bool SP2 = false>
; __device__ __forceinline__ void gemm_phase(PG8_LAS unsigned char* lds, const Gemm g, const Sched& S, const Epi& E) {
;     ...
;             PG8_LDB(B0, 0, 0); PG8_LDB(B1, 0, 1); PG8_SCHED; PG8_LDA(At, 0, 0); PG8_STAGE(PG8_SA(1, 1), a1 + hstep, voffA);
;             PG8_WAIT_V(8); PG8_WAIT_L(0); PG8_BAR; PG8_MMA(0, 0, At, B0); PG8_MMA(0, 1, At, B1); PG8_BAR; PG8_SCHED;
;             PG8_LDA(At, 0, 1); PG8_STAGE(PG8_SB(0, 0), b2, voffB); PG8_STAGE(PG8_SB(0, 1), b2 + hstep, voffB); PG8_STAGE(PG8_SA(0, 0), a2, voffA);
;             PG8_WAIT_V(8); PG8_WAIT_L(0); PG8_BAR; PG8_MMA(1, 0, At, B0); PG8_MMA(1, 1, At, B1); PG8_BAR; PG8_SCHED;
.LBB0_997:
	ds_read_b128 v[154:157], v131
	ds_read_b128 v[158:161], v131 offset:1024
	ds_read_b128 v[164:167], v131 offset:2048
	ds_read_b128 v[168:171], v131 offset:3072
	ds_read_b128 v[178:181], v176
	ds_read_b128 v[182:185], v176 offset:1024
	ds_read_b128 v[186:189], v176 offset:2048
	ds_read_b128 v[190:193], v176 offset:3072
	s_add_u32 s30, s28, 0xfffe0080
	s_addc_u32 s31, s29, -1
	s_cmp_eq_u32 s73, 4
	s_cselect_b32 s35, s19, s31
	s_cselect_b32 s34, s56, s30
	s_cselect_b32 s31, s17, s72
	s_cselect_b32 s30, s57, s71
	v_lshl_add_u64 v[172:173], s[28:29], 0, v[146:147]
	s_add_i32 m0, s43, 0xc000
	ds_read_b128 v[194:197], v177
	ds_read_b128 v[198:201], v177 offset:1024
	ds_read_b128 v[202:205], v177 offset:2048
	ds_read_b128 v[210:213], v177 offset:3072
	ds_read_b128 v[214:217], v177 offset:4096
	ds_read_b128 v[218:221], v177 offset:5120
	ds_read_b128 v[222:225], v177 offset:6144
	ds_read_b128 v[226:229], v177 offset:7168
	global_load_lds_dwordx4 v[172:173], off
	v_lshl_add_u64 v[172:173], s[28:29], 0, v[148:149]
	s_add_i32 m0, s43, 0xe000
	s_nop 0
	global_load_lds_dwordx4 v[172:173], off
	s_waitcnt vmcnt(8)
	s_waitcnt lgkmcnt(0)
	s_waitcnt lgkmcnt(0)
	v_mfma_f32_16x16x32_bf16 v[124:127], v[154:157], v[194:197], v[124:127]
	v_mfma_f32_16x16x32_bf16 v[120:123], v[164:167], v[194:197], v[120:123]
	v_mfma_f32_16x16x32_bf16 v[116:119], v[154:157], v[202:205], v[116:119]
	v_mfma_f32_16x16x32_bf16 v[108:111], v[164:167], v[202:205], v[108:111]
	v_mfma_f32_16x16x32_bf16 v[100:103], v[154:157], v[214:217], v[100:103]
	v_mfma_f32_16x16x32_bf16 v[92:95], v[164:167], v[214:217], v[92:95]
	v_mfma_f32_16x16x32_bf16 v[84:87], v[154:157], v[222:225], v[84:87]
	v_mfma_f32_16x16x32_bf16 v[76:79], v[164:167], v[222:225], v[76:79]
	s_barrier
	s_setprio 1
	v_mfma_f32_16x16x32_bf16 v[124:127], v[158:161], v[198:201], v[124:127]
	v_mfma_f32_16x16x32_bf16 v[120:123], v[168:171], v[198:201], v[120:123]
	v_mfma_f32_16x16x32_bf16 v[116:119], v[158:161], v[210:213], v[116:119]
	v_mfma_f32_16x16x32_bf16 v[108:111], v[168:171], v[210:213], v[108:111]
	v_mfma_f32_16x16x32_bf16 v[100:103], v[158:161], v[218:221], v[100:103]
	v_mfma_f32_16x16x32_bf16 v[92:95], v[168:171], v[218:221], v[92:95]
	v_mfma_f32_16x16x32_bf16 v[84:87], v[158:161], v[226:229], v[84:87]
	v_mfma_f32_16x16x32_bf16 v[76:79], v[168:171], v[226:229], v[76:79]
	s_setprio 0
	s_setprio 1
	v_mfma_f32_16x16x32_bf16 v[112:115], v[178:181], v[194:197], v[112:115]
	v_mfma_f32_16x16x32_bf16 v[104:107], v[186:189], v[194:197], v[104:107]
	v_mfma_f32_16x16x32_bf16 v[96:99], v[178:181], v[202:205], v[96:99]
	v_mfma_f32_16x16x32_bf16 v[88:91], v[186:189], v[202:205], v[88:91]
	v_mfma_f32_16x16x32_bf16 v[80:83], v[178:181], v[214:217], v[80:83]
	v_mfma_f32_16x16x32_bf16 v[72:75], v[186:189], v[214:217], v[72:75]
	v_mfma_f32_16x16x32_bf16 v[68:71], v[178:181], v[222:225], v[68:71]
	v_mfma_f32_16x16x32_bf16 v[64:67], v[186:189], v[222:225], v[64:67]
	v_mfma_f32_16x16x32_bf16 v[112:115], v[182:185], v[198:201], v[112:115]
	v_mfma_f32_16x16x32_bf16 v[104:107], v[190:193], v[198:201], v[104:107]
	v_mfma_f32_16x16x32_bf16 v[96:99], v[182:185], v[210:213], v[96:99]
	v_mfma_f32_16x16x32_bf16 v[88:91], v[190:193], v[210:213], v[88:91]
	v_mfma_f32_16x16x32_bf16 v[80:83], v[182:185], v[218:221], v[80:83]
	v_mfma_f32_16x16x32_bf16 v[72:75], v[190:193], v[218:221], v[72:75]
	v_mfma_f32_16x16x32_bf16 v[68:71], v[182:185], v[226:229], v[68:71]
	v_mfma_f32_16x16x32_bf16 v[64:67], v[190:193], v[226:229], v[64:67]
	s_setprio 0
	s_barrier
	s_add_i32 s74, s66, s0
	v_lshl_add_u64 v[172:173], s[30:31], 0, v[136:137]
	s_mov_b32 m0, s74
	ds_read_b128 v[194:197], v177 offset:16384
	ds_read_b128 v[198:201], v177 offset:17408
	ds_read_b128 v[202:205], v177 offset:18432
	ds_read_b128 v[210:213], v177 offset:19456
	ds_read_b128 v[214:217], v177 offset:20480
	ds_read_b128 v[218:221], v177 offset:21504
	ds_read_b128 v[222:225], v177 offset:22528
	ds_read_b128 v[226:229], v177 offset:23552
	global_load_lds_dwordx4 v[172:173], off
	s_add_i32 m0, s74, 0x2000
	s_add_u32 s74, s30, 0x20000
	v_lshl_add_u64 v[206:207], s[30:31], 0, v[132:133]
	s_addc_u32 s75, s31, 0
	s_add_i32 s76, s67, s0
	global_load_lds_dwordx4 v[206:207], off
	v_lshl_add_u64 v[230:231], s[74:75], 0, v[136:137]
	s_mov_b32 m0, s76
	v_lshl_add_u64 v[234:235], s[34:35], 0, v[134:135]
	global_load_lds_dwordx4 v[230:231], off
	v_lshl_add_u64 v[230:231], s[74:75], 0, v[132:133]
	s_add_i32 m0, s76, 0x2000
	s_nop 0
	global_load_lds_dwordx4 v[230:231], off
	v_lshl_add_u64 v[230:231], s[34:35], 0, v[138:139]
	s_mov_b32 m0, s43
	s_nop 0
	global_load_lds_dwordx4 v[230:231], off
	s_mov_b32 m0, s46
	s_nop 0
	global_load_lds_dwordx4 v[234:235], off
	s_waitcnt vmcnt(8)
	s_waitcnt lgkmcnt(0)
	s_waitcnt lgkmcnt(0)
	v_mfma_f32_16x16x32_bf16 v[60:63], v[154:157], v[194:197], v[60:63]
	v_mfma_f32_16x16x32_bf16 v[56:59], v[164:167], v[194:197], v[56:59]
	v_mfma_f32_16x16x32_bf16 v[52:55], v[154:157], v[202:205], v[52:55]
	v_mfma_f32_16x16x32_bf16 v[44:47], v[164:167], v[202:205], v[44:47]
	v_mfma_f32_16x16x32_bf16 v[36:39], v[154:157], v[214:217], v[36:39]
	v_mfma_f32_16x16x32_bf16 v[28:31], v[164:167], v[214:217], v[28:31]
	v_mfma_f32_16x16x32_bf16 v[20:23], v[154:157], v[222:225], v[20:23]
	v_mfma_f32_16x16x32_bf16 v[12:15], v[164:167], v[222:225], v[12:15]
	s_barrier
; #define PG8_STAGE(bufoff, gbase, voff) do { _Pragma("unroll") for (int _i = 0; _i < 2; ++_i) \
;         __builtin_amdgcn_global_load_lds((const unsigned*)((const char*)(gbase) + (voff)[_i]), (PG8_LAS unsigned*)(lds + (bufoff) + ldsw + _i * 8192), 16, 0, 0); } while (0)
; #define PG8_LDA(dst, b, h) do { _Pragma("unroll") for (int m = 0; m < 4; ++m) _Pragma("unroll") for (int k = 0; k < 2; ++k) dst[m][k] = *(const PG8_LAS bf16x8*)(lds + PG8_SA(b, h) + aoff + m * 2048 + k * 1024); } while (0)
; #define PG8_LDB(dst, b, h) do { _Pragma("unroll") for (int n = 0; n < 2; ++n) _Pragma("unroll") for (int k = 0; k < 2; ++k) dst[n][k] = *(const PG8_LAS bf16x8*)(lds + PG8_SB(b, h) + boff + n * 2048 + k * 1024); } while (0)
; #define PG8_MMA(ai, bj, At, Bt) do { __builtin_amdgcn_s_setprio(1); _Pragma("unroll") for (int m = 0; m < 4; ++m) _Pragma("unroll") for (int n = 0; n < 2; ++n) _Pragma("unroll") for (int k = 0; k < 2; ++k) \
;         acc[ai][bj][m][n] = __builtin_amdgcn_mfma_f32_16x16x32_bf16(Bt[n][k], At[m][k], acc[ai][bj][m][n], 0, 0, 0); __builtin_amdgcn_s_setprio(0); } while (0)
; #define PG8_WAIT_V(n) asm volatile("s_waitcnt vmcnt(" #n ")" ::: "memory")
; #define PG8_WAIT_L(n) asm volatile("s_waitcnt lgkmcnt(" #n ")" ::: "memory")
; #define PG8_BAR __builtin_amdgcn_s_barrier()
; #define PG8_SCHED __builtin_amdgcn_sched_barrier(0)
; template <class Epi, class Sched, bool ALIGN_EPI = false, bool SP2 = false>
; __device__ __forceinline__ void gemm_phase(PG8_LAS unsigned char* lds, const Gemm g, const Sched& S, const Epi& E) {
;     ...
;             PG8_WAIT_V(8); PG8_WAIT_L(0); PG8_BAR; PG8_MMA(1, 0, At, B0); PG8_MMA(1, 1, At, B1); PG8_BAR; PG8_SCHED;
;             PG8_LDB(B0, 1, 0); PG8_LDB(B1, 1, 1); PG8_SCHED; PG8_LDA(At, 1, 0); PG8_STAGE(PG8_SA(0, 1), a2 + hstep, voffA);
;             PG8_WAIT_V(8); PG8_WAIT_L(0); PG8_BAR; PG8_MMA(0, 0, At, B0); PG8_MMA(0, 1, At, B1); PG8_BAR; PG8_SCHED;
	s_setprio 1
	v_mfma_f32_16x16x32_bf16 v[60:63], v[158:161], v[198:201], v[60:63]
	v_mfma_f32_16x16x32_bf16 v[56:59], v[168:171], v[198:201], v[56:59]
	v_mfma_f32_16x16x32_bf16 v[52:55], v[158:161], v[210:213], v[52:55]
	v_mfma_f32_16x16x32_bf16 v[44:47], v[168:171], v[210:213], v[44:47]
	v_mfma_f32_16x16x32_bf16 v[36:39], v[158:161], v[218:221], v[36:39]
	v_mfma_f32_16x16x32_bf16 v[28:31], v[168:171], v[218:221], v[28:31]
	v_mfma_f32_16x16x32_bf16 v[20:23], v[158:161], v[226:229], v[20:23]
	v_mfma_f32_16x16x32_bf16 v[12:15], v[168:171], v[226:229], v[12:15]
	s_setprio 0
	s_setprio 1
	v_mfma_f32_16x16x32_bf16 v[48:51], v[178:181], v[194:197], v[48:51]
	v_mfma_f32_16x16x32_bf16 v[40:43], v[186:189], v[194:197], v[40:43]
	v_mfma_f32_16x16x32_bf16 v[32:35], v[178:181], v[202:205], v[32:35]
	v_mfma_f32_16x16x32_bf16 v[24:27], v[186:189], v[202:205], v[24:27]
	v_mfma_f32_16x16x32_bf16 v[16:19], v[178:181], v[214:217], v[16:19]
	v_mfma_f32_16x16x32_bf16 v[8:11], v[186:189], v[214:217], v[8:11]
	v_mfma_f32_16x16x32_bf16 v[4:7], v[178:181], v[222:225], v[4:7]
	v_mfma_f32_16x16x32_bf16 v[0:3], v[186:189], v[222:225], v[0:3]
	v_mfma_f32_16x16x32_bf16 v[48:51], v[182:185], v[198:201], v[48:51]
	v_mfma_f32_16x16x32_bf16 v[40:43], v[190:193], v[198:201], v[40:43]
	v_mfma_f32_16x16x32_bf16 v[32:35], v[182:185], v[210:213], v[32:35]
	v_mfma_f32_16x16x32_bf16 v[24:27], v[190:193], v[210:213], v[24:27]
	v_mfma_f32_16x16x32_bf16 v[16:19], v[182:185], v[218:221], v[16:19]
	v_mfma_f32_16x16x32_bf16 v[8:11], v[190:193], v[218:221], v[8:11]
	v_mfma_f32_16x16x32_bf16 v[4:7], v[182:185], v[226:229], v[4:7]
	v_mfma_f32_16x16x32_bf16 v[0:3], v[190:193], v[226:229], v[0:3]
	s_setprio 0
	s_barrier
	s_add_i32 s74, 0, 0x18000
	s_add_i32 s75, 0, 0x1c000
	v_add_u32_e32 v168, s74, v175
	v_add_u32_e32 v190, s75, v175
	ds_read_b128 v[154:157], v168
	ds_read_b128 v[158:161], v168 offset:1024
	ds_read_b128 v[164:167], v168 offset:2048
	ds_read_b128 v[168:171], v168 offset:3072
	ds_read_b128 v[178:181], v190
	ds_read_b128 v[182:185], v190 offset:1024
	ds_read_b128 v[186:189], v190 offset:2048
	ds_read_b128 v[190:193], v190 offset:3072
	s_add_u32 s34, s34, 0x20000
	s_addc_u32 s35, s35, 0
	s_mov_b32 m0, s47
	v_lshl_add_u64 v[236:237], s[34:35], 0, v[138:139]
	ds_read_b128 v[194:197], v177 offset:32768
	ds_read_b128 v[198:201], v177 offset:33792
	ds_read_b128 v[202:205], v177 offset:34816
	ds_read_b128 v[210:213], v177 offset:35840
	ds_read_b128 v[214:217], v177 offset:36864
	ds_read_b128 v[218:221], v177 offset:37888
	ds_read_b128 v[222:225], v177 offset:38912
	ds_read_b128 v[226:229], v177 offset:39936
	global_load_lds_dwordx4 v[236:237], off
	v_lshl_add_u64 v[236:237], s[34:35], 0, v[134:135]
	s_mov_b32 m0, s48
	s_nop 0
	global_load_lds_dwordx4 v[236:237], off
	s_waitcnt vmcnt(8)
	s_waitcnt lgkmcnt(0)
	s_waitcnt lgkmcnt(0)
	v_mfma_f32_16x16x32_bf16 v[124:127], v[154:157], v[194:197], v[124:127]
	v_mfma_f32_16x16x32_bf16 v[120:123], v[164:167], v[194:197], v[120:123]
	v_mfma_f32_16x16x32_bf16 v[116:119], v[154:157], v[202:205], v[116:119]
	v_mfma_f32_16x16x32_bf16 v[108:111], v[164:167], v[202:205], v[108:111]
	v_mfma_f32_16x16x32_bf16 v[100:103], v[154:157], v[214:217], v[100:103]
	v_mfma_f32_16x16x32_bf16 v[92:95], v[164:167], v[214:217], v[92:95]
	v_mfma_f32_16x16x32_bf16 v[84:87], v[154:157], v[222:225], v[84:87]
	v_mfma_f32_16x16x32_bf16 v[76:79], v[164:167], v[222:225], v[76:79]
	s_barrier
	s_setprio 1
	v_mfma_f32_16x16x32_bf16 v[124:127], v[158:161], v[198:201], v[124:127]
	v_mfma_f32_16x16x32_bf16 v[120:123], v[168:171], v[198:201], v[120:123]
	v_mfma_f32_16x16x32_bf16 v[116:119], v[158:161], v[210:213], v[116:119]
	v_mfma_f32_16x16x32_bf16 v[108:111], v[168:171], v[210:213], v[108:111]
	v_mfma_f32_16x16x32_bf16 v[100:103], v[158:161], v[218:221], v[100:103]
	v_mfma_f32_16x16x32_bf16 v[92:95], v[168:171], v[218:221], v[92:95]
	v_mfma_f32_16x16x32_bf16 v[84:87], v[158:161], v[226:229], v[84:87]
	v_mfma_f32_16x16x32_bf16 v[76:79], v[168:171], v[226:229], v[76:79]
	s_setprio 0
	s_setprio 1
	v_mfma_f32_16x16x32_bf16 v[112:115], v[178:181], v[194:197], v[112:115]
	v_mfma_f32_16x16x32_bf16 v[104:107], v[186:189], v[194:197], v[104:107]
	v_mfma_f32_16x16x32_bf16 v[96:99], v[178:181], v[202:205], v[96:99]
	v_mfma_f32_16x16x32_bf16 v[88:91], v[186:189], v[202:205], v[88:91]
	v_mfma_f32_16x16x32_bf16 v[80:83], v[178:181], v[214:217], v[80:83]
	v_mfma_f32_16x16x32_bf16 v[72:75], v[186:189], v[214:217], v[72:75]
	v_mfma_f32_16x16x32_bf16 v[68:71], v[178:181], v[222:225], v[68:71]
	v_mfma_f32_16x16x32_bf16 v[64:67], v[186:189], v[222:225], v[64:67]
	v_mfma_f32_16x16x32_bf16 v[112:115], v[182:185], v[198:201], v[112:115]
	v_mfma_f32_16x16x32_bf16 v[104:107], v[190:193], v[198:201], v[104:107]
	v_mfma_f32_16x16x32_bf16 v[96:99], v[182:185], v[210:213], v[96:99]
	v_mfma_f32_16x16x32_bf16 v[88:91], v[190:193], v[210:213], v[88:91]
	v_mfma_f32_16x16x32_bf16 v[80:83], v[182:185], v[218:221], v[80:83]
	v_mfma_f32_16x16x32_bf16 v[72:75], v[190:193], v[218:221], v[72:75]
	v_mfma_f32_16x16x32_bf16 v[68:71], v[182:185], v[226:229], v[68:71]
	v_mfma_f32_16x16x32_bf16 v[64:67], v[190:193], v[226:229], v[64:67]
	s_setprio 0
	s_barrier
; #define PG8_STAGE(bufoff, gbase, voff) do { _Pragma("unroll") for (int _i = 0; _i < 2; ++_i) \
;         __builtin_amdgcn_global_load_lds((const unsigned*)((const char*)(gbase) + (voff)[_i]), (PG8_LAS unsigned*)(lds + (bufoff) + ldsw + _i * 8192), 16, 0, 0); } while (0)
; #define PG8_LDA(dst, b, h) do { _Pragma("unroll") for (int m = 0; m < 4; ++m) _Pragma("unroll") for (int k = 0; k < 2; ++k) dst[m][k] = *(const PG8_LAS bf16x8*)(lds + PG8_SA(b, h) + aoff + m * 2048 + k * 1024); } while (0)
; #define PG8_MMA(ai, bj, At, Bt) do { __builtin_amdgcn_s_setprio(1); _Pragma("unroll") for (int m = 0; m < 4; ++m) _Pragma("unroll") for (int n = 0; n < 2; ++n) _Pragma("unroll") for (int k = 0; k < 2; ++k) \
;         acc[ai][bj][m][n] = __builtin_amdgcn_mfma_f32_16x16x32_bf16(Bt[n][k], At[m][k], acc[ai][bj][m][n], 0, 0, 0); __builtin_amdgcn_s_setprio(0); } while (0)
; #define PG8_WAIT_V(n) asm volatile("s_waitcnt vmcnt(" #n ")" ::: "memory")
; #define PG8_WAIT_L(n) asm volatile("s_waitcnt lgkmcnt(" #n ")" ::: "memory")
; #define PG8_BAR __builtin_amdgcn_s_barrier()
; #define PG8_SCHED __builtin_amdgcn_sched_barrier(0)
; template <class Epi, class Sched, bool ALIGN_EPI = false, bool SP2 = false>
; __device__ __forceinline__ void gemm_phase(PG8_LAS unsigned char* lds, const Gemm g, const Sched& S, const Epi& E) {
;     ...
;             PG8_LDA(At, 1, 1); PG8_STAGE(PG8_SB(1, 0), b3, voffB); PG8_STAGE(PG8_SB(1, 1), b3 + hstep, voffB); PG8_STAGE(PG8_SA(1, 0), a3, voffA);
;             PG8_WAIT_V(8); PG8_WAIT_L(0); PG8_BAR; PG8_MMA(1, 0, At, B0); PG8_MMA(1, 1, At, B1); PG8_BAR; PG8_SCHED;
;     ...
;         }
;         if constexpr (ALIGN_EPI) { if (wr == 0) PG8_BAR; }
	s_add_i32 s34, s74, s0
	v_lshl_add_u64 v[172:173], v[172:173], 0, s[12:13]
	s_mov_b32 m0, s34
	ds_read_b128 v[194:197], v177 offset:49152
	ds_read_b128 v[198:201], v177 offset:50176
	ds_read_b128 v[202:205], v177 offset:51200
	ds_read_b128 v[210:213], v177 offset:52224
	ds_read_b128 v[214:217], v177 offset:53248
	ds_read_b128 v[218:221], v177 offset:54272
	ds_read_b128 v[222:225], v177 offset:55296
	ds_read_b128 v[226:229], v177 offset:56320
	global_load_lds_dwordx4 v[172:173], off
	s_add_i32 m0, s34, 0x2000
	s_add_u32 s30, s30, 0x20080
	v_lshl_add_u64 v[172:173], v[206:207], 0, s[12:13]
	s_addc_u32 s31, s31, 0
	s_add_i32 s34, s75, s0
	global_load_lds_dwordx4 v[172:173], off
	v_lshl_add_u64 v[172:173], s[30:31], 0, v[136:137]
	s_mov_b32 m0, s34
	s_nop 0
	global_load_lds_dwordx4 v[172:173], off
	v_lshl_add_u64 v[172:173], s[30:31], 0, v[132:133]
	s_add_i32 m0, s34, 0x2000
	s_nop 0
	global_load_lds_dwordx4 v[172:173], off
	v_lshl_add_u64 v[172:173], v[230:231], 0, s[12:13]
	s_mov_b32 m0, s49
	s_nop 0
	global_load_lds_dwordx4 v[172:173], off
	v_lshl_add_u64 v[172:173], v[234:235], 0, s[12:13]
	s_mov_b32 m0, s50
	s_nop 0
	global_load_lds_dwordx4 v[172:173], off
	s_waitcnt vmcnt(8)
	s_waitcnt lgkmcnt(0)
	s_waitcnt lgkmcnt(0)
	v_mfma_f32_16x16x32_bf16 v[60:63], v[154:157], v[194:197], v[60:63]
	v_mfma_f32_16x16x32_bf16 v[56:59], v[164:167], v[194:197], v[56:59]
	v_mfma_f32_16x16x32_bf16 v[52:55], v[154:157], v[202:205], v[52:55]
	v_mfma_f32_16x16x32_bf16 v[44:47], v[164:167], v[202:205], v[44:47]
	v_mfma_f32_16x16x32_bf16 v[36:39], v[154:157], v[214:217], v[36:39]
	v_mfma_f32_16x16x32_bf16 v[28:31], v[164:167], v[214:217], v[28:31]
	v_mfma_f32_16x16x32_bf16 v[20:23], v[154:157], v[222:225], v[20:23]
	v_mfma_f32_16x16x32_bf16 v[12:15], v[164:167], v[222:225], v[12:15]
	s_barrier
	s_setprio 1
	v_mfma_f32_16x16x32_bf16 v[60:63], v[158:161], v[198:201], v[60:63]
	v_mfma_f32_16x16x32_bf16 v[56:59], v[168:171], v[198:201], v[56:59]
	v_mfma_f32_16x16x32_bf16 v[52:55], v[158:161], v[210:213], v[52:55]
	v_mfma_f32_16x16x32_bf16 v[44:47], v[168:171], v[210:213], v[44:47]
	v_mfma_f32_16x16x32_bf16 v[36:39], v[158:161], v[218:221], v[36:39]
	v_mfma_f32_16x16x32_bf16 v[28:31], v[168:171], v[218:221], v[28:31]
	v_mfma_f32_16x16x32_bf16 v[20:23], v[158:161], v[226:229], v[20:23]
	v_mfma_f32_16x16x32_bf16 v[12:15], v[168:171], v[226:229], v[12:15]
	s_setprio 0
	s_setprio 1
	v_mfma_f32_16x16x32_bf16 v[48:51], v[178:181], v[194:197], v[48:51]
	v_mfma_f32_16x16x32_bf16 v[40:43], v[186:189], v[194:197], v[40:43]
	v_mfma_f32_16x16x32_bf16 v[32:35], v[178:181], v[202:205], v[32:35]
	v_mfma_f32_16x16x32_bf16 v[24:27], v[186:189], v[202:205], v[24:27]
	v_mfma_f32_16x16x32_bf16 v[16:19], v[178:181], v[214:217], v[16:19]
	v_mfma_f32_16x16x32_bf16 v[8:11], v[186:189], v[214:217], v[8:11]
	v_mfma_f32_16x16x32_bf16 v[4:7], v[178:181], v[222:225], v[4:7]
	v_mfma_f32_16x16x32_bf16 v[0:3], v[186:189], v[222:225], v[0:3]
	v_mfma_f32_16x16x32_bf16 v[48:51], v[182:185], v[198:201], v[48:51]
	v_mfma_f32_16x16x32_bf16 v[40:43], v[190:193], v[198:201], v[40:43]
	v_mfma_f32_16x16x32_bf16 v[32:35], v[182:185], v[210:213], v[32:35]
	v_mfma_f32_16x16x32_bf16 v[24:27], v[190:193], v[210:213], v[24:27]
	v_mfma_f32_16x16x32_bf16 v[16:19], v[182:185], v[218:221], v[16:19]
	v_mfma_f32_16x16x32_bf16 v[8:11], v[190:193], v[218:221], v[8:11]
	v_mfma_f32_16x16x32_bf16 v[4:7], v[182:185], v[226:229], v[4:7]
	v_mfma_f32_16x16x32_bf16 v[0:3], v[190:193], v[226:229], v[0:3]
	s_setprio 0
	s_barrier
	s_add_i32 s73, s73, 2
	s_add_u32 s28, s28, 0x100
	s_addc_u32 s29, s29, 0
	s_add_u32 s71, s71, 0x100
	s_addc_u32 s72, s72, 0
	s_cmp_gt_u32 s73, 5
	s_cbranch_scc0 .LBB0_997
	s_and_b64 vcc, exec, s[14:15]
	s_cbranch_vccz .LBB0_1000
	s_barrier

; #define PG8_STAGE(bufoff, gbase, voff) do { _Pragma("unroll") for (int _i = 0; _i < 2; ++_i) \
;         __builtin_amdgcn_global_load_lds((const unsigned*)((const char*)(gbase) + (voff)[_i]), (PG8_LAS unsigned*)(lds + (bufoff) + ldsw + _i * 8192), 16, 0, 0); } while (0)
; #define PG8_LDA(dst, b, h) do { _Pragma("unroll") for (int m = 0; m < 4; ++m) _Pragma("unroll") for (int k = 0; k < 2; ++k) dst[m][k] = *(const PG8_LAS bf16x8*)(lds + PG8_SA(b, h) + aoff + m * 2048 + k * 1024); } while (0)
; #define PG8_LDB(dst, b, h) do { _Pragma("unroll") for (int n = 0; n < 2; ++n) _Pragma("unroll") for (int k = 0; k < 2; ++k) dst[n][k] = *(const PG8_LAS bf16x8*)(lds + PG8_SB(b, h) + boff + n * 2048 + k * 1024); } while (0)
; #define PG8_MMA(ai, bj, At, Bt) do { __builtin_amdgcn_s_setprio(1); _Pragma("unroll") for (int m = 0; m < 4; ++m) _Pragma("unroll") for (int n = 0; n < 2; ++n) _Pragma("unroll") for (int k = 0; k < 2; ++k) \
;         acc[ai][bj][m][n] = __builtin_amdgcn_mfma_f32_16x16x32_bf16(Bt[n][k], At[m][k], acc[ai][bj][m][n], 0, 0, 0); __builtin_amdgcn_s_setprio(0); } while (0)
; #define PG8_WAIT_V(n) asm volatile("s_waitcnt vmcnt(" #n ")" ::: "memory")
; #define PG8_WAIT_L(n) asm volatile("s_waitcnt lgkmcnt(" #n ")" ::: "memory")
; #define PG8_BAR __builtin_amdgcn_s_barrier()
; #define PG8_SCHED __builtin_amdgcn_sched_barrier(0)
; template <class Epi, class Sched, bool ALIGN_EPI = false, bool SP2 = false>
; __device__ __forceinline__ void gemm_phase(PG8_LAS unsigned char* lds, const Gemm g, const Sched& S, const Epi& E) {
;     ...
;             const char* a2 = last ? nA : cA + (size_t)(t + 2) * kstep; const char* b2 = last ? nB : cB + (size_t)(t + 2) * kstep;
;             const char* a3 = a2 + kstep; const char* b3 = b2 + kstep;
;             if (last && has_next) S.a_ready(nxt);
;             if constexpr (SP2) {
;             PG8_LDB(B0, 0, 0); PG8_LDB(B1, 0, 1); PG8_SCHED; PG8_LDA(At, 0, 0); PG8_STAGE(PG8_SA(1, 1), a1 + hstep, voffA);
;             PG8_WAIT_V(8); PG8_WAIT_L(0); PG8_BAR; PG8_MMA(0, 0, At, B0); PG8_MMA(0, 1, At, B1); PG8_BAR; PG8_SCHED;
;             PG8_LDA(At, 0, 1); PG8_STAGE(PG8_SB(0, 0), b2, voffB); PG8_STAGE(PG8_SB(0, 1), b2 + hstep, voffB); PG8_STAGE(PG8_SA(0, 0), a2, voffA);
;             PG8_WAIT_V(8); PG8_WAIT_L(0); PG8_BAR; PG8_MMA(1, 0, At, B0); PG8_MMA(1, 1, At, B1); PG8_BAR; PG8_SCHED;
.LBB0_1017:
	ds_read_b128 v[152:155], v149
	ds_read_b128 v[156:159], v149 offset:1024
	ds_read_b128 v[164:167], v149 offset:2048
	ds_read_b128 v[168:171], v149 offset:3072
	ds_read_b128 v[172:175], v150
	ds_read_b128 v[176:179], v150 offset:1024
	ds_read_b128 v[180:183], v150 offset:2048
	ds_read_b128 v[184:187], v150 offset:3072
	s_add_u32 s64, s38, 0xfffe0080
	s_addc_u32 s65, s39, -1
	s_cmp_eq_u32 s80, 4
	s_cselect_b32 s67, s27, s65
	s_cselect_b32 s66, s76, s64
	s_cselect_b32 s65, s25, s79
	s_cselect_b32 s64, s77, s78
	v_lshl_add_u64 v[144:145], s[38:39], 0, v[128:129]
	s_add_i32 m0, s35, 0xc000
	ds_read_b128 v[188:191], v151
	ds_read_b128 v[192:195], v151 offset:1024
	ds_read_b128 v[196:199], v151 offset:2048
	ds_read_b128 v[200:203], v151 offset:3072
	ds_read_b128 v[204:207], v151 offset:4096
	ds_read_b128 v[210:213], v151 offset:5120
	ds_read_b128 v[214:217], v151 offset:6144
	ds_read_b128 v[218:221], v151 offset:7168
	global_load_lds_dwordx4 v[144:145], off
	v_lshl_add_u64 v[144:145], s[38:39], 0, v[130:131]
	s_add_i32 m0, s35, 0xe000
	s_nop 0
	global_load_lds_dwordx4 v[144:145], off
	s_waitcnt vmcnt(8)
	s_waitcnt lgkmcnt(0)
	s_waitcnt lgkmcnt(0)
	v_mfma_f32_16x16x32_bf16 v[124:127], v[152:155], v[188:191], v[124:127]
	v_mfma_f32_16x16x32_bf16 v[120:123], v[164:167], v[188:191], v[120:123]
	v_mfma_f32_16x16x32_bf16 v[116:119], v[152:155], v[196:199], v[116:119]
	v_mfma_f32_16x16x32_bf16 v[108:111], v[164:167], v[196:199], v[108:111]
	v_mfma_f32_16x16x32_bf16 v[100:103], v[152:155], v[204:207], v[100:103]
	v_mfma_f32_16x16x32_bf16 v[92:95], v[164:167], v[204:207], v[92:95]
	v_mfma_f32_16x16x32_bf16 v[84:87], v[152:155], v[214:217], v[84:87]
	v_mfma_f32_16x16x32_bf16 v[76:79], v[164:167], v[214:217], v[76:79]
	s_barrier
	s_setprio 1
	v_mfma_f32_16x16x32_bf16 v[124:127], v[156:159], v[192:195], v[124:127]
	v_mfma_f32_16x16x32_bf16 v[120:123], v[168:171], v[192:195], v[120:123]
	v_mfma_f32_16x16x32_bf16 v[116:119], v[156:159], v[200:203], v[116:119]
	v_mfma_f32_16x16x32_bf16 v[108:111], v[168:171], v[200:203], v[108:111]
	v_mfma_f32_16x16x32_bf16 v[100:103], v[156:159], v[210:213], v[100:103]
	v_mfma_f32_16x16x32_bf16 v[92:95], v[168:171], v[210:213], v[92:95]
	v_mfma_f32_16x16x32_bf16 v[84:87], v[156:159], v[218:221], v[84:87]
	v_mfma_f32_16x16x32_bf16 v[76:79], v[168:171], v[218:221], v[76:79]
	s_setprio 0
	s_setprio 1
	v_mfma_f32_16x16x32_bf16 v[112:115], v[172:175], v[188:191], v[112:115]
	v_mfma_f32_16x16x32_bf16 v[104:107], v[180:183], v[188:191], v[104:107]
	v_mfma_f32_16x16x32_bf16 v[96:99], v[172:175], v[196:199], v[96:99]
	v_mfma_f32_16x16x32_bf16 v[88:91], v[180:183], v[196:199], v[88:91]
	v_mfma_f32_16x16x32_bf16 v[80:83], v[172:175], v[204:207], v[80:83]
	v_mfma_f32_16x16x32_bf16 v[72:75], v[180:183], v[204:207], v[72:75]
	v_mfma_f32_16x16x32_bf16 v[68:71], v[172:175], v[214:217], v[68:71]
	v_mfma_f32_16x16x32_bf16 v[64:67], v[180:183], v[214:217], v[64:67]
	v_mfma_f32_16x16x32_bf16 v[112:115], v[176:179], v[192:195], v[112:115]
	v_mfma_f32_16x16x32_bf16 v[104:107], v[184:187], v[192:195], v[104:107]
	v_mfma_f32_16x16x32_bf16 v[96:99], v[176:179], v[200:203], v[96:99]
	v_mfma_f32_16x16x32_bf16 v[88:91], v[184:187], v[200:203], v[88:91]
	v_mfma_f32_16x16x32_bf16 v[80:83], v[176:179], v[210:213], v[80:83]
	v_mfma_f32_16x16x32_bf16 v[72:75], v[184:187], v[210:213], v[72:75]
	v_mfma_f32_16x16x32_bf16 v[68:71], v[176:179], v[218:221], v[68:71]
	v_mfma_f32_16x16x32_bf16 v[64:67], v[184:187], v[218:221], v[64:67]
	s_setprio 0
	s_barrier
	s_add_i32 s81, s69, s0
	v_lshl_add_u64 v[144:145], s[64:65], 0, v[136:137]
	s_mov_b32 m0, s81
	ds_read_b128 v[188:191], v151 offset:16384
	ds_read_b128 v[192:195], v151 offset:17408
	ds_read_b128 v[196:199], v151 offset:18432
	ds_read_b128 v[200:203], v151 offset:19456
	ds_read_b128 v[204:207], v151 offset:20480
	ds_read_b128 v[210:213], v151 offset:21504
	ds_read_b128 v[214:217], v151 offset:22528
	ds_read_b128 v[218:221], v151 offset:23552
	global_load_lds_dwordx4 v[144:145], off
	s_add_i32 m0, s81, 0x2000
	s_add_u32 s82, s64, 0x20000
	v_lshl_add_u64 v[160:161], s[64:65], 0, v[132:133]
	s_addc_u32 s83, s65, 0
	s_add_i32 s81, s70, s0
	global_load_lds_dwordx4 v[160:161], off
	v_lshl_add_u64 v[222:223], s[82:83], 0, v[136:137]
	s_mov_b32 m0, s81
	v_lshl_add_u64 v[224:225], s[66:67], 0, v[134:135]
	global_load_lds_dwordx4 v[222:223], off
	v_lshl_add_u64 v[222:223], s[82:83], 0, v[132:133]
	s_add_i32 m0, s81, 0x2000
	s_nop 0
	global_load_lds_dwordx4 v[222:223], off
	v_lshl_add_u64 v[222:223], s[66:67], 0, v[138:139]
	s_mov_b32 m0, s35
	s_nop 0
	global_load_lds_dwordx4 v[222:223], off
	s_mov_b32 m0, s47
	s_nop 0
	global_load_lds_dwordx4 v[224:225], off
	s_waitcnt vmcnt(8)
	s_waitcnt lgkmcnt(0)
	s_waitcnt lgkmcnt(0)
	v_mfma_f32_16x16x32_bf16 v[60:63], v[152:155], v[188:191], v[60:63]
	v_mfma_f32_16x16x32_bf16 v[56:59], v[164:167], v[188:191], v[56:59]
	v_mfma_f32_16x16x32_bf16 v[52:55], v[152:155], v[196:199], v[52:55]
	v_mfma_f32_16x16x32_bf16 v[44:47], v[164:167], v[196:199], v[44:47]
	v_mfma_f32_16x16x32_bf16 v[36:39], v[152:155], v[204:207], v[36:39]
	v_mfma_f32_16x16x32_bf16 v[28:31], v[164:167], v[204:207], v[28:31]
	v_mfma_f32_16x16x32_bf16 v[20:23], v[152:155], v[214:217], v[20:23]
	v_mfma_f32_16x16x32_bf16 v[12:15], v[164:167], v[214:217], v[12:15]
	s_barrier
; #define PG8_STAGE(bufoff, gbase, voff) do { _Pragma("unroll") for (int _i = 0; _i < 2; ++_i) \
;         __builtin_amdgcn_global_load_lds((const unsigned*)((const char*)(gbase) + (voff)[_i]), (PG8_LAS unsigned*)(lds + (bufoff) + ldsw + _i * 8192), 16, 0, 0); } while (0)
; #define PG8_LDA(dst, b, h) do { _Pragma("unroll") for (int m = 0; m < 4; ++m) _Pragma("unroll") for (int k = 0; k < 2; ++k) dst[m][k] = *(const PG8_LAS bf16x8*)(lds + PG8_SA(b, h) + aoff + m * 2048 + k * 1024); } while (0)
; #define PG8_LDB(dst, b, h) do { _Pragma("unroll") for (int n = 0; n < 2; ++n) _Pragma("unroll") for (int k = 0; k < 2; ++k) dst[n][k] = *(const PG8_LAS bf16x8*)(lds + PG8_SB(b, h) + boff + n * 2048 + k * 1024); } while (0)
; #define PG8_MMA(ai, bj, At, Bt) do { __builtin_amdgcn_s_setprio(1); _Pragma("unroll") for (int m = 0; m < 4; ++m) _Pragma("unroll") for (int n = 0; n < 2; ++n) _Pragma("unroll") for (int k = 0; k < 2; ++k) \
;         acc[ai][bj][m][n] = __builtin_amdgcn_mfma_f32_16x16x32_bf16(Bt[n][k], At[m][k], acc[ai][bj][m][n], 0, 0, 0); __builtin_amdgcn_s_setprio(0); } while (0)
; #define PG8_WAIT_V(n) asm volatile("s_waitcnt vmcnt(" #n ")" ::: "memory")
; #define PG8_WAIT_L(n) asm volatile("s_waitcnt lgkmcnt(" #n ")" ::: "memory")
; #define PG8_BAR __builtin_amdgcn_s_barrier()
; #define PG8_SCHED __builtin_amdgcn_sched_barrier(0)
; template <class Epi, class Sched, bool ALIGN_EPI = false, bool SP2 = false>
; __device__ __forceinline__ void gemm_phase(PG8_LAS unsigned char* lds, const Gemm g, const Sched& S, const Epi& E) {
;     ...
;             PG8_WAIT_V(8); PG8_WAIT_L(0); PG8_BAR; PG8_MMA(1, 0, At, B0); PG8_MMA(1, 1, At, B1); PG8_BAR; PG8_SCHED;
;             PG8_LDB(B0, 1, 0); PG8_LDB(B1, 1, 1); PG8_SCHED; PG8_LDA(At, 1, 0); PG8_STAGE(PG8_SA(0, 1), a2 + hstep, voffA);
;             PG8_WAIT_V(8); PG8_WAIT_L(0); PG8_BAR; PG8_MMA(0, 0, At, B0); PG8_MMA(0, 1, At, B1); PG8_BAR; PG8_SCHED;
	s_setprio 1
	v_mfma_f32_16x16x32_bf16 v[60:63], v[156:159], v[192:195], v[60:63]
	v_mfma_f32_16x16x32_bf16 v[56:59], v[168:171], v[192:195], v[56:59]
	v_mfma_f32_16x16x32_bf16 v[52:55], v[156:159], v[200:203], v[52:55]
	v_mfma_f32_16x16x32_bf16 v[44:47], v[168:171], v[200:203], v[44:47]
	v_mfma_f32_16x16x32_bf16 v[36:39], v[156:159], v[210:213], v[36:39]
	v_mfma_f32_16x16x32_bf16 v[28:31], v[168:171], v[210:213], v[28:31]
	v_mfma_f32_16x16x32_bf16 v[20:23], v[156:159], v[218:221], v[20:23]
	v_mfma_f32_16x16x32_bf16 v[12:15], v[168:171], v[218:221], v[12:15]
	s_setprio 0
	s_setprio 1
	v_mfma_f32_16x16x32_bf16 v[48:51], v[172:175], v[188:191], v[48:51]
	v_mfma_f32_16x16x32_bf16 v[40:43], v[180:183], v[188:191], v[40:43]
	v_mfma_f32_16x16x32_bf16 v[32:35], v[172:175], v[196:199], v[32:35]
	v_mfma_f32_16x16x32_bf16 v[24:27], v[180:183], v[196:199], v[24:27]
	v_mfma_f32_16x16x32_bf16 v[16:19], v[172:175], v[204:207], v[16:19]
	v_mfma_f32_16x16x32_bf16 v[8:11], v[180:183], v[204:207], v[8:11]
	v_mfma_f32_16x16x32_bf16 v[4:7], v[172:175], v[214:217], v[4:7]
	v_mfma_f32_16x16x32_bf16 v[0:3], v[180:183], v[214:217], v[0:3]
	v_mfma_f32_16x16x32_bf16 v[48:51], v[176:179], v[192:195], v[48:51]
	v_mfma_f32_16x16x32_bf16 v[40:43], v[184:187], v[192:195], v[40:43]
	v_mfma_f32_16x16x32_bf16 v[32:35], v[176:179], v[200:203], v[32:35]
	v_mfma_f32_16x16x32_bf16 v[24:27], v[184:187], v[200:203], v[24:27]
	v_mfma_f32_16x16x32_bf16 v[16:19], v[176:179], v[210:213], v[16:19]
	v_mfma_f32_16x16x32_bf16 v[8:11], v[184:187], v[210:213], v[8:11]
	v_mfma_f32_16x16x32_bf16 v[4:7], v[176:179], v[218:221], v[4:7]
	v_mfma_f32_16x16x32_bf16 v[0:3], v[184:187], v[218:221], v[0:3]
	s_setprio 0
	s_barrier
	s_add_i32 s81, 0, 0x18000
	v_add_u32_e32 v163, s81, v147
	s_add_i32 s82, 0, 0x1c000
	ds_read_b128 v[152:155], v163
	ds_read_b128 v[156:159], v163 offset:1024
	ds_read_b128 v[164:167], v163 offset:2048
	ds_read_b128 v[168:171], v163 offset:3072
	v_add_u32_e32 v163, s82, v147
	ds_read_b128 v[172:175], v163
	ds_read_b128 v[176:179], v163 offset:1024
	ds_read_b128 v[180:183], v163 offset:2048
	ds_read_b128 v[184:187], v163 offset:3072
	s_add_u32 s66, s66, 0x20000
	s_addc_u32 s67, s67, 0
	s_mov_b32 m0, s48
	v_lshl_add_u64 v[226:227], s[66:67], 0, v[138:139]
	ds_read_b128 v[188:191], v151 offset:32768
	ds_read_b128 v[192:195], v151 offset:33792
	ds_read_b128 v[196:199], v151 offset:34816
	ds_read_b128 v[200:203], v151 offset:35840
	ds_read_b128 v[204:207], v151 offset:36864
	ds_read_b128 v[210:213], v151 offset:37888
	ds_read_b128 v[214:217], v151 offset:38912
	ds_read_b128 v[218:221], v151 offset:39936
	global_load_lds_dwordx4 v[226:227], off
	v_lshl_add_u64 v[226:227], s[66:67], 0, v[134:135]
	s_mov_b32 m0, s49
	s_nop 0
	global_load_lds_dwordx4 v[226:227], off
	s_waitcnt vmcnt(8)
	s_waitcnt lgkmcnt(0)
	s_waitcnt lgkmcnt(0)
	v_mfma_f32_16x16x32_bf16 v[124:127], v[152:155], v[188:191], v[124:127]
	v_mfma_f32_16x16x32_bf16 v[120:123], v[164:167], v[188:191], v[120:123]
	v_mfma_f32_16x16x32_bf16 v[116:119], v[152:155], v[196:199], v[116:119]
	v_mfma_f32_16x16x32_bf16 v[108:111], v[164:167], v[196:199], v[108:111]
	v_mfma_f32_16x16x32_bf16 v[100:103], v[152:155], v[204:207], v[100:103]
	v_mfma_f32_16x16x32_bf16 v[92:95], v[164:167], v[204:207], v[92:95]
	v_mfma_f32_16x16x32_bf16 v[84:87], v[152:155], v[214:217], v[84:87]
	v_mfma_f32_16x16x32_bf16 v[76:79], v[164:167], v[214:217], v[76:79]
	s_barrier
	s_setprio 1
	v_mfma_f32_16x16x32_bf16 v[124:127], v[156:159], v[192:195], v[124:127]
	v_mfma_f32_16x16x32_bf16 v[120:123], v[168:171], v[192:195], v[120:123]
	v_mfma_f32_16x16x32_bf16 v[116:119], v[156:159], v[200:203], v[116:119]
	v_mfma_f32_16x16x32_bf16 v[108:111], v[168:171], v[200:203], v[108:111]
	v_mfma_f32_16x16x32_bf16 v[100:103], v[156:159], v[210:213], v[100:103]
	v_mfma_f32_16x16x32_bf16 v[92:95], v[168:171], v[210:213], v[92:95]
	v_mfma_f32_16x16x32_bf16 v[84:87], v[156:159], v[218:221], v[84:87]
	v_mfma_f32_16x16x32_bf16 v[76:79], v[168:171], v[218:221], v[76:79]
	s_setprio 0
	s_setprio 1
	v_mfma_f32_16x16x32_bf16 v[112:115], v[172:175], v[188:191], v[112:115]
	v_mfma_f32_16x16x32_bf16 v[104:107], v[180:183], v[188:191], v[104:107]
	v_mfma_f32_16x16x32_bf16 v[96:99], v[172:175], v[196:199], v[96:99]
	v_mfma_f32_16x16x32_bf16 v[88:91], v[180:183], v[196:199], v[88:91]
	v_mfma_f32_16x16x32_bf16 v[80:83], v[172:175], v[204:207], v[80:83]
	v_mfma_f32_16x16x32_bf16 v[72:75], v[180:183], v[204:207], v[72:75]
	v_mfma_f32_16x16x32_bf16 v[68:71], v[172:175], v[214:217], v[68:71]
	v_mfma_f32_16x16x32_bf16 v[64:67], v[180:183], v[214:217], v[64:67]
	v_mfma_f32_16x16x32_bf16 v[112:115], v[176:179], v[192:195], v[112:115]
	v_mfma_f32_16x16x32_bf16 v[104:107], v[184:187], v[192:195], v[104:107]
	v_mfma_f32_16x16x32_bf16 v[96:99], v[176:179], v[200:203], v[96:99]
	v_mfma_f32_16x16x32_bf16 v[88:91], v[184:187], v[200:203], v[88:91]
	v_mfma_f32_16x16x32_bf16 v[80:83], v[176:179], v[210:213], v[80:83]
	v_mfma_f32_16x16x32_bf16 v[72:75], v[184:187], v[210:213], v[72:75]
	v_mfma_f32_16x16x32_bf16 v[68:71], v[176:179], v[218:221], v[68:71]
	v_mfma_f32_16x16x32_bf16 v[64:67], v[184:187], v[218:221], v[64:67]
	s_setprio 0
	s_barrier
; #define PG8_STAGE(bufoff, gbase, voff) do { _Pragma("unroll") for (int _i = 0; _i < 2; ++_i) \
;         __builtin_amdgcn_global_load_lds((const unsigned*)((const char*)(gbase) + (voff)[_i]), (PG8_LAS unsigned*)(lds + (bufoff) + ldsw + _i * 8192), 16, 0, 0); } while (0)
; #define PG8_LDA(dst, b, h) do { _Pragma("unroll") for (int m = 0; m < 4; ++m) _Pragma("unroll") for (int k = 0; k < 2; ++k) dst[m][k] = *(const PG8_LAS bf16x8*)(lds + PG8_SA(b, h) + aoff + m * 2048 + k * 1024); } while (0)
; #define PG8_MMA(ai, bj, At, Bt) do { __builtin_amdgcn_s_setprio(1); _Pragma("unroll") for (int m = 0; m < 4; ++m) _Pragma("unroll") for (int n = 0; n < 2; ++n) _Pragma("unroll") for (int k = 0; k < 2; ++k) \
;         acc[ai][bj][m][n] = __builtin_amdgcn_mfma_f32_16x16x32_bf16(Bt[n][k], At[m][k], acc[ai][bj][m][n], 0, 0, 0); __builtin_amdgcn_s_setprio(0); } while (0)
; #define PG8_WAIT_V(n) asm volatile("s_waitcnt vmcnt(" #n ")" ::: "memory")
; #define PG8_WAIT_L(n) asm volatile("s_waitcnt lgkmcnt(" #n ")" ::: "memory")
; #define PG8_BAR __builtin_amdgcn_s_barrier()
; #define PG8_SCHED __builtin_amdgcn_sched_barrier(0)
; template <class Epi, class Sched, bool ALIGN_EPI = false, bool SP2 = false>
; __device__ __forceinline__ void gemm_phase(PG8_LAS unsigned char* lds, const Gemm g, const Sched& S, const Epi& E) {
;     ...
;             PG8_LDA(At, 1, 1); PG8_STAGE(PG8_SB(1, 0), b3, voffB); PG8_STAGE(PG8_SB(1, 1), b3 + hstep, voffB); PG8_STAGE(PG8_SA(1, 0), a3, voffA);
;             PG8_WAIT_V(8); PG8_WAIT_L(0); PG8_BAR; PG8_MMA(1, 0, At, B0); PG8_MMA(1, 1, At, B1); PG8_BAR; PG8_SCHED;
	s_add_i32 s66, s81, s0
	v_lshl_add_u64 v[144:145], v[144:145], 0, s[10:11]
	s_mov_b32 m0, s66
	ds_read_b128 v[188:191], v151 offset:49152
	ds_read_b128 v[192:195], v151 offset:50176
	ds_read_b128 v[196:199], v151 offset:51200
	ds_read_b128 v[200:203], v151 offset:52224
	ds_read_b128 v[204:207], v151 offset:53248
	ds_read_b128 v[210:213], v151 offset:54272
	ds_read_b128 v[214:217], v151 offset:55296
	ds_read_b128 v[218:221], v151 offset:56320
	global_load_lds_dwordx4 v[144:145], off
	s_add_i32 m0, s66, 0x2000
	s_add_u32 s64, s64, 0x20080
	v_lshl_add_u64 v[144:145], v[160:161], 0, s[10:11]
	s_addc_u32 s65, s65, 0
	s_add_i32 s66, s82, s0
	global_load_lds_dwordx4 v[144:145], off
	v_lshl_add_u64 v[144:145], s[64:65], 0, v[136:137]
	s_mov_b32 m0, s66
	s_nop 0
	global_load_lds_dwordx4 v[144:145], off
	v_lshl_add_u64 v[144:145], s[64:65], 0, v[132:133]
	s_add_i32 m0, s66, 0x2000
	s_nop 0
	global_load_lds_dwordx4 v[144:145], off
	v_lshl_add_u64 v[144:145], v[222:223], 0, s[10:11]
	s_mov_b32 m0, s51
	s_nop 0
	global_load_lds_dwordx4 v[144:145], off
	v_lshl_add_u64 v[144:145], v[224:225], 0, s[10:11]
	s_mov_b32 m0, s56
	s_nop 0
	global_load_lds_dwordx4 v[144:145], off
	s_waitcnt vmcnt(8)
	s_waitcnt lgkmcnt(0)
	s_waitcnt lgkmcnt(0)
	v_mfma_f32_16x16x32_bf16 v[60:63], v[152:155], v[188:191], v[60:63]
	v_mfma_f32_16x16x32_bf16 v[56:59], v[164:167], v[188:191], v[56:59]
	v_mfma_f32_16x16x32_bf16 v[52:55], v[152:155], v[196:199], v[52:55]
	v_mfma_f32_16x16x32_bf16 v[44:47], v[164:167], v[196:199], v[44:47]
	v_mfma_f32_16x16x32_bf16 v[36:39], v[152:155], v[204:207], v[36:39]
	v_mfma_f32_16x16x32_bf16 v[28:31], v[164:167], v[204:207], v[28:31]
	v_mfma_f32_16x16x32_bf16 v[20:23], v[152:155], v[214:217], v[20:23]
	v_mfma_f32_16x16x32_bf16 v[12:15], v[164:167], v[214:217], v[12:15]
	s_barrier
	s_setprio 1
	v_mfma_f32_16x16x32_bf16 v[60:63], v[156:159], v[192:195], v[60:63]
	v_mfma_f32_16x16x32_bf16 v[56:59], v[168:171], v[192:195], v[56:59]
	v_mfma_f32_16x16x32_bf16 v[52:55], v[156:159], v[200:203], v[52:55]
	v_mfma_f32_16x16x32_bf16 v[44:47], v[168:171], v[200:203], v[44:47]
	v_mfma_f32_16x16x32_bf16 v[36:39], v[156:159], v[210:213], v[36:39]
	v_mfma_f32_16x16x32_bf16 v[28:31], v[168:171], v[210:213], v[28:31]
	v_mfma_f32_16x16x32_bf16 v[20:23], v[156:159], v[218:221], v[20:23]
	v_mfma_f32_16x16x32_bf16 v[12:15], v[168:171], v[218:221], v[12:15]
	s_setprio 0
	s_setprio 1
	v_mfma_f32_16x16x32_bf16 v[48:51], v[172:175], v[188:191], v[48:51]
	v_mfma_f32_16x16x32_bf16 v[40:43], v[180:183], v[188:191], v[40:43]
	v_mfma_f32_16x16x32_bf16 v[32:35], v[172:175], v[196:199], v[32:35]
	v_mfma_f32_16x16x32_bf16 v[24:27], v[180:183], v[196:199], v[24:27]
	v_mfma_f32_16x16x32_bf16 v[16:19], v[172:175], v[204:207], v[16:19]
	v_mfma_f32_16x16x32_bf16 v[8:11], v[180:183], v[204:207], v[8:11]
	v_mfma_f32_16x16x32_bf16 v[4:7], v[172:175], v[214:217], v[4:7]
	v_mfma_f32_16x16x32_bf16 v[0:3], v[180:183], v[214:217], v[0:3]
	v_mfma_f32_16x16x32_bf16 v[48:51], v[176:179], v[192:195], v[48:51]
	v_mfma_f32_16x16x32_bf16 v[40:43], v[184:187], v[192:195], v[40:43]
	v_mfma_f32_16x16x32_bf16 v[32:35], v[176:179], v[200:203], v[32:35]
	v_mfma_f32_16x16x32_bf16 v[24:27], v[184:187], v[200:203], v[24:27]
	v_mfma_f32_16x16x32_bf16 v[16:19], v[176:179], v[210:213], v[16:19]
	v_mfma_f32_16x16x32_bf16 v[8:11], v[184:187], v[210:213], v[8:11]
	v_mfma_f32_16x16x32_bf16 v[4:7], v[176:179], v[218:221], v[4:7]
	v_mfma_f32_16x16x32_bf16 v[0:3], v[184:187], v[218:221], v[0:3]
	s_setprio 0
	s_barrier
	s_add_i32 s80, s80, 2
	s_add_u32 s38, s38, 0x100
	s_addc_u32 s39, s39, 0
	s_add_u32 s78, s78, 0x100
	s_addc_u32 s79, s79, 0
	s_cmp_gt_u32 s80, 5
	s_cbranch_scc0 .LBB0_1017
	s_and_b64 vcc, exec, s[12:13]
	s_cbranch_vccz .LBB0_1020
	s_barrier

; #define PG8_STAGE(bufoff, gbase, voff) do { _Pragma("unroll") for (int _i = 0; _i < 2; ++_i) \
;         __builtin_amdgcn_global_load_lds((const unsigned*)((const char*)(gbase) + (voff)[_i]), (PG8_LAS unsigned*)(lds + (bufoff) + ldsw + _i * 8192), 16, 0, 0); } while (0)
; #define PG8_LDA(dst, b, h) do { _Pragma("unroll") for (int m = 0; m < 4; ++m) _Pragma("unroll") for (int k = 0; k < 2; ++k) dst[m][k] = *(const PG8_LAS bf16x8*)(lds + PG8_SA(b, h) + aoff + m * 2048 + k * 1024); } while (0)
; #define PG8_LDB(dst, b, h) do { _Pragma("unroll") for (int n = 0; n < 2; ++n) _Pragma("unroll") for (int k = 0; k < 2; ++k) dst[n][k] = *(const PG8_LAS bf16x8*)(lds + PG8_SB(b, h) + boff + n * 2048 + k * 1024); } while (0)
; #define PG8_MMA(ai, bj, At, Bt) do { __builtin_amdgcn_s_setprio(1); _Pragma("unroll") for (int m = 0; m < 4; ++m) _Pragma("unroll") for (int n = 0; n < 2; ++n) _Pragma("unroll") for (int k = 0; k < 2; ++k) \
;         acc[ai][bj][m][n] = __builtin_amdgcn_mfma_f32_16x16x32_bf16(Bt[n][k], At[m][k], acc[ai][bj][m][n], 0, 0, 0); __builtin_amdgcn_s_setprio(0); } while (0)
; #define PG8_WAIT_V(n) asm volatile("s_waitcnt vmcnt(" #n ")" ::: "memory")
; #define PG8_WAIT_L(n) asm volatile("s_waitcnt lgkmcnt(" #n ")" ::: "memory")
; #define PG8_BAR __builtin_amdgcn_s_barrier()
; #define PG8_SCHED __builtin_amdgcn_sched_barrier(0)
; template <class Epi, class Sched, bool ALIGN_EPI = false, bool SP2 = false>
; __device__ __forceinline__ void gemm_phase(PG8_LAS unsigned char* lds, const Gemm g, const Sched& S, const Epi& E) {
;     ...
;             const char* a2 = last ? nA : cA + (size_t)(t + 2) * kstep; const char* b2 = last ? nB : cB + (size_t)(t + 2) * kstep;
;             const char* a3 = a2 + kstep; const char* b3 = b2 + kstep;
;             if (last && has_next) S.a_ready(nxt);
;             if constexpr (SP2) {
;             PG8_LDB(B0, 0, 0); PG8_LDB(B1, 0, 1); PG8_SCHED; PG8_LDA(At, 0, 0); PG8_STAGE(PG8_SA(1, 1), a1 + hstep, voffA);
;             PG8_WAIT_V(8); PG8_WAIT_L(0); PG8_BAR; PG8_MMA(0, 0, At, B0); PG8_MMA(0, 1, At, B1); PG8_BAR; PG8_SCHED;
;             PG8_LDA(At, 0, 1); PG8_STAGE(PG8_SB(0, 0), b2, voffB); PG8_STAGE(PG8_SB(0, 1), b2 + hstep, voffB); PG8_STAGE(PG8_SA(0, 0), a2, voffA);
;             PG8_WAIT_V(8); PG8_WAIT_L(0); PG8_BAR; PG8_MMA(1, 0, At, B0); PG8_MMA(1, 1, At, B1); PG8_BAR; PG8_SCHED;
.LBB0_1189:
	ds_read_b128 v[152:155], v149
	ds_read_b128 v[156:159], v149 offset:1024
	ds_read_b128 v[164:167], v149 offset:2048
	ds_read_b128 v[168:171], v149 offset:3072
	ds_read_b128 v[172:175], v150
	ds_read_b128 v[176:179], v150 offset:1024
	ds_read_b128 v[180:183], v150 offset:2048
	ds_read_b128 v[184:187], v150 offset:3072
	s_add_u32 s38, s34, 0xfff80080
	s_addc_u32 s39, s35, -1
	s_cmp_eq_u32 s72, 28
	s_cselect_b32 s63, s25, s39
	s_cselect_b32 s62, s68, s38
	s_cselect_b32 s39, s23, s71
	s_cselect_b32 s38, s69, s70
	v_lshl_add_u64 v[144:145], s[34:35], 0, v[136:137]
	s_add_i32 m0, s3, 0xc000
	ds_read_b128 v[188:191], v151
	ds_read_b128 v[192:195], v151 offset:1024
	ds_read_b128 v[196:199], v151 offset:2048
	ds_read_b128 v[200:203], v151 offset:3072
	ds_read_b128 v[204:207], v151 offset:4096
	ds_read_b128 v[210:213], v151 offset:5120
	ds_read_b128 v[214:217], v151 offset:6144
	ds_read_b128 v[218:221], v151 offset:7168
	global_load_lds_dwordx4 v[144:145], off
	v_lshl_add_u64 v[144:145], s[34:35], 0, v[138:139]
	s_add_i32 m0, s3, 0xe000
	s_nop 0
	global_load_lds_dwordx4 v[144:145], off
	s_waitcnt vmcnt(8)
	s_waitcnt lgkmcnt(0)
	s_waitcnt lgkmcnt(0)
	v_mfma_f32_16x16x32_bf16 v[124:127], v[152:155], v[188:191], v[124:127]
	v_mfma_f32_16x16x32_bf16 v[120:123], v[164:167], v[188:191], v[120:123]
	v_mfma_f32_16x16x32_bf16 v[116:119], v[152:155], v[196:199], v[116:119]
	v_mfma_f32_16x16x32_bf16 v[108:111], v[164:167], v[196:199], v[108:111]
	v_mfma_f32_16x16x32_bf16 v[100:103], v[152:155], v[204:207], v[100:103]
	v_mfma_f32_16x16x32_bf16 v[92:95], v[164:167], v[204:207], v[92:95]
	v_mfma_f32_16x16x32_bf16 v[84:87], v[152:155], v[214:217], v[84:87]
	v_mfma_f32_16x16x32_bf16 v[76:79], v[164:167], v[214:217], v[76:79]
	s_barrier
	s_setprio 1
	v_mfma_f32_16x16x32_bf16 v[124:127], v[156:159], v[192:195], v[124:127]
	v_mfma_f32_16x16x32_bf16 v[120:123], v[168:171], v[192:195], v[120:123]
	v_mfma_f32_16x16x32_bf16 v[116:119], v[156:159], v[200:203], v[116:119]
	v_mfma_f32_16x16x32_bf16 v[108:111], v[168:171], v[200:203], v[108:111]
	v_mfma_f32_16x16x32_bf16 v[100:103], v[156:159], v[210:213], v[100:103]
	v_mfma_f32_16x16x32_bf16 v[92:95], v[168:171], v[210:213], v[92:95]
	v_mfma_f32_16x16x32_bf16 v[84:87], v[156:159], v[218:221], v[84:87]
	v_mfma_f32_16x16x32_bf16 v[76:79], v[168:171], v[218:221], v[76:79]
	s_setprio 0
	s_setprio 1
	v_mfma_f32_16x16x32_bf16 v[112:115], v[172:175], v[188:191], v[112:115]
	v_mfma_f32_16x16x32_bf16 v[104:107], v[180:183], v[188:191], v[104:107]
	v_mfma_f32_16x16x32_bf16 v[96:99], v[172:175], v[196:199], v[96:99]
	v_mfma_f32_16x16x32_bf16 v[88:91], v[180:183], v[196:199], v[88:91]
	v_mfma_f32_16x16x32_bf16 v[80:83], v[172:175], v[204:207], v[80:83]
	v_mfma_f32_16x16x32_bf16 v[72:75], v[180:183], v[204:207], v[72:75]
	v_mfma_f32_16x16x32_bf16 v[68:71], v[172:175], v[214:217], v[68:71]
	v_mfma_f32_16x16x32_bf16 v[64:67], v[180:183], v[214:217], v[64:67]
	v_mfma_f32_16x16x32_bf16 v[112:115], v[176:179], v[192:195], v[112:115]
	v_mfma_f32_16x16x32_bf16 v[104:107], v[184:187], v[192:195], v[104:107]
	v_mfma_f32_16x16x32_bf16 v[96:99], v[176:179], v[200:203], v[96:99]
	v_mfma_f32_16x16x32_bf16 v[88:91], v[184:187], v[200:203], v[88:91]
	v_mfma_f32_16x16x32_bf16 v[80:83], v[176:179], v[210:213], v[80:83]
	v_mfma_f32_16x16x32_bf16 v[72:75], v[184:187], v[210:213], v[72:75]
	v_mfma_f32_16x16x32_bf16 v[68:71], v[176:179], v[218:221], v[68:71]
	v_mfma_f32_16x16x32_bf16 v[64:67], v[184:187], v[218:221], v[64:67]
	s_setprio 0
	s_barrier
	s_add_i32 s73, s51, s0
	v_lshl_add_u64 v[144:145], s[38:39], 0, v[132:133]
	s_mov_b32 m0, s73
	ds_read_b128 v[188:191], v151 offset:16384
	ds_read_b128 v[192:195], v151 offset:17408
	ds_read_b128 v[196:199], v151 offset:18432
	ds_read_b128 v[200:203], v151 offset:19456
	ds_read_b128 v[204:207], v151 offset:20480
	ds_read_b128 v[210:213], v151 offset:21504
	ds_read_b128 v[214:217], v151 offset:22528
	ds_read_b128 v[218:221], v151 offset:23552
	global_load_lds_dwordx4 v[144:145], off
	s_add_i32 m0, s73, 0x2000
	s_add_u32 s74, s38, 0x80000
	v_lshl_add_u64 v[160:161], s[38:39], 0, v[128:129]
	s_addc_u32 s75, s39, 0
	s_add_i32 s73, s56, s0
	global_load_lds_dwordx4 v[160:161], off
	v_lshl_add_u64 v[222:223], s[74:75], 0, v[132:133]
	s_mov_b32 m0, s73
	v_lshl_add_u64 v[224:225], s[62:63], 0, v[130:131]
	global_load_lds_dwordx4 v[222:223], off
	v_lshl_add_u64 v[222:223], s[74:75], 0, v[128:129]
	s_add_i32 m0, s73, 0x2000
	s_nop 0
	global_load_lds_dwordx4 v[222:223], off
	v_lshl_add_u64 v[222:223], s[62:63], 0, v[134:135]
	s_mov_b32 m0, s3
	s_nop 0
	global_load_lds_dwordx4 v[222:223], off
	s_mov_b32 m0, s31
	s_nop 0
	global_load_lds_dwordx4 v[224:225], off
	s_waitcnt vmcnt(8)
	s_waitcnt lgkmcnt(0)
	s_waitcnt lgkmcnt(0)
	v_mfma_f32_16x16x32_bf16 v[60:63], v[152:155], v[188:191], v[60:63]
	v_mfma_f32_16x16x32_bf16 v[56:59], v[164:167], v[188:191], v[56:59]
	v_mfma_f32_16x16x32_bf16 v[52:55], v[152:155], v[196:199], v[52:55]
	v_mfma_f32_16x16x32_bf16 v[44:47], v[164:167], v[196:199], v[44:47]
	v_mfma_f32_16x16x32_bf16 v[36:39], v[152:155], v[204:207], v[36:39]
	v_mfma_f32_16x16x32_bf16 v[28:31], v[164:167], v[204:207], v[28:31]
	v_mfma_f32_16x16x32_bf16 v[20:23], v[152:155], v[214:217], v[20:23]
	v_mfma_f32_16x16x32_bf16 v[12:15], v[164:167], v[214:217], v[12:15]
	s_barrier
; #define PG8_STAGE(bufoff, gbase, voff) do { _Pragma("unroll") for (int _i = 0; _i < 2; ++_i) \
;         __builtin_amdgcn_global_load_lds((const unsigned*)((const char*)(gbase) + (voff)[_i]), (PG8_LAS unsigned*)(lds + (bufoff) + ldsw + _i * 8192), 16, 0, 0); } while (0)
; #define PG8_LDA(dst, b, h) do { _Pragma("unroll") for (int m = 0; m < 4; ++m) _Pragma("unroll") for (int k = 0; k < 2; ++k) dst[m][k] = *(const PG8_LAS bf16x8*)(lds + PG8_SA(b, h) + aoff + m * 2048 + k * 1024); } while (0)
; #define PG8_LDB(dst, b, h) do { _Pragma("unroll") for (int n = 0; n < 2; ++n) _Pragma("unroll") for (int k = 0; k < 2; ++k) dst[n][k] = *(const PG8_LAS bf16x8*)(lds + PG8_SB(b, h) + boff + n * 2048 + k * 1024); } while (0)
; #define PG8_MMA(ai, bj, At, Bt) do { __builtin_amdgcn_s_setprio(1); _Pragma("unroll") for (int m = 0; m < 4; ++m) _Pragma("unroll") for (int n = 0; n < 2; ++n) _Pragma("unroll") for (int k = 0; k < 2; ++k) \
;         acc[ai][bj][m][n] = __builtin_amdgcn_mfma_f32_16x16x32_bf16(Bt[n][k], At[m][k], acc[ai][bj][m][n], 0, 0, 0); __builtin_amdgcn_s_setprio(0); } while (0)
; #define PG8_WAIT_V(n) asm volatile("s_waitcnt vmcnt(" #n ")" ::: "memory")
; #define PG8_WAIT_L(n) asm volatile("s_waitcnt lgkmcnt(" #n ")" ::: "memory")
; #define PG8_BAR __builtin_amdgcn_s_barrier()
; #define PG8_SCHED __builtin_amdgcn_sched_barrier(0)
; template <class Epi, class Sched, bool ALIGN_EPI = false, bool SP2 = false>
; __device__ __forceinline__ void gemm_phase(PG8_LAS unsigned char* lds, const Gemm g, const Sched& S, const Epi& E) {
;     ...
;             PG8_WAIT_V(8); PG8_WAIT_L(0); PG8_BAR; PG8_MMA(1, 0, At, B0); PG8_MMA(1, 1, At, B1); PG8_BAR; PG8_SCHED;
;             PG8_LDB(B0, 1, 0); PG8_LDB(B1, 1, 1); PG8_SCHED; PG8_LDA(At, 1, 0); PG8_STAGE(PG8_SA(0, 1), a2 + hstep, voffA);
;             PG8_WAIT_V(8); PG8_WAIT_L(0); PG8_BAR; PG8_MMA(0, 0, At, B0); PG8_MMA(0, 1, At, B1); PG8_BAR; PG8_SCHED;
	s_setprio 1
	v_mfma_f32_16x16x32_bf16 v[60:63], v[156:159], v[192:195], v[60:63]
	v_mfma_f32_16x16x32_bf16 v[56:59], v[168:171], v[192:195], v[56:59]
	v_mfma_f32_16x16x32_bf16 v[52:55], v[156:159], v[200:203], v[52:55]
	v_mfma_f32_16x16x32_bf16 v[44:47], v[168:171], v[200:203], v[44:47]
	v_mfma_f32_16x16x32_bf16 v[36:39], v[156:159], v[210:213], v[36:39]
	v_mfma_f32_16x16x32_bf16 v[28:31], v[168:171], v[210:213], v[28:31]
	v_mfma_f32_16x16x32_bf16 v[20:23], v[156:159], v[218:221], v[20:23]
	v_mfma_f32_16x16x32_bf16 v[12:15], v[168:171], v[218:221], v[12:15]
	s_setprio 0
	s_setprio 1
	v_mfma_f32_16x16x32_bf16 v[48:51], v[172:175], v[188:191], v[48:51]
	v_mfma_f32_16x16x32_bf16 v[40:43], v[180:183], v[188:191], v[40:43]
	v_mfma_f32_16x16x32_bf16 v[32:35], v[172:175], v[196:199], v[32:35]
	v_mfma_f32_16x16x32_bf16 v[24:27], v[180:183], v[196:199], v[24:27]
	v_mfma_f32_16x16x32_bf16 v[16:19], v[172:175], v[204:207], v[16:19]
	v_mfma_f32_16x16x32_bf16 v[8:11], v[180:183], v[204:207], v[8:11]
	v_mfma_f32_16x16x32_bf16 v[4:7], v[172:175], v[214:217], v[4:7]
	v_mfma_f32_16x16x32_bf16 v[0:3], v[180:183], v[214:217], v[0:3]
	v_mfma_f32_16x16x32_bf16 v[48:51], v[176:179], v[192:195], v[48:51]
	v_mfma_f32_16x16x32_bf16 v[40:43], v[184:187], v[192:195], v[40:43]
	v_mfma_f32_16x16x32_bf16 v[32:35], v[176:179], v[200:203], v[32:35]
	v_mfma_f32_16x16x32_bf16 v[24:27], v[184:187], v[200:203], v[24:27]
	v_mfma_f32_16x16x32_bf16 v[16:19], v[176:179], v[210:213], v[16:19]
	v_mfma_f32_16x16x32_bf16 v[8:11], v[184:187], v[210:213], v[8:11]
	v_mfma_f32_16x16x32_bf16 v[4:7], v[176:179], v[218:221], v[4:7]
	v_mfma_f32_16x16x32_bf16 v[0:3], v[184:187], v[218:221], v[0:3]
	s_setprio 0
	s_barrier
	s_add_i32 s73, 0, 0x18000
	v_add_u32_e32 v163, s73, v147
	s_add_i32 s74, 0, 0x1c000
	ds_read_b128 v[152:155], v163
	ds_read_b128 v[156:159], v163 offset:1024
	ds_read_b128 v[164:167], v163 offset:2048
	ds_read_b128 v[168:171], v163 offset:3072
	v_add_u32_e32 v163, s74, v147
	ds_read_b128 v[172:175], v163
	ds_read_b128 v[176:179], v163 offset:1024
	ds_read_b128 v[180:183], v163 offset:2048
	ds_read_b128 v[184:187], v163 offset:3072
	s_add_u32 s62, s62, 0x80000
	s_addc_u32 s63, s63, 0
	s_mov_b32 m0, s41
	v_lshl_add_u64 v[226:227], s[62:63], 0, v[134:135]
	ds_read_b128 v[188:191], v151 offset:32768
	ds_read_b128 v[192:195], v151 offset:33792
	ds_read_b128 v[196:199], v151 offset:34816
	ds_read_b128 v[200:203], v151 offset:35840
	ds_read_b128 v[204:207], v151 offset:36864
	ds_read_b128 v[210:213], v151 offset:37888
	ds_read_b128 v[214:217], v151 offset:38912
	ds_read_b128 v[218:221], v151 offset:39936
	global_load_lds_dwordx4 v[226:227], off
	v_lshl_add_u64 v[226:227], s[62:63], 0, v[130:131]
	s_mov_b32 m0, s43
	s_nop 0
	global_load_lds_dwordx4 v[226:227], off
	s_waitcnt vmcnt(8)
	s_waitcnt lgkmcnt(0)
	s_waitcnt lgkmcnt(0)
	v_mfma_f32_16x16x32_bf16 v[124:127], v[152:155], v[188:191], v[124:127]
	v_mfma_f32_16x16x32_bf16 v[120:123], v[164:167], v[188:191], v[120:123]
	v_mfma_f32_16x16x32_bf16 v[116:119], v[152:155], v[196:199], v[116:119]
	v_mfma_f32_16x16x32_bf16 v[108:111], v[164:167], v[196:199], v[108:111]
	v_mfma_f32_16x16x32_bf16 v[100:103], v[152:155], v[204:207], v[100:103]
	v_mfma_f32_16x16x32_bf16 v[92:95], v[164:167], v[204:207], v[92:95]
	v_mfma_f32_16x16x32_bf16 v[84:87], v[152:155], v[214:217], v[84:87]
	v_mfma_f32_16x16x32_bf16 v[76:79], v[164:167], v[214:217], v[76:79]
	s_barrier
	s_setprio 1
	v_mfma_f32_16x16x32_bf16 v[124:127], v[156:159], v[192:195], v[124:127]
	v_mfma_f32_16x16x32_bf16 v[120:123], v[168:171], v[192:195], v[120:123]
	v_mfma_f32_16x16x32_bf16 v[116:119], v[156:159], v[200:203], v[116:119]
	v_mfma_f32_16x16x32_bf16 v[108:111], v[168:171], v[200:203], v[108:111]
	v_mfma_f32_16x16x32_bf16 v[100:103], v[156:159], v[210:213], v[100:103]
	v_mfma_f32_16x16x32_bf16 v[92:95], v[168:171], v[210:213], v[92:95]
	v_mfma_f32_16x16x32_bf16 v[84:87], v[156:159], v[218:221], v[84:87]
	v_mfma_f32_16x16x32_bf16 v[76:79], v[168:171], v[218:221], v[76:79]
	s_setprio 0
	s_setprio 1
	v_mfma_f32_16x16x32_bf16 v[112:115], v[172:175], v[188:191], v[112:115]
	v_mfma_f32_16x16x32_bf16 v[104:107], v[180:183], v[188:191], v[104:107]
	v_mfma_f32_16x16x32_bf16 v[96:99], v[172:175], v[196:199], v[96:99]
	v_mfma_f32_16x16x32_bf16 v[88:91], v[180:183], v[196:199], v[88:91]
	v_mfma_f32_16x16x32_bf16 v[80:83], v[172:175], v[204:207], v[80:83]
	v_mfma_f32_16x16x32_bf16 v[72:75], v[180:183], v[204:207], v[72:75]
	v_mfma_f32_16x16x32_bf16 v[68:71], v[172:175], v[214:217], v[68:71]
	v_mfma_f32_16x16x32_bf16 v[64:67], v[180:183], v[214:217], v[64:67]
	v_mfma_f32_16x16x32_bf16 v[112:115], v[176:179], v[192:195], v[112:115]
	v_mfma_f32_16x16x32_bf16 v[104:107], v[184:187], v[192:195], v[104:107]
	v_mfma_f32_16x16x32_bf16 v[96:99], v[176:179], v[200:203], v[96:99]
	v_mfma_f32_16x16x32_bf16 v[88:91], v[184:187], v[200:203], v[88:91]
	v_mfma_f32_16x16x32_bf16 v[80:83], v[176:179], v[210:213], v[80:83]
	v_mfma_f32_16x16x32_bf16 v[72:75], v[184:187], v[210:213], v[72:75]
	v_mfma_f32_16x16x32_bf16 v[68:71], v[176:179], v[218:221], v[68:71]
	v_mfma_f32_16x16x32_bf16 v[64:67], v[184:187], v[218:221], v[64:67]
	s_setprio 0
	s_barrier
; #define PG8_STAGE(bufoff, gbase, voff) do { _Pragma("unroll") for (int _i = 0; _i < 2; ++_i) \
;         __builtin_amdgcn_global_load_lds((const unsigned*)((const char*)(gbase) + (voff)[_i]), (PG8_LAS unsigned*)(lds + (bufoff) + ldsw + _i * 8192), 16, 0, 0); } while (0)
; #define PG8_LDA(dst, b, h) do { _Pragma("unroll") for (int m = 0; m < 4; ++m) _Pragma("unroll") for (int k = 0; k < 2; ++k) dst[m][k] = *(const PG8_LAS bf16x8*)(lds + PG8_SA(b, h) + aoff + m * 2048 + k * 1024); } while (0)
; #define PG8_MMA(ai, bj, At, Bt) do { __builtin_amdgcn_s_setprio(1); _Pragma("unroll") for (int m = 0; m < 4; ++m) _Pragma("unroll") for (int n = 0; n < 2; ++n) _Pragma("unroll") for (int k = 0; k < 2; ++k) \
;         acc[ai][bj][m][n] = __builtin_amdgcn_mfma_f32_16x16x32_bf16(Bt[n][k], At[m][k], acc[ai][bj][m][n], 0, 0, 0); __builtin_amdgcn_s_setprio(0); } while (0)
; #define PG8_WAIT_V(n) asm volatile("s_waitcnt vmcnt(" #n ")" ::: "memory")
; #define PG8_WAIT_L(n) asm volatile("s_waitcnt lgkmcnt(" #n ")" ::: "memory")
; #define PG8_BAR __builtin_amdgcn_s_barrier()
; #define PG8_SCHED __builtin_amdgcn_sched_barrier(0)
; template <class Epi, class Sched, bool ALIGN_EPI = false, bool SP2 = false>
; __device__ __forceinline__ void gemm_phase(PG8_LAS unsigned char* lds, const Gemm g, const Sched& S, const Epi& E) {
;     ...
;             PG8_LDA(At, 1, 1); PG8_STAGE(PG8_SB(1, 0), b3, voffB); PG8_STAGE(PG8_SB(1, 1), b3 + hstep, voffB); PG8_STAGE(PG8_SA(1, 0), a3, voffA);
;             PG8_WAIT_V(8); PG8_WAIT_L(0); PG8_BAR; PG8_MMA(1, 0, At, B0); PG8_MMA(1, 1, At, B1); PG8_BAR; PG8_SCHED;
	s_add_i32 s62, s73, s0
	v_lshl_add_u64 v[144:145], v[144:145], 0, s[12:13]
	s_mov_b32 m0, s62
	ds_read_b128 v[188:191], v151 offset:49152
	ds_read_b128 v[192:195], v151 offset:50176
	ds_read_b128 v[196:199], v151 offset:51200
	ds_read_b128 v[200:203], v151 offset:52224
	ds_read_b128 v[204:207], v151 offset:53248
	ds_read_b128 v[210:213], v151 offset:54272
	ds_read_b128 v[214:217], v151 offset:55296
	ds_read_b128 v[218:221], v151 offset:56320
	global_load_lds_dwordx4 v[144:145], off
	s_add_i32 m0, s62, 0x2000
	s_add_u32 s38, s38, 0x80080
	v_lshl_add_u64 v[144:145], v[160:161], 0, s[12:13]
	s_addc_u32 s39, s39, 0
	s_add_i32 s62, s74, s0
	global_load_lds_dwordx4 v[144:145], off
	v_lshl_add_u64 v[144:145], s[38:39], 0, v[132:133]
	s_mov_b32 m0, s62
	s_nop 0
	global_load_lds_dwordx4 v[144:145], off
	v_lshl_add_u64 v[144:145], s[38:39], 0, v[128:129]
	s_add_i32 m0, s62, 0x2000
	s_nop 0
	global_load_lds_dwordx4 v[144:145], off
	v_lshl_add_u64 v[144:145], v[222:223], 0, s[12:13]
	s_mov_b32 m0, s47
	s_nop 0
	global_load_lds_dwordx4 v[144:145], off
	v_lshl_add_u64 v[144:145], v[224:225], 0, s[12:13]
	s_mov_b32 m0, s48
	s_nop 0
	global_load_lds_dwordx4 v[144:145], off
	s_waitcnt vmcnt(8)
	s_waitcnt lgkmcnt(0)
	s_waitcnt lgkmcnt(0)
	v_mfma_f32_16x16x32_bf16 v[60:63], v[152:155], v[188:191], v[60:63]
	v_mfma_f32_16x16x32_bf16 v[56:59], v[164:167], v[188:191], v[56:59]
	v_mfma_f32_16x16x32_bf16 v[52:55], v[152:155], v[196:199], v[52:55]
	v_mfma_f32_16x16x32_bf16 v[44:47], v[164:167], v[196:199], v[44:47]
	v_mfma_f32_16x16x32_bf16 v[36:39], v[152:155], v[204:207], v[36:39]
	v_mfma_f32_16x16x32_bf16 v[28:31], v[164:167], v[204:207], v[28:31]
	v_mfma_f32_16x16x32_bf16 v[20:23], v[152:155], v[214:217], v[20:23]
	v_mfma_f32_16x16x32_bf16 v[12:15], v[164:167], v[214:217], v[12:15]
	s_barrier
	s_setprio 1
	v_mfma_f32_16x16x32_bf16 v[60:63], v[156:159], v[192:195], v[60:63]
	v_mfma_f32_16x16x32_bf16 v[56:59], v[168:171], v[192:195], v[56:59]
	v_mfma_f32_16x16x32_bf16 v[52:55], v[156:159], v[200:203], v[52:55]
	v_mfma_f32_16x16x32_bf16 v[44:47], v[168:171], v[200:203], v[44:47]
	v_mfma_f32_16x16x32_bf16 v[36:39], v[156:159], v[210:213], v[36:39]
	v_mfma_f32_16x16x32_bf16 v[28:31], v[168:171], v[210:213], v[28:31]
	v_mfma_f32_16x16x32_bf16 v[20:23], v[156:159], v[218:221], v[20:23]
	v_mfma_f32_16x16x32_bf16 v[12:15], v[168:171], v[218:221], v[12:15]
	s_setprio 0
	s_setprio 1
	v_mfma_f32_16x16x32_bf16 v[48:51], v[172:175], v[188:191], v[48:51]
	v_mfma_f32_16x16x32_bf16 v[40:43], v[180:183], v[188:191], v[40:43]
	v_mfma_f32_16x16x32_bf16 v[32:35], v[172:175], v[196:199], v[32:35]
	v_mfma_f32_16x16x32_bf16 v[24:27], v[180:183], v[196:199], v[24:27]
	v_mfma_f32_16x16x32_bf16 v[16:19], v[172:175], v[204:207], v[16:19]
	v_mfma_f32_16x16x32_bf16 v[8:11], v[180:183], v[204:207], v[8:11]
	v_mfma_f32_16x16x32_bf16 v[4:7], v[172:175], v[214:217], v[4:7]
	v_mfma_f32_16x16x32_bf16 v[0:3], v[180:183], v[214:217], v[0:3]
	v_mfma_f32_16x16x32_bf16 v[48:51], v[176:179], v[192:195], v[48:51]
	v_mfma_f32_16x16x32_bf16 v[40:43], v[184:187], v[192:195], v[40:43]
	v_mfma_f32_16x16x32_bf16 v[32:35], v[176:179], v[200:203], v[32:35]
	v_mfma_f32_16x16x32_bf16 v[24:27], v[184:187], v[200:203], v[24:27]
	v_mfma_f32_16x16x32_bf16 v[16:19], v[176:179], v[210:213], v[16:19]
	v_mfma_f32_16x16x32_bf16 v[8:11], v[184:187], v[210:213], v[8:11]
	v_mfma_f32_16x16x32_bf16 v[4:7], v[176:179], v[218:221], v[4:7]
	v_mfma_f32_16x16x32_bf16 v[0:3], v[184:187], v[218:221], v[0:3]
	s_setprio 0
	s_barrier
	s_add_i32 s72, s72, 2
	s_add_u32 s34, s34, 0x100
	s_addc_u32 s35, s35, 0
	s_add_u32 s70, s70, 0x100
	s_addc_u32 s71, s71, 0
	s_cmp_gt_u32 s72, 29
	s_cbranch_scc0 .LBB0_1189
	s_and_b64 vcc, exec, s[14:15]
	s_cbranch_vccz .LBB0_1192
	s_barrier

; #define PG8_STAGE(bufoff, gbase, voff) do { _Pragma("unroll") for (int _i = 0; _i < 2; ++_i) \
;         __builtin_amdgcn_global_load_lds((const unsigned*)((const char*)(gbase) + (voff)[_i]), (PG8_LAS unsigned*)(lds + (bufoff) + ldsw + _i * 8192), 16, 0, 0); } while (0)
; #define PG8_LDA(dst, b, h) do { _Pragma("unroll") for (int m = 0; m < 4; ++m) _Pragma("unroll") for (int k = 0; k < 2; ++k) dst[m][k] = *(const PG8_LAS bf16x8*)(lds + PG8_SA(b, h) + aoff + m * 2048 + k * 1024); } while (0)
; #define PG8_LDB(dst, b, h) do { _Pragma("unroll") for (int n = 0; n < 2; ++n) _Pragma("unroll") for (int k = 0; k < 2; ++k) dst[n][k] = *(const PG8_LAS bf16x8*)(lds + PG8_SB(b, h) + boff + n * 2048 + k * 1024); } while (0)
; #define PG8_MMA(ai, bj, At, Bt) do { __builtin_amdgcn_s_setprio(1); _Pragma("unroll") for (int m = 0; m < 4; ++m) _Pragma("unroll") for (int n = 0; n < 2; ++n) _Pragma("unroll") for (int k = 0; k < 2; ++k) \
;         acc[ai][bj][m][n] = __builtin_amdgcn_mfma_f32_16x16x32_bf16(Bt[n][k], At[m][k], acc[ai][bj][m][n], 0, 0, 0); __builtin_amdgcn_s_setprio(0); } while (0)
; #define PG8_WAIT_V(n) asm volatile("s_waitcnt vmcnt(" #n ")" ::: "memory")
; #define PG8_WAIT_L(n) asm volatile("s_waitcnt lgkmcnt(" #n ")" ::: "memory")
; #define PG8_BAR __builtin_amdgcn_s_barrier()
; #define PG8_SCHED __builtin_amdgcn_sched_barrier(0)
; template <class Epi, class Sched, bool ALIGN_EPI = false, bool SP2 = false>
; __device__ __forceinline__ void gemm_phase(PG8_LAS unsigned char* lds, const Gemm g, const Sched& S, const Epi& E) {
;     ...
;             const char* a2 = last ? nA : cA + (size_t)(t + 2) * kstep; const char* b2 = last ? nB : cB + (size_t)(t + 2) * kstep;
;             const char* a3 = a2 + kstep; const char* b3 = b2 + kstep;
;             if (last && has_next) S.a_ready(nxt);
;             if constexpr (SP2) {
;             PG8_LDB(B0, 0, 0); PG8_LDB(B1, 0, 1); PG8_SCHED; PG8_LDA(At, 0, 0); PG8_STAGE(PG8_SA(1, 1), a1 + hstep, voffA);
;             PG8_WAIT_V(8); PG8_WAIT_L(0); PG8_BAR; PG8_MMA(0, 0, At, B0); PG8_MMA(0, 1, At, B1); PG8_BAR; PG8_SCHED;
;             PG8_LDA(At, 0, 1); PG8_STAGE(PG8_SB(0, 0), b2, voffB); PG8_STAGE(PG8_SB(0, 1), b2 + hstep, voffB); PG8_STAGE(PG8_SA(0, 0), a2, voffA);
;             PG8_WAIT_V(8); PG8_WAIT_L(0); PG8_BAR; PG8_MMA(1, 0, At, B0); PG8_MMA(1, 1, At, B1); PG8_BAR; PG8_SCHED;
.LBB0_1317:
	ds_read_b128 v[144:147], v151
	ds_read_b128 v[154:157], v151 offset:1024
	ds_read_b128 v[158:161], v151 offset:2048
	ds_read_b128 v[164:167], v151 offset:3072
	ds_read_b128 v[168:171], v152
	ds_read_b128 v[172:175], v152 offset:1024
	ds_read_b128 v[176:179], v152 offset:2048
	ds_read_b128 v[180:183], v152 offset:3072
	s_add_u32 s26, s24, 0xfff80080
	s_addc_u32 s27, s25, -1
	s_cmp_eq_u32 s64, 28
	s_cselect_b32 s29, s17, s27
	s_cselect_b32 s28, s56, s26
	s_cselect_b32 s27, s15, s63
	s_cselect_b32 s26, s57, s62
	v_lshl_add_u64 v[218:219], s[24:25], 0, v[136:137]
	s_add_i32 m0, s23, 0xc000
	ds_read_b128 v[184:187], v153
	ds_read_b128 v[188:191], v153 offset:1024
	ds_read_b128 v[192:195], v153 offset:2048
	ds_read_b128 v[196:199], v153 offset:3072
	ds_read_b128 v[200:203], v153 offset:4096
	ds_read_b128 v[204:207], v153 offset:5120
	ds_read_b128 v[210:213], v153 offset:6144
	ds_read_b128 v[214:217], v153 offset:7168
	global_load_lds_dwordx4 v[218:219], off
	v_lshl_add_u64 v[218:219], s[24:25], 0, v[138:139]
	s_add_i32 m0, s23, 0xe000
	s_nop 0
	global_load_lds_dwordx4 v[218:219], off
	s_waitcnt vmcnt(8)
	s_waitcnt lgkmcnt(0)
	s_waitcnt lgkmcnt(0)
	v_mfma_f32_16x16x32_bf16 v[124:127], v[144:147], v[184:187], v[124:127]
	v_mfma_f32_16x16x32_bf16 v[116:119], v[158:161], v[184:187], v[116:119]
	v_mfma_f32_16x16x32_bf16 v[108:111], v[144:147], v[192:195], v[108:111]
	v_mfma_f32_16x16x32_bf16 v[100:103], v[158:161], v[192:195], v[100:103]
	v_mfma_f32_16x16x32_bf16 v[92:95], v[144:147], v[200:203], v[92:95]
	v_mfma_f32_16x16x32_bf16 v[84:87], v[158:161], v[200:203], v[84:87]
	v_mfma_f32_16x16x32_bf16 v[76:79], v[144:147], v[210:213], v[76:79]
	v_mfma_f32_16x16x32_bf16 v[68:71], v[158:161], v[210:213], v[68:71]
	s_barrier
	s_setprio 1
	v_mfma_f32_16x16x32_bf16 v[124:127], v[154:157], v[188:191], v[124:127]
	v_mfma_f32_16x16x32_bf16 v[116:119], v[164:167], v[188:191], v[116:119]
	v_mfma_f32_16x16x32_bf16 v[108:111], v[154:157], v[196:199], v[108:111]
	v_mfma_f32_16x16x32_bf16 v[100:103], v[164:167], v[196:199], v[100:103]
	v_mfma_f32_16x16x32_bf16 v[92:95], v[154:157], v[204:207], v[92:95]
	v_mfma_f32_16x16x32_bf16 v[84:87], v[164:167], v[204:207], v[84:87]
	v_mfma_f32_16x16x32_bf16 v[76:79], v[154:157], v[214:217], v[76:79]
	v_mfma_f32_16x16x32_bf16 v[68:71], v[164:167], v[214:217], v[68:71]
	s_setprio 0
	s_setprio 1
	v_mfma_f32_16x16x32_bf16 v[120:123], v[168:171], v[184:187], v[120:123]
	v_mfma_f32_16x16x32_bf16 v[112:115], v[176:179], v[184:187], v[112:115]
	v_mfma_f32_16x16x32_bf16 v[104:107], v[168:171], v[192:195], v[104:107]
	v_mfma_f32_16x16x32_bf16 v[96:99], v[176:179], v[192:195], v[96:99]
	v_mfma_f32_16x16x32_bf16 v[88:91], v[168:171], v[200:203], v[88:91]
	v_mfma_f32_16x16x32_bf16 v[80:83], v[176:179], v[200:203], v[80:83]
	v_mfma_f32_16x16x32_bf16 v[72:75], v[168:171], v[210:213], v[72:75]
	v_mfma_f32_16x16x32_bf16 v[64:67], v[176:179], v[210:213], v[64:67]
	v_mfma_f32_16x16x32_bf16 v[120:123], v[172:175], v[188:191], v[120:123]
	v_mfma_f32_16x16x32_bf16 v[112:115], v[180:183], v[188:191], v[112:115]
	v_mfma_f32_16x16x32_bf16 v[104:107], v[172:175], v[196:199], v[104:107]
	v_mfma_f32_16x16x32_bf16 v[96:99], v[180:183], v[196:199], v[96:99]
	v_mfma_f32_16x16x32_bf16 v[88:91], v[172:175], v[204:207], v[88:91]
	v_mfma_f32_16x16x32_bf16 v[80:83], v[180:183], v[204:207], v[80:83]
	v_mfma_f32_16x16x32_bf16 v[72:75], v[172:175], v[214:217], v[72:75]
	v_mfma_f32_16x16x32_bf16 v[64:67], v[180:183], v[214:217], v[64:67]
	s_setprio 0
	s_barrier
	s_add_i32 s65, s48, s3
	v_lshl_add_u64 v[218:219], s[26:27], 0, v[132:133]
	s_mov_b32 m0, s65
	ds_read_b128 v[184:187], v153 offset:16384
	ds_read_b128 v[188:191], v153 offset:17408
	ds_read_b128 v[192:195], v153 offset:18432
	ds_read_b128 v[196:199], v153 offset:19456
	ds_read_b128 v[200:203], v153 offset:20480
	ds_read_b128 v[204:207], v153 offset:21504
	ds_read_b128 v[210:213], v153 offset:22528
	ds_read_b128 v[214:217], v153 offset:23552
	global_load_lds_dwordx4 v[218:219], off
	s_add_i32 m0, s65, 0x2000
	s_add_u32 s66, s26, 0x80000
	v_lshl_add_u64 v[220:221], s[26:27], 0, v[128:129]
	s_addc_u32 s67, s27, 0
	s_add_i32 s65, s49, s3
	global_load_lds_dwordx4 v[220:221], off
	v_lshl_add_u64 v[222:223], s[66:67], 0, v[132:133]
	s_mov_b32 m0, s65
	v_lshl_add_u64 v[224:225], s[28:29], 0, v[130:131]
	global_load_lds_dwordx4 v[222:223], off
	v_lshl_add_u64 v[222:223], s[66:67], 0, v[128:129]
	s_add_i32 m0, s65, 0x2000
	s_nop 0
	global_load_lds_dwordx4 v[222:223], off
	v_lshl_add_u64 v[222:223], s[28:29], 0, v[134:135]
	s_mov_b32 m0, s23
	s_nop 0
	global_load_lds_dwordx4 v[222:223], off
	s_mov_b32 m0, s34
	s_nop 0
	global_load_lds_dwordx4 v[224:225], off
	s_waitcnt vmcnt(8)
	s_waitcnt lgkmcnt(0)
	s_waitcnt lgkmcnt(0)
	v_mfma_f32_16x16x32_bf16 v[60:63], v[144:147], v[184:187], v[60:63]
	v_mfma_f32_16x16x32_bf16 v[52:55], v[158:161], v[184:187], v[52:55]
	v_mfma_f32_16x16x32_bf16 v[44:47], v[144:147], v[192:195], v[44:47]
	v_mfma_f32_16x16x32_bf16 v[36:39], v[158:161], v[192:195], v[36:39]
	v_mfma_f32_16x16x32_bf16 v[28:31], v[144:147], v[200:203], v[28:31]
	v_mfma_f32_16x16x32_bf16 v[20:23], v[158:161], v[200:203], v[20:23]
	v_mfma_f32_16x16x32_bf16 v[12:15], v[144:147], v[210:213], v[12:15]
	v_mfma_f32_16x16x32_bf16 v[4:7], v[158:161], v[210:213], v[4:7]
	s_barrier
; #define PG8_STAGE(bufoff, gbase, voff) do { _Pragma("unroll") for (int _i = 0; _i < 2; ++_i) \
;         __builtin_amdgcn_global_load_lds((const unsigned*)((const char*)(gbase) + (voff)[_i]), (PG8_LAS unsigned*)(lds + (bufoff) + ldsw + _i * 8192), 16, 0, 0); } while (0)
; #define PG8_LDA(dst, b, h) do { _Pragma("unroll") for (int m = 0; m < 4; ++m) _Pragma("unroll") for (int k = 0; k < 2; ++k) dst[m][k] = *(const PG8_LAS bf16x8*)(lds + PG8_SA(b, h) + aoff + m * 2048 + k * 1024); } while (0)
; #define PG8_LDB(dst, b, h) do { _Pragma("unroll") for (int n = 0; n < 2; ++n) _Pragma("unroll") for (int k = 0; k < 2; ++k) dst[n][k] = *(const PG8_LAS bf16x8*)(lds + PG8_SB(b, h) + boff + n * 2048 + k * 1024); } while (0)
; #define PG8_MMA(ai, bj, At, Bt) do { __builtin_amdgcn_s_setprio(1); _Pragma("unroll") for (int m = 0; m < 4; ++m) _Pragma("unroll") for (int n = 0; n < 2; ++n) _Pragma("unroll") for (int k = 0; k < 2; ++k) \
;         acc[ai][bj][m][n] = __builtin_amdgcn_mfma_f32_16x16x32_bf16(Bt[n][k], At[m][k], acc[ai][bj][m][n], 0, 0, 0); __builtin_amdgcn_s_setprio(0); } while (0)
; #define PG8_WAIT_V(n) asm volatile("s_waitcnt vmcnt(" #n ")" ::: "memory")
; #define PG8_WAIT_L(n) asm volatile("s_waitcnt lgkmcnt(" #n ")" ::: "memory")
; #define PG8_BAR __builtin_amdgcn_s_barrier()
; #define PG8_SCHED __builtin_amdgcn_sched_barrier(0)
; template <class Epi, class Sched, bool ALIGN_EPI = false, bool SP2 = false>
; __device__ __forceinline__ void gemm_phase(PG8_LAS unsigned char* lds, const Gemm g, const Sched& S, const Epi& E) {
;     ...
;             PG8_WAIT_V(8); PG8_WAIT_L(0); PG8_BAR; PG8_MMA(1, 0, At, B0); PG8_MMA(1, 1, At, B1); PG8_BAR; PG8_SCHED;
;             PG8_LDB(B0, 1, 0); PG8_LDB(B1, 1, 1); PG8_SCHED; PG8_LDA(At, 1, 0); PG8_STAGE(PG8_SA(0, 1), a2 + hstep, voffA);
;             PG8_WAIT_V(8); PG8_WAIT_L(0); PG8_BAR; PG8_MMA(0, 0, At, B0); PG8_MMA(0, 1, At, B1); PG8_BAR; PG8_SCHED;
	s_setprio 1
	v_mfma_f32_16x16x32_bf16 v[60:63], v[154:157], v[188:191], v[60:63]
	v_mfma_f32_16x16x32_bf16 v[52:55], v[164:167], v[188:191], v[52:55]
	v_mfma_f32_16x16x32_bf16 v[44:47], v[154:157], v[196:199], v[44:47]
	v_mfma_f32_16x16x32_bf16 v[36:39], v[164:167], v[196:199], v[36:39]
	v_mfma_f32_16x16x32_bf16 v[28:31], v[154:157], v[204:207], v[28:31]
	v_mfma_f32_16x16x32_bf16 v[20:23], v[164:167], v[204:207], v[20:23]
	v_mfma_f32_16x16x32_bf16 v[12:15], v[154:157], v[214:217], v[12:15]
	v_mfma_f32_16x16x32_bf16 v[4:7], v[164:167], v[214:217], v[4:7]
	s_setprio 0
	s_setprio 1
	v_mfma_f32_16x16x32_bf16 v[56:59], v[168:171], v[184:187], v[56:59]
	v_mfma_f32_16x16x32_bf16 v[48:51], v[176:179], v[184:187], v[48:51]
	v_mfma_f32_16x16x32_bf16 v[40:43], v[168:171], v[192:195], v[40:43]
	v_mfma_f32_16x16x32_bf16 v[32:35], v[176:179], v[192:195], v[32:35]
	v_mfma_f32_16x16x32_bf16 v[24:27], v[168:171], v[200:203], v[24:27]
	v_mfma_f32_16x16x32_bf16 v[16:19], v[176:179], v[200:203], v[16:19]
	v_mfma_f32_16x16x32_bf16 v[8:11], v[168:171], v[210:213], v[8:11]
	v_mfma_f32_16x16x32_bf16 v[0:3], v[176:179], v[210:213], v[0:3]
	v_mfma_f32_16x16x32_bf16 v[56:59], v[172:175], v[188:191], v[56:59]
	v_mfma_f32_16x16x32_bf16 v[48:51], v[180:183], v[188:191], v[48:51]
	v_mfma_f32_16x16x32_bf16 v[40:43], v[172:175], v[196:199], v[40:43]
	v_mfma_f32_16x16x32_bf16 v[32:35], v[180:183], v[196:199], v[32:35]
	v_mfma_f32_16x16x32_bf16 v[24:27], v[172:175], v[204:207], v[24:27]
	v_mfma_f32_16x16x32_bf16 v[16:19], v[180:183], v[204:207], v[16:19]
	v_mfma_f32_16x16x32_bf16 v[8:11], v[172:175], v[214:217], v[8:11]
	v_mfma_f32_16x16x32_bf16 v[0:3], v[180:183], v[214:217], v[0:3]
	s_setprio 0
	s_barrier
	s_add_i32 s65, 0, 0x18000
	v_add_u32_e32 v163, s65, v149
	s_add_i32 s66, 0, 0x1c000
	ds_read_b128 v[144:147], v163
	ds_read_b128 v[154:157], v163 offset:1024
	ds_read_b128 v[158:161], v163 offset:2048
	ds_read_b128 v[164:167], v163 offset:3072
	v_add_u32_e32 v163, s66, v149
	ds_read_b128 v[168:171], v163
	ds_read_b128 v[172:175], v163 offset:1024
	ds_read_b128 v[176:179], v163 offset:2048
	ds_read_b128 v[180:183], v163 offset:3072
	s_add_u32 s28, s28, 0x80000
	s_addc_u32 s29, s29, 0
	s_mov_b32 m0, s35
	v_lshl_add_u64 v[226:227], s[28:29], 0, v[134:135]
	ds_read_b128 v[184:187], v153 offset:32768
	ds_read_b128 v[188:191], v153 offset:33792
	ds_read_b128 v[192:195], v153 offset:34816
	ds_read_b128 v[196:199], v153 offset:35840
	ds_read_b128 v[200:203], v153 offset:36864
	ds_read_b128 v[204:207], v153 offset:37888
	ds_read_b128 v[210:213], v153 offset:38912
	ds_read_b128 v[214:217], v153 offset:39936
	global_load_lds_dwordx4 v[226:227], off
	v_lshl_add_u64 v[226:227], s[28:29], 0, v[130:131]
	s_mov_b32 m0, s38
	s_nop 0
	global_load_lds_dwordx4 v[226:227], off
	s_waitcnt vmcnt(8)
	s_waitcnt lgkmcnt(0)
	s_waitcnt lgkmcnt(0)
	v_mfma_f32_16x16x32_bf16 v[124:127], v[144:147], v[184:187], v[124:127]
	v_mfma_f32_16x16x32_bf16 v[116:119], v[158:161], v[184:187], v[116:119]
	v_mfma_f32_16x16x32_bf16 v[108:111], v[144:147], v[192:195], v[108:111]
	v_mfma_f32_16x16x32_bf16 v[100:103], v[158:161], v[192:195], v[100:103]
	v_mfma_f32_16x16x32_bf16 v[92:95], v[144:147], v[200:203], v[92:95]
	v_mfma_f32_16x16x32_bf16 v[84:87], v[158:161], v[200:203], v[84:87]
	v_mfma_f32_16x16x32_bf16 v[76:79], v[144:147], v[210:213], v[76:79]
	v_mfma_f32_16x16x32_bf16 v[68:71], v[158:161], v[210:213], v[68:71]
	s_barrier
	s_setprio 1
	v_mfma_f32_16x16x32_bf16 v[124:127], v[154:157], v[188:191], v[124:127]
	v_mfma_f32_16x16x32_bf16 v[116:119], v[164:167], v[188:191], v[116:119]
	v_mfma_f32_16x16x32_bf16 v[108:111], v[154:157], v[196:199], v[108:111]
	v_mfma_f32_16x16x32_bf16 v[100:103], v[164:167], v[196:199], v[100:103]
	v_mfma_f32_16x16x32_bf16 v[92:95], v[154:157], v[204:207], v[92:95]
	v_mfma_f32_16x16x32_bf16 v[84:87], v[164:167], v[204:207], v[84:87]
	v_mfma_f32_16x16x32_bf16 v[76:79], v[154:157], v[214:217], v[76:79]
	v_mfma_f32_16x16x32_bf16 v[68:71], v[164:167], v[214:217], v[68:71]
	s_setprio 0
	s_setprio 1
	v_mfma_f32_16x16x32_bf16 v[120:123], v[168:171], v[184:187], v[120:123]
	v_mfma_f32_16x16x32_bf16 v[112:115], v[176:179], v[184:187], v[112:115]
	v_mfma_f32_16x16x32_bf16 v[104:107], v[168:171], v[192:195], v[104:107]
	v_mfma_f32_16x16x32_bf16 v[96:99], v[176:179], v[192:195], v[96:99]
	v_mfma_f32_16x16x32_bf16 v[88:91], v[168:171], v[200:203], v[88:91]
	v_mfma_f32_16x16x32_bf16 v[80:83], v[176:179], v[200:203], v[80:83]
	v_mfma_f32_16x16x32_bf16 v[72:75], v[168:171], v[210:213], v[72:75]
	v_mfma_f32_16x16x32_bf16 v[64:67], v[176:179], v[210:213], v[64:67]
	v_mfma_f32_16x16x32_bf16 v[120:123], v[172:175], v[188:191], v[120:123]
	v_mfma_f32_16x16x32_bf16 v[112:115], v[180:183], v[188:191], v[112:115]
	v_mfma_f32_16x16x32_bf16 v[104:107], v[172:175], v[196:199], v[104:107]
	v_mfma_f32_16x16x32_bf16 v[96:99], v[180:183], v[196:199], v[96:99]
	v_mfma_f32_16x16x32_bf16 v[88:91], v[172:175], v[204:207], v[88:91]
	v_mfma_f32_16x16x32_bf16 v[80:83], v[180:183], v[204:207], v[80:83]
	v_mfma_f32_16x16x32_bf16 v[72:75], v[172:175], v[214:217], v[72:75]
	v_mfma_f32_16x16x32_bf16 v[64:67], v[180:183], v[214:217], v[64:67]
	s_setprio 0
	s_barrier
; #define PG8_STAGE(bufoff, gbase, voff) do { _Pragma("unroll") for (int _i = 0; _i < 2; ++_i) \
;         __builtin_amdgcn_global_load_lds((const unsigned*)((const char*)(gbase) + (voff)[_i]), (PG8_LAS unsigned*)(lds + (bufoff) + ldsw + _i * 8192), 16, 0, 0); } while (0)
; #define PG8_LDA(dst, b, h) do { _Pragma("unroll") for (int m = 0; m < 4; ++m) _Pragma("unroll") for (int k = 0; k < 2; ++k) dst[m][k] = *(const PG8_LAS bf16x8*)(lds + PG8_SA(b, h) + aoff + m * 2048 + k * 1024); } while (0)
; #define PG8_MMA(ai, bj, At, Bt) do { __builtin_amdgcn_s_setprio(1); _Pragma("unroll") for (int m = 0; m < 4; ++m) _Pragma("unroll") for (int n = 0; n < 2; ++n) _Pragma("unroll") for (int k = 0; k < 2; ++k) \
;         acc[ai][bj][m][n] = __builtin_amdgcn_mfma_f32_16x16x32_bf16(Bt[n][k], At[m][k], acc[ai][bj][m][n], 0, 0, 0); __builtin_amdgcn_s_setprio(0); } while (0)
; #define PG8_WAIT_V(n) asm volatile("s_waitcnt vmcnt(" #n ")" ::: "memory")
; #define PG8_WAIT_L(n) asm volatile("s_waitcnt lgkmcnt(" #n ")" ::: "memory")
; #define PG8_BAR __builtin_amdgcn_s_barrier()
; #define PG8_SCHED __builtin_amdgcn_sched_barrier(0)
; template <class Epi, class Sched, bool ALIGN_EPI = false, bool SP2 = false>
; __device__ __forceinline__ void gemm_phase(PG8_LAS unsigned char* lds, const Gemm g, const Sched& S, const Epi& E) {
;     ...
;             PG8_LDA(At, 1, 1); PG8_STAGE(PG8_SB(1, 0), b3, voffB); PG8_STAGE(PG8_SB(1, 1), b3 + hstep, voffB); PG8_STAGE(PG8_SA(1, 0), a3, voffA);
;             PG8_WAIT_V(8); PG8_WAIT_L(0); PG8_BAR; PG8_MMA(1, 0, At, B0); PG8_MMA(1, 1, At, B1); PG8_BAR; PG8_SCHED;
	s_add_i32 s28, s65, s3
	v_lshl_add_u64 v[218:219], v[218:219], 0, s[10:11]
	s_mov_b32 m0, s28
	ds_read_b128 v[184:187], v153 offset:49152
	ds_read_b128 v[188:191], v153 offset:50176
	ds_read_b128 v[192:195], v153 offset:51200
	ds_read_b128 v[196:199], v153 offset:52224
	ds_read_b128 v[200:203], v153 offset:53248
	ds_read_b128 v[204:207], v153 offset:54272
	ds_read_b128 v[210:213], v153 offset:55296
	ds_read_b128 v[214:217], v153 offset:56320
	global_load_lds_dwordx4 v[218:219], off
	s_add_i32 m0, s28, 0x2000
	s_add_u32 s26, s26, 0x80080
	v_lshl_add_u64 v[218:219], v[220:221], 0, s[10:11]
	s_addc_u32 s27, s27, 0
	s_add_i32 s28, s66, s3
	global_load_lds_dwordx4 v[218:219], off
	v_lshl_add_u64 v[218:219], s[26:27], 0, v[132:133]
	s_mov_b32 m0, s28
	s_nop 0
	global_load_lds_dwordx4 v[218:219], off
	v_lshl_add_u64 v[218:219], s[26:27], 0, v[128:129]
	s_add_i32 m0, s28, 0x2000
	s_nop 0
	global_load_lds_dwordx4 v[218:219], off
	v_lshl_add_u64 v[218:219], v[222:223], 0, s[10:11]
	s_mov_b32 m0, s41
	s_nop 0
	global_load_lds_dwordx4 v[218:219], off
	v_lshl_add_u64 v[218:219], v[224:225], 0, s[10:11]
	s_mov_b32 m0, s43
	s_nop 0
	global_load_lds_dwordx4 v[218:219], off
	s_waitcnt vmcnt(8)
	s_waitcnt lgkmcnt(0)
	s_waitcnt lgkmcnt(0)
	v_mfma_f32_16x16x32_bf16 v[60:63], v[144:147], v[184:187], v[60:63]
	v_mfma_f32_16x16x32_bf16 v[52:55], v[158:161], v[184:187], v[52:55]
	v_mfma_f32_16x16x32_bf16 v[44:47], v[144:147], v[192:195], v[44:47]
	v_mfma_f32_16x16x32_bf16 v[36:39], v[158:161], v[192:195], v[36:39]
	v_mfma_f32_16x16x32_bf16 v[28:31], v[144:147], v[200:203], v[28:31]
	v_mfma_f32_16x16x32_bf16 v[20:23], v[158:161], v[200:203], v[20:23]
	v_mfma_f32_16x16x32_bf16 v[12:15], v[144:147], v[210:213], v[12:15]
	v_mfma_f32_16x16x32_bf16 v[4:7], v[158:161], v[210:213], v[4:7]
	s_barrier
	s_setprio 1
	v_mfma_f32_16x16x32_bf16 v[60:63], v[154:157], v[188:191], v[60:63]
	v_mfma_f32_16x16x32_bf16 v[52:55], v[164:167], v[188:191], v[52:55]
	v_mfma_f32_16x16x32_bf16 v[44:47], v[154:157], v[196:199], v[44:47]
	v_mfma_f32_16x16x32_bf16 v[36:39], v[164:167], v[196:199], v[36:39]
	v_mfma_f32_16x16x32_bf16 v[28:31], v[154:157], v[204:207], v[28:31]
	v_mfma_f32_16x16x32_bf16 v[20:23], v[164:167], v[204:207], v[20:23]
	v_mfma_f32_16x16x32_bf16 v[12:15], v[154:157], v[214:217], v[12:15]
	v_mfma_f32_16x16x32_bf16 v[4:7], v[164:167], v[214:217], v[4:7]
	s_setprio 0
	s_setprio 1
	v_mfma_f32_16x16x32_bf16 v[56:59], v[168:171], v[184:187], v[56:59]
	v_mfma_f32_16x16x32_bf16 v[48:51], v[176:179], v[184:187], v[48:51]
	v_mfma_f32_16x16x32_bf16 v[40:43], v[168:171], v[192:195], v[40:43]
	v_mfma_f32_16x16x32_bf16 v[32:35], v[176:179], v[192:195], v[32:35]
	v_mfma_f32_16x16x32_bf16 v[24:27], v[168:171], v[200:203], v[24:27]
	v_mfma_f32_16x16x32_bf16 v[16:19], v[176:179], v[200:203], v[16:19]
	v_mfma_f32_16x16x32_bf16 v[8:11], v[168:171], v[210:213], v[8:11]
	v_mfma_f32_16x16x32_bf16 v[0:3], v[176:179], v[210:213], v[0:3]
	v_mfma_f32_16x16x32_bf16 v[56:59], v[172:175], v[188:191], v[56:59]
	v_mfma_f32_16x16x32_bf16 v[48:51], v[180:183], v[188:191], v[48:51]
	v_mfma_f32_16x16x32_bf16 v[40:43], v[172:175], v[196:199], v[40:43]
	v_mfma_f32_16x16x32_bf16 v[32:35], v[180:183], v[196:199], v[32:35]
	v_mfma_f32_16x16x32_bf16 v[24:27], v[172:175], v[204:207], v[24:27]
	v_mfma_f32_16x16x32_bf16 v[16:19], v[180:183], v[204:207], v[16:19]
	v_mfma_f32_16x16x32_bf16 v[8:11], v[172:175], v[214:217], v[8:11]
	v_mfma_f32_16x16x32_bf16 v[0:3], v[180:183], v[214:217], v[0:3]
	s_setprio 0
	s_barrier
	s_add_i32 s64, s64, 2
	s_add_u32 s24, s24, 0x100
	s_addc_u32 s25, s25, 0
	s_add_u32 s62, s62, 0x100
	s_addc_u32 s63, s63, 0
	s_cmp_gt_u32 s64, 29
	s_cbranch_scc0 .LBB0_1317
	s_and_b64 vcc, exec, s[12:13]
	s_cbranch_vccz .LBB0_1320
	s_barrier

; #define PG8_STAGE(bufoff, gbase, voff) do { _Pragma("unroll") for (int _i = 0; _i < 2; ++_i) \
;         __builtin_amdgcn_global_load_lds((const unsigned*)((const char*)(gbase) + (voff)[_i]), (PG8_LAS unsigned*)(lds + (bufoff) + ldsw + _i * 8192), 16, 0, 0); } while (0)
; #define PG8_LDA(dst, b, h) do { _Pragma("unroll") for (int m = 0; m < 4; ++m) _Pragma("unroll") for (int k = 0; k < 2; ++k) dst[m][k] = *(const PG8_LAS bf16x8*)(lds + PG8_SA(b, h) + aoff + m * 2048 + k * 1024); } while (0)
; #define PG8_LDB(dst, b, h) do { _Pragma("unroll") for (int n = 0; n < 2; ++n) _Pragma("unroll") for (int k = 0; k < 2; ++k) dst[n][k] = *(const PG8_LAS bf16x8*)(lds + PG8_SB(b, h) + boff + n * 2048 + k * 1024); } while (0)
; #define PG8_MMA(ai, bj, At, Bt) do { __builtin_amdgcn_s_setprio(1); _Pragma("unroll") for (int m = 0; m < 4; ++m) _Pragma("unroll") for (int n = 0; n < 2; ++n) _Pragma("unroll") for (int k = 0; k < 2; ++k) \
;         acc[ai][bj][m][n] = __builtin_amdgcn_mfma_f32_16x16x32_bf16(Bt[n][k], At[m][k], acc[ai][bj][m][n], 0, 0, 0); __builtin_amdgcn_s_setprio(0); } while (0)
; #define PG8_WAIT_V(n) asm volatile("s_waitcnt vmcnt(" #n ")" ::: "memory")
; #define PG8_WAIT_L(n) asm volatile("s_waitcnt lgkmcnt(" #n ")" ::: "memory")
; #define PG8_BAR __builtin_amdgcn_s_barrier()
; #define PG8_SCHED __builtin_amdgcn_sched_barrier(0)
; template <class Epi, class Sched, bool ALIGN_EPI = false, bool SP2 = false>
; __device__ __forceinline__ void gemm_phase(PG8_LAS unsigned char* lds, const Gemm g, const Sched& S, const Epi& E) {
;     ...
;             const char* a2 = last ? nA : cA + (size_t)(t + 2) * kstep; const char* b2 = last ? nB : cB + (size_t)(t + 2) * kstep;
;             const char* a3 = a2 + kstep; const char* b3 = b2 + kstep;
;             if (last && has_next) S.a_ready(nxt);
;             if constexpr (SP2) {
;             PG8_LDB(B0, 0, 0); PG8_LDB(B1, 0, 1); PG8_SCHED; PG8_LDA(At, 0, 0); PG8_STAGE(PG8_SA(1, 1), a1 + hstep, voffA);
;             PG8_WAIT_V(8); PG8_WAIT_L(0); PG8_BAR; PG8_MMA(0, 0, At, B0); PG8_MMA(0, 1, At, B1); PG8_BAR; PG8_SCHED;
;             PG8_LDA(At, 0, 1); PG8_STAGE(PG8_SB(0, 0), b2, voffB); PG8_STAGE(PG8_SB(0, 1), b2 + hstep, voffB); PG8_STAGE(PG8_SA(0, 0), a2, voffA);
;             PG8_WAIT_V(8); PG8_WAIT_L(0); PG8_BAR; PG8_MMA(1, 0, At, B0); PG8_MMA(1, 1, At, B1); PG8_BAR; PG8_SCHED;
.LBB0_1392:
	ds_read_b128 v[152:155], v149
	ds_read_b128 v[156:159], v149 offset:1024
	ds_read_b128 v[164:167], v149 offset:2048
	ds_read_b128 v[168:171], v149 offset:3072
	ds_read_b128 v[172:175], v150
	ds_read_b128 v[176:179], v150 offset:1024
	ds_read_b128 v[180:183], v150 offset:2048
	ds_read_b128 v[184:187], v150 offset:3072
	s_add_u32 s28, s26, 0xffea0080
	s_addc_u32 s29, s27, -1
	s_cmpk_eq_i32 s68, 0x54
	s_cselect_b32 s31, s7, s29
	s_cselect_b32 s30, s6, s28
	s_cselect_b32 s29, s25, s67
	s_cselect_b32 s28, s24, s66
	v_lshl_add_u64 v[144:145], s[26:27], 0, v[136:137]
	s_add_i32 m0, s35, 0xc000
	ds_read_b128 v[188:191], v151
	ds_read_b128 v[192:195], v151 offset:1024
	ds_read_b128 v[196:199], v151 offset:2048
	ds_read_b128 v[200:203], v151 offset:3072
	ds_read_b128 v[204:207], v151 offset:4096
	ds_read_b128 v[210:213], v151 offset:5120
	ds_read_b128 v[214:217], v151 offset:6144
	ds_read_b128 v[218:221], v151 offset:7168
	global_load_lds_dwordx4 v[144:145], off
	v_lshl_add_u64 v[144:145], s[26:27], 0, v[138:139]
	s_add_i32 m0, s35, 0xe000
	s_nop 0
	global_load_lds_dwordx4 v[144:145], off
	s_waitcnt vmcnt(8)
	s_waitcnt lgkmcnt(0)
	s_waitcnt lgkmcnt(0)
	v_mfma_f32_16x16x32_bf16 v[124:127], v[152:155], v[188:191], v[124:127]
	v_mfma_f32_16x16x32_bf16 v[120:123], v[164:167], v[188:191], v[120:123]
	v_mfma_f32_16x16x32_bf16 v[116:119], v[152:155], v[196:199], v[116:119]
	v_mfma_f32_16x16x32_bf16 v[108:111], v[164:167], v[196:199], v[108:111]
	v_mfma_f32_16x16x32_bf16 v[100:103], v[152:155], v[204:207], v[100:103]
	v_mfma_f32_16x16x32_bf16 v[92:95], v[164:167], v[204:207], v[92:95]
	v_mfma_f32_16x16x32_bf16 v[84:87], v[152:155], v[214:217], v[84:87]
	v_mfma_f32_16x16x32_bf16 v[76:79], v[164:167], v[214:217], v[76:79]
	s_barrier
	s_setprio 1
	v_mfma_f32_16x16x32_bf16 v[124:127], v[156:159], v[192:195], v[124:127]
	v_mfma_f32_16x16x32_bf16 v[120:123], v[168:171], v[192:195], v[120:123]
	v_mfma_f32_16x16x32_bf16 v[116:119], v[156:159], v[200:203], v[116:119]
	v_mfma_f32_16x16x32_bf16 v[108:111], v[168:171], v[200:203], v[108:111]
	v_mfma_f32_16x16x32_bf16 v[100:103], v[156:159], v[210:213], v[100:103]
	v_mfma_f32_16x16x32_bf16 v[92:95], v[168:171], v[210:213], v[92:95]
	v_mfma_f32_16x16x32_bf16 v[84:87], v[156:159], v[218:221], v[84:87]
	v_mfma_f32_16x16x32_bf16 v[76:79], v[168:171], v[218:221], v[76:79]
	s_setprio 0
	s_setprio 1
	v_mfma_f32_16x16x32_bf16 v[112:115], v[172:175], v[188:191], v[112:115]
	v_mfma_f32_16x16x32_bf16 v[104:107], v[180:183], v[188:191], v[104:107]
	v_mfma_f32_16x16x32_bf16 v[96:99], v[172:175], v[196:199], v[96:99]
	v_mfma_f32_16x16x32_bf16 v[88:91], v[180:183], v[196:199], v[88:91]
	v_mfma_f32_16x16x32_bf16 v[80:83], v[172:175], v[204:207], v[80:83]
	v_mfma_f32_16x16x32_bf16 v[72:75], v[180:183], v[204:207], v[72:75]
	v_mfma_f32_16x16x32_bf16 v[68:71], v[172:175], v[214:217], v[68:71]
	v_mfma_f32_16x16x32_bf16 v[64:67], v[180:183], v[214:217], v[64:67]
	v_mfma_f32_16x16x32_bf16 v[112:115], v[176:179], v[192:195], v[112:115]
	v_mfma_f32_16x16x32_bf16 v[104:107], v[184:187], v[192:195], v[104:107]
	v_mfma_f32_16x16x32_bf16 v[96:99], v[176:179], v[200:203], v[96:99]
	v_mfma_f32_16x16x32_bf16 v[88:91], v[184:187], v[200:203], v[88:91]
	v_mfma_f32_16x16x32_bf16 v[80:83], v[176:179], v[210:213], v[80:83]
	v_mfma_f32_16x16x32_bf16 v[72:75], v[184:187], v[210:213], v[72:75]
	v_mfma_f32_16x16x32_bf16 v[68:71], v[176:179], v[218:221], v[68:71]
	v_mfma_f32_16x16x32_bf16 v[64:67], v[184:187], v[218:221], v[64:67]
	s_setprio 0
	s_barrier
	s_add_i32 s69, s50, s3
	v_lshl_add_u64 v[144:145], s[28:29], 0, v[132:133]
	s_mov_b32 m0, s69
	ds_read_b128 v[188:191], v151 offset:16384
	ds_read_b128 v[192:195], v151 offset:17408
	ds_read_b128 v[196:199], v151 offset:18432
	ds_read_b128 v[200:203], v151 offset:19456
	ds_read_b128 v[204:207], v151 offset:20480
	ds_read_b128 v[210:213], v151 offset:21504
	ds_read_b128 v[214:217], v151 offset:22528
	ds_read_b128 v[218:221], v151 offset:23552
	global_load_lds_dwordx4 v[144:145], off
	s_add_i32 m0, s69, 0x2000
	s_add_u32 s70, s28, 0x160000
	v_lshl_add_u64 v[160:161], s[28:29], 0, v[128:129]
	s_addc_u32 s71, s29, 0
	s_add_i32 s69, s51, s3
	global_load_lds_dwordx4 v[160:161], off
	v_lshl_add_u64 v[222:223], s[70:71], 0, v[132:133]
	s_mov_b32 m0, s69
	v_lshl_add_u64 v[224:225], s[30:31], 0, v[130:131]
	global_load_lds_dwordx4 v[222:223], off
	v_lshl_add_u64 v[222:223], s[70:71], 0, v[128:129]
	s_add_i32 m0, s69, 0x2000
	s_nop 0
	global_load_lds_dwordx4 v[222:223], off
	v_lshl_add_u64 v[222:223], s[30:31], 0, v[134:135]
	s_mov_b32 m0, s35
	s_nop 0
	global_load_lds_dwordx4 v[222:223], off
	s_mov_b32 m0, s38
	s_nop 0
	global_load_lds_dwordx4 v[224:225], off
	s_waitcnt vmcnt(8)
	s_waitcnt lgkmcnt(0)
	s_waitcnt lgkmcnt(0)
	v_mfma_f32_16x16x32_bf16 v[60:63], v[152:155], v[188:191], v[60:63]
	v_mfma_f32_16x16x32_bf16 v[56:59], v[164:167], v[188:191], v[56:59]
	v_mfma_f32_16x16x32_bf16 v[52:55], v[152:155], v[196:199], v[52:55]
	v_mfma_f32_16x16x32_bf16 v[44:47], v[164:167], v[196:199], v[44:47]
	v_mfma_f32_16x16x32_bf16 v[36:39], v[152:155], v[204:207], v[36:39]
	v_mfma_f32_16x16x32_bf16 v[28:31], v[164:167], v[204:207], v[28:31]
	v_mfma_f32_16x16x32_bf16 v[20:23], v[152:155], v[214:217], v[20:23]
	v_mfma_f32_16x16x32_bf16 v[12:15], v[164:167], v[214:217], v[12:15]
	s_barrier
; #define PG8_STAGE(bufoff, gbase, voff) do { _Pragma("unroll") for (int _i = 0; _i < 2; ++_i) \
;         __builtin_amdgcn_global_load_lds((const unsigned*)((const char*)(gbase) + (voff)[_i]), (PG8_LAS unsigned*)(lds + (bufoff) + ldsw + _i * 8192), 16, 0, 0); } while (0)
; #define PG8_LDA(dst, b, h) do { _Pragma("unroll") for (int m = 0; m < 4; ++m) _Pragma("unroll") for (int k = 0; k < 2; ++k) dst[m][k] = *(const PG8_LAS bf16x8*)(lds + PG8_SA(b, h) + aoff + m * 2048 + k * 1024); } while (0)
; #define PG8_LDB(dst, b, h) do { _Pragma("unroll") for (int n = 0; n < 2; ++n) _Pragma("unroll") for (int k = 0; k < 2; ++k) dst[n][k] = *(const PG8_LAS bf16x8*)(lds + PG8_SB(b, h) + boff + n * 2048 + k * 1024); } while (0)
; #define PG8_MMA(ai, bj, At, Bt) do { __builtin_amdgcn_s_setprio(1); _Pragma("unroll") for (int m = 0; m < 4; ++m) _Pragma("unroll") for (int n = 0; n < 2; ++n) _Pragma("unroll") for (int k = 0; k < 2; ++k) \
;         acc[ai][bj][m][n] = __builtin_amdgcn_mfma_f32_16x16x32_bf16(Bt[n][k], At[m][k], acc[ai][bj][m][n], 0, 0, 0); __builtin_amdgcn_s_setprio(0); } while (0)
; #define PG8_WAIT_V(n) asm volatile("s_waitcnt vmcnt(" #n ")" ::: "memory")
; #define PG8_WAIT_L(n) asm volatile("s_waitcnt lgkmcnt(" #n ")" ::: "memory")
; #define PG8_BAR __builtin_amdgcn_s_barrier()
; #define PG8_SCHED __builtin_amdgcn_sched_barrier(0)
; template <class Epi, class Sched, bool ALIGN_EPI = false, bool SP2 = false>
; __device__ __forceinline__ void gemm_phase(PG8_LAS unsigned char* lds, const Gemm g, const Sched& S, const Epi& E) {
;     ...
;             PG8_WAIT_V(8); PG8_WAIT_L(0); PG8_BAR; PG8_MMA(1, 0, At, B0); PG8_MMA(1, 1, At, B1); PG8_BAR; PG8_SCHED;
;             PG8_LDB(B0, 1, 0); PG8_LDB(B1, 1, 1); PG8_SCHED; PG8_LDA(At, 1, 0); PG8_STAGE(PG8_SA(0, 1), a2 + hstep, voffA);
;             PG8_WAIT_V(8); PG8_WAIT_L(0); PG8_BAR; PG8_MMA(0, 0, At, B0); PG8_MMA(0, 1, At, B1); PG8_BAR; PG8_SCHED;
	s_setprio 1
	v_mfma_f32_16x16x32_bf16 v[60:63], v[156:159], v[192:195], v[60:63]
	v_mfma_f32_16x16x32_bf16 v[56:59], v[168:171], v[192:195], v[56:59]
	v_mfma_f32_16x16x32_bf16 v[52:55], v[156:159], v[200:203], v[52:55]
	v_mfma_f32_16x16x32_bf16 v[44:47], v[168:171], v[200:203], v[44:47]
	v_mfma_f32_16x16x32_bf16 v[36:39], v[156:159], v[210:213], v[36:39]
	v_mfma_f32_16x16x32_bf16 v[28:31], v[168:171], v[210:213], v[28:31]
	v_mfma_f32_16x16x32_bf16 v[20:23], v[156:159], v[218:221], v[20:23]
	v_mfma_f32_16x16x32_bf16 v[12:15], v[168:171], v[218:221], v[12:15]
	s_setprio 0
	s_setprio 1
	v_mfma_f32_16x16x32_bf16 v[48:51], v[172:175], v[188:191], v[48:51]
	v_mfma_f32_16x16x32_bf16 v[40:43], v[180:183], v[188:191], v[40:43]
	v_mfma_f32_16x16x32_bf16 v[32:35], v[172:175], v[196:199], v[32:35]
	v_mfma_f32_16x16x32_bf16 v[24:27], v[180:183], v[196:199], v[24:27]
	v_mfma_f32_16x16x32_bf16 v[16:19], v[172:175], v[204:207], v[16:19]
	v_mfma_f32_16x16x32_bf16 v[8:11], v[180:183], v[204:207], v[8:11]
	v_mfma_f32_16x16x32_bf16 v[4:7], v[172:175], v[214:217], v[4:7]
	v_mfma_f32_16x16x32_bf16 v[0:3], v[180:183], v[214:217], v[0:3]
	v_mfma_f32_16x16x32_bf16 v[48:51], v[176:179], v[192:195], v[48:51]
	v_mfma_f32_16x16x32_bf16 v[40:43], v[184:187], v[192:195], v[40:43]
	v_mfma_f32_16x16x32_bf16 v[32:35], v[176:179], v[200:203], v[32:35]
	v_mfma_f32_16x16x32_bf16 v[24:27], v[184:187], v[200:203], v[24:27]
	v_mfma_f32_16x16x32_bf16 v[16:19], v[176:179], v[210:213], v[16:19]
	v_mfma_f32_16x16x32_bf16 v[8:11], v[184:187], v[210:213], v[8:11]
	v_mfma_f32_16x16x32_bf16 v[4:7], v[176:179], v[218:221], v[4:7]
	v_mfma_f32_16x16x32_bf16 v[0:3], v[184:187], v[218:221], v[0:3]
	s_setprio 0
	s_barrier
	s_add_i32 s69, 0, 0x18000
	v_add_u32_e32 v163, s69, v147
	s_add_i32 s70, 0, 0x1c000
	ds_read_b128 v[152:155], v163
	ds_read_b128 v[156:159], v163 offset:1024
	ds_read_b128 v[164:167], v163 offset:2048
	ds_read_b128 v[168:171], v163 offset:3072
	v_add_u32_e32 v163, s70, v147
	ds_read_b128 v[172:175], v163
	ds_read_b128 v[176:179], v163 offset:1024
	ds_read_b128 v[180:183], v163 offset:2048
	ds_read_b128 v[184:187], v163 offset:3072
	s_add_u32 s30, s30, 0x160000
	s_addc_u32 s31, s31, 0
	s_mov_b32 m0, s39
	v_lshl_add_u64 v[226:227], s[30:31], 0, v[134:135]
	ds_read_b128 v[188:191], v151 offset:32768
	ds_read_b128 v[192:195], v151 offset:33792
	ds_read_b128 v[196:199], v151 offset:34816
	ds_read_b128 v[200:203], v151 offset:35840
	ds_read_b128 v[204:207], v151 offset:36864
	ds_read_b128 v[210:213], v151 offset:37888
	ds_read_b128 v[214:217], v151 offset:38912
	ds_read_b128 v[218:221], v151 offset:39936
	global_load_lds_dwordx4 v[226:227], off
	v_lshl_add_u64 v[226:227], s[30:31], 0, v[130:131]
	s_mov_b32 m0, s41
	s_nop 0
	global_load_lds_dwordx4 v[226:227], off
	s_waitcnt vmcnt(8)
	s_waitcnt lgkmcnt(0)
	s_waitcnt lgkmcnt(0)
	v_mfma_f32_16x16x32_bf16 v[124:127], v[152:155], v[188:191], v[124:127]
	v_mfma_f32_16x16x32_bf16 v[120:123], v[164:167], v[188:191], v[120:123]
	v_mfma_f32_16x16x32_bf16 v[116:119], v[152:155], v[196:199], v[116:119]
	v_mfma_f32_16x16x32_bf16 v[108:111], v[164:167], v[196:199], v[108:111]
	v_mfma_f32_16x16x32_bf16 v[100:103], v[152:155], v[204:207], v[100:103]
	v_mfma_f32_16x16x32_bf16 v[92:95], v[164:167], v[204:207], v[92:95]
	v_mfma_f32_16x16x32_bf16 v[84:87], v[152:155], v[214:217], v[84:87]
	v_mfma_f32_16x16x32_bf16 v[76:79], v[164:167], v[214:217], v[76:79]
	s_barrier
	s_setprio 1
	v_mfma_f32_16x16x32_bf16 v[124:127], v[156:159], v[192:195], v[124:127]
	v_mfma_f32_16x16x32_bf16 v[120:123], v[168:171], v[192:195], v[120:123]
	v_mfma_f32_16x16x32_bf16 v[116:119], v[156:159], v[200:203], v[116:119]
	v_mfma_f32_16x16x32_bf16 v[108:111], v[168:171], v[200:203], v[108:111]
	v_mfma_f32_16x16x32_bf16 v[100:103], v[156:159], v[210:213], v[100:103]
	v_mfma_f32_16x16x32_bf16 v[92:95], v[168:171], v[210:213], v[92:95]
	v_mfma_f32_16x16x32_bf16 v[84:87], v[156:159], v[218:221], v[84:87]
	v_mfma_f32_16x16x32_bf16 v[76:79], v[168:171], v[218:221], v[76:79]
	s_setprio 0
	s_setprio 1
	v_mfma_f32_16x16x32_bf16 v[112:115], v[172:175], v[188:191], v[112:115]
	v_mfma_f32_16x16x32_bf16 v[104:107], v[180:183], v[188:191], v[104:107]
	v_mfma_f32_16x16x32_bf16 v[96:99], v[172:175], v[196:199], v[96:99]
	v_mfma_f32_16x16x32_bf16 v[88:91], v[180:183], v[196:199], v[88:91]
	v_mfma_f32_16x16x32_bf16 v[80:83], v[172:175], v[204:207], v[80:83]
	v_mfma_f32_16x16x32_bf16 v[72:75], v[180:183], v[204:207], v[72:75]
	v_mfma_f32_16x16x32_bf16 v[68:71], v[172:175], v[214:217], v[68:71]
	v_mfma_f32_16x16x32_bf16 v[64:67], v[180:183], v[214:217], v[64:67]
	v_mfma_f32_16x16x32_bf16 v[112:115], v[176:179], v[192:195], v[112:115]
	v_mfma_f32_16x16x32_bf16 v[104:107], v[184:187], v[192:195], v[104:107]
	v_mfma_f32_16x16x32_bf16 v[96:99], v[176:179], v[200:203], v[96:99]
	v_mfma_f32_16x16x32_bf16 v[88:91], v[184:187], v[200:203], v[88:91]
	v_mfma_f32_16x16x32_bf16 v[80:83], v[176:179], v[210:213], v[80:83]
	v_mfma_f32_16x16x32_bf16 v[72:75], v[184:187], v[210:213], v[72:75]
	v_mfma_f32_16x16x32_bf16 v[68:71], v[176:179], v[218:221], v[68:71]
	v_mfma_f32_16x16x32_bf16 v[64:67], v[184:187], v[218:221], v[64:67]
	s_setprio 0
	s_barrier
; #define PG8_STAGE(bufoff, gbase, voff) do { _Pragma("unroll") for (int _i = 0; _i < 2; ++_i) \
;         __builtin_amdgcn_global_load_lds((const unsigned*)((const char*)(gbase) + (voff)[_i]), (PG8_LAS unsigned*)(lds + (bufoff) + ldsw + _i * 8192), 16, 0, 0); } while (0)
; #define PG8_LDA(dst, b, h) do { _Pragma("unroll") for (int m = 0; m < 4; ++m) _Pragma("unroll") for (int k = 0; k < 2; ++k) dst[m][k] = *(const PG8_LAS bf16x8*)(lds + PG8_SA(b, h) + aoff + m * 2048 + k * 1024); } while (0)
; #define PG8_MMA(ai, bj, At, Bt) do { __builtin_amdgcn_s_setprio(1); _Pragma("unroll") for (int m = 0; m < 4; ++m) _Pragma("unroll") for (int n = 0; n < 2; ++n) _Pragma("unroll") for (int k = 0; k < 2; ++k) \
;         acc[ai][bj][m][n] = __builtin_amdgcn_mfma_f32_16x16x32_bf16(Bt[n][k], At[m][k], acc[ai][bj][m][n], 0, 0, 0); __builtin_amdgcn_s_setprio(0); } while (0)
; #define PG8_WAIT_V(n) asm volatile("s_waitcnt vmcnt(" #n ")" ::: "memory")
; #define PG8_WAIT_L(n) asm volatile("s_waitcnt lgkmcnt(" #n ")" ::: "memory")
; #define PG8_BAR __builtin_amdgcn_s_barrier()
; #define PG8_SCHED __builtin_amdgcn_sched_barrier(0)
; template <class Epi, class Sched, bool ALIGN_EPI = false, bool SP2 = false>
; __device__ __forceinline__ void gemm_phase(PG8_LAS unsigned char* lds, const Gemm g, const Sched& S, const Epi& E) {
;     ...
;             PG8_LDA(At, 1, 1); PG8_STAGE(PG8_SB(1, 0), b3, voffB); PG8_STAGE(PG8_SB(1, 1), b3 + hstep, voffB); PG8_STAGE(PG8_SA(1, 0), a3, voffA);
;             PG8_WAIT_V(8); PG8_WAIT_L(0); PG8_BAR; PG8_MMA(1, 0, At, B0); PG8_MMA(1, 1, At, B1); PG8_BAR; PG8_SCHED;
	s_add_i32 s30, s69, s3
	v_lshl_add_u64 v[144:145], v[144:145], 0, s[12:13]
	s_mov_b32 m0, s30
	ds_read_b128 v[188:191], v151 offset:49152
	ds_read_b128 v[192:195], v151 offset:50176
	ds_read_b128 v[196:199], v151 offset:51200
	ds_read_b128 v[200:203], v151 offset:52224
	ds_read_b128 v[204:207], v151 offset:53248
	ds_read_b128 v[210:213], v151 offset:54272
	ds_read_b128 v[214:217], v151 offset:55296
	ds_read_b128 v[218:221], v151 offset:56320
	global_load_lds_dwordx4 v[144:145], off
	s_add_i32 m0, s30, 0x2000
	s_add_u32 s28, s28, 0x160080
	v_lshl_add_u64 v[144:145], v[160:161], 0, s[12:13]
	s_addc_u32 s29, s29, 0
	s_add_i32 s30, s70, s3
	global_load_lds_dwordx4 v[144:145], off
	v_lshl_add_u64 v[144:145], s[28:29], 0, v[132:133]
	s_mov_b32 m0, s30
	s_nop 0
	global_load_lds_dwordx4 v[144:145], off
	v_lshl_add_u64 v[144:145], s[28:29], 0, v[128:129]
	s_add_i32 m0, s30, 0x2000
	s_nop 0
	global_load_lds_dwordx4 v[144:145], off
	v_lshl_add_u64 v[144:145], v[222:223], 0, s[12:13]
	s_mov_b32 m0, s46
	s_nop 0
	global_load_lds_dwordx4 v[144:145], off
	v_lshl_add_u64 v[144:145], v[224:225], 0, s[12:13]
	s_mov_b32 m0, s47
	s_nop 0
	global_load_lds_dwordx4 v[144:145], off
	s_waitcnt vmcnt(8)
	s_waitcnt lgkmcnt(0)
	s_waitcnt lgkmcnt(0)
	v_mfma_f32_16x16x32_bf16 v[60:63], v[152:155], v[188:191], v[60:63]
	v_mfma_f32_16x16x32_bf16 v[56:59], v[164:167], v[188:191], v[56:59]
	v_mfma_f32_16x16x32_bf16 v[52:55], v[152:155], v[196:199], v[52:55]
	v_mfma_f32_16x16x32_bf16 v[44:47], v[164:167], v[196:199], v[44:47]
	v_mfma_f32_16x16x32_bf16 v[36:39], v[152:155], v[204:207], v[36:39]
	v_mfma_f32_16x16x32_bf16 v[28:31], v[164:167], v[204:207], v[28:31]
	v_mfma_f32_16x16x32_bf16 v[20:23], v[152:155], v[214:217], v[20:23]
	v_mfma_f32_16x16x32_bf16 v[12:15], v[164:167], v[214:217], v[12:15]
	s_barrier
	s_setprio 1
	v_mfma_f32_16x16x32_bf16 v[60:63], v[156:159], v[192:195], v[60:63]
	v_mfma_f32_16x16x32_bf16 v[56:59], v[168:171], v[192:195], v[56:59]
	v_mfma_f32_16x16x32_bf16 v[52:55], v[156:159], v[200:203], v[52:55]
	v_mfma_f32_16x16x32_bf16 v[44:47], v[168:171], v[200:203], v[44:47]
	v_mfma_f32_16x16x32_bf16 v[36:39], v[156:159], v[210:213], v[36:39]
	v_mfma_f32_16x16x32_bf16 v[28:31], v[168:171], v[210:213], v[28:31]
	v_mfma_f32_16x16x32_bf16 v[20:23], v[156:159], v[218:221], v[20:23]
	v_mfma_f32_16x16x32_bf16 v[12:15], v[168:171], v[218:221], v[12:15]
	s_setprio 0
	s_setprio 1
	v_mfma_f32_16x16x32_bf16 v[48:51], v[172:175], v[188:191], v[48:51]
	v_mfma_f32_16x16x32_bf16 v[40:43], v[180:183], v[188:191], v[40:43]
	v_mfma_f32_16x16x32_bf16 v[32:35], v[172:175], v[196:199], v[32:35]
	v_mfma_f32_16x16x32_bf16 v[24:27], v[180:183], v[196:199], v[24:27]
	v_mfma_f32_16x16x32_bf16 v[16:19], v[172:175], v[204:207], v[16:19]
	v_mfma_f32_16x16x32_bf16 v[8:11], v[180:183], v[204:207], v[8:11]
	v_mfma_f32_16x16x32_bf16 v[4:7], v[172:175], v[214:217], v[4:7]
	v_mfma_f32_16x16x32_bf16 v[0:3], v[180:183], v[214:217], v[0:3]
	v_mfma_f32_16x16x32_bf16 v[48:51], v[176:179], v[192:195], v[48:51]
	v_mfma_f32_16x16x32_bf16 v[40:43], v[184:187], v[192:195], v[40:43]
	v_mfma_f32_16x16x32_bf16 v[32:35], v[176:179], v[200:203], v[32:35]
	v_mfma_f32_16x16x32_bf16 v[24:27], v[184:187], v[200:203], v[24:27]
	v_mfma_f32_16x16x32_bf16 v[16:19], v[176:179], v[210:213], v[16:19]
	v_mfma_f32_16x16x32_bf16 v[8:11], v[184:187], v[210:213], v[8:11]
	v_mfma_f32_16x16x32_bf16 v[4:7], v[176:179], v[218:221], v[4:7]
	v_mfma_f32_16x16x32_bf16 v[0:3], v[184:187], v[218:221], v[0:3]
	s_setprio 0
	s_barrier
	s_add_i32 s68, s68, 2
	s_add_u32 s26, s26, 0x100
	s_addc_u32 s27, s27, 0
	s_add_u32 s66, s66, 0x100
	s_addc_u32 s67, s67, 0
	s_cmpk_gt_u32 s68, 0x55
	s_cbranch_scc0 .LBB0_1392
	s_and_b64 vcc, exec, s[14:15]
	s_cbranch_vccz .LBB0_1395
	s_barrier
